# saddr-form LDS-DMA (no per-load 64-bit VALU address adds) + swapped MFMA pair order in K-loops
# speedup vs baseline: 1.0059x; 1.0059x over previous
; #define PG8_STAGE(bufoff, gbase, voff) do { _Pragma("unroll") for (int _i = 0; _i < 2; ++_i) \
;         __builtin_amdgcn_global_load_lds((const unsigned*)((const char*)(gbase) + (voff)[_i]), (PG8_LAS unsigned*)(lds + (bufoff) + ldsw + _i * 8192), 16, 0, 0); } while (0)
; #define PG8_LDA(dst, b, h) do { _Pragma("unroll") for (int m = 0; m < 4; ++m) _Pragma("unroll") for (int k = 0; k < 2; ++k) dst[m][k] = *(const PG8_LAS bf16x8*)(lds + PG8_SA(b, h) + aoff + m * 2048 + k * 1024); } while (0)
; #define PG8_LDB(dst, b, h) do { _Pragma("unroll") for (int n = 0; n < 2; ++n) _Pragma("unroll") for (int k = 0; k < 2; ++k) dst[n][k] = *(const PG8_LAS bf16x8*)(lds + PG8_SB(b, h) + boff + n * 2048 + k * 1024); } while (0)
; #define PG8_MMA(ai, bj, At, Bt) do { __builtin_amdgcn_s_setprio(1); _Pragma("unroll") for (int m = 0; m < 4; ++m) _Pragma("unroll") for (int n = 0; n < 2; ++n) _Pragma("unroll") for (int k = 0; k < 2; ++k) \
;         acc[ai][bj][m][n] = __builtin_amdgcn_mfma_f32_16x16x32_f16(Bt[n][k], At[m][k], acc[ai][bj][m][n], 0, 0, 0); __builtin_amdgcn_s_setprio(0); } while (0)
; #define PG8_WAIT_V(n) asm volatile("s_waitcnt vmcnt(" #n ")" ::: "memory")
; #define PG8_WAIT_L(n) asm volatile("s_waitcnt lgkmcnt(" #n ")" ::: "memory")
; #define PG8_BAR __builtin_amdgcn_s_barrier()
; #define PG8_SCHED __builtin_amdgcn_sched_barrier(0)
; template <class Epi, class Sched, bool ALIGN_EPI = false, bool SP2 = false>
; __device__ __forceinline__ void gemm_phase(PG8_LAS unsigned char* lds, const Gemm g, const Sched& S, const Epi& E) {
;     ...
;             const char* a2 = last ? nA : cA + (size_t)(t + 2) * kstep; const char* b2 = last ? nB : cB + (size_t)(t + 2) * kstep;
;             const char* a3 = a2 + kstep; const char* b3 = b2 + kstep;
;             if (last && has_next) S.a_ready(nxt);
;             if constexpr (SP2) {
;             PG8_LDB(B0, 0, 0); PG8_LDB(B1, 0, 1); PG8_SCHED; PG8_LDA(At, 0, 0); PG8_STAGE(PG8_SA(1, 1), a1 + hstep, voffA);
;             PG8_WAIT_V(8); PG8_WAIT_L(0); PG8_BAR; PG8_MMA(0, 0, At, B0); PG8_MMA(0, 1, At, B1); PG8_BAR; PG8_SCHED;
;             PG8_LDA(At, 0, 1); PG8_STAGE(PG8_SB(0, 0), b2, voffB); PG8_STAGE(PG8_SB(0, 1), b2 + hstep, voffB); PG8_STAGE(PG8_SA(0, 0), a2, voffA);
;             PG8_WAIT_V(8); PG8_WAIT_L(0); PG8_BAR; PG8_MMA(1, 0, At, B0); PG8_MMA(1, 1, At, B1); PG8_BAR; PG8_SCHED;
.LBB0_146:
	ds_read_b128 v[150:153], v147
	ds_read_b128 v[154:157], v147 offset:1024
	ds_read_b128 v[158:161], v147 offset:2048
	ds_read_b128 v[162:165], v147 offset:3072
	ds_read_b128 v[166:169], v148
	ds_read_b128 v[170:173], v148 offset:1024
	ds_read_b128 v[174:177], v148 offset:2048
	ds_read_b128 v[178:181], v148 offset:3072
	s_add_u32 s24, s22, 0xfff80080
	s_addc_u32 s25, s23, -1
	s_cmp_eq_u32 s62, 28
	s_cselect_b32 s27, s17, s25
	s_cselect_b32 s26, s54, s24
	s_cselect_b32 s25, s15, s61
	s_cselect_b32 s24, s55, s60
	s_add_i32 m0, s13, 0xc000
	ds_read_b128 v[182:185], v149
	ds_read_b128 v[186:189], v149 offset:1024
	ds_read_b128 v[190:193], v149 offset:2048
	ds_read_b128 v[194:197], v149 offset:3072
	ds_read_b128 v[198:201], v149 offset:4096
	ds_read_b128 v[206:209], v149 offset:5120
	ds_read_b128 v[210:213], v149 offset:6144
	ds_read_b128 v[214:217], v149 offset:7168
	global_load_lds_dwordx4 v138, s[22:23]
	s_add_i32 m0, s13, 0xe000
	s_nop 0
	global_load_lds_dwordx4 v136, s[22:23]
	s_waitcnt vmcnt(8)
	s_waitcnt lgkmcnt(0)
	s_barrier
	s_setprio 1
	s_waitcnt lgkmcnt(0)
	v_mfma_f32_16x16x32_f16 v[120:123], v[158:161], v[182:185], v[120:123]
	v_mfma_f32_16x16x32_f16 v[124:127], v[150:153], v[182:185], v[124:127]
	v_mfma_f32_16x16x32_f16 v[112:115], v[158:161], v[190:193], v[112:115]
	v_mfma_f32_16x16x32_f16 v[116:119], v[150:153], v[190:193], v[116:119]
	v_mfma_f32_16x16x32_f16 v[96:99], v[158:161], v[198:201], v[96:99]
	v_mfma_f32_16x16x32_f16 v[100:103], v[150:153], v[198:201], v[100:103]
	v_mfma_f32_16x16x32_f16 v[80:83], v[158:161], v[210:213], v[80:83]
	v_mfma_f32_16x16x32_f16 v[84:87], v[150:153], v[210:213], v[84:87]
	v_mfma_f32_16x16x32_f16 v[120:123], v[162:165], v[186:189], v[120:123]
	v_mfma_f32_16x16x32_f16 v[124:127], v[154:157], v[186:189], v[124:127]
	v_mfma_f32_16x16x32_f16 v[112:115], v[162:165], v[194:197], v[112:115]
	v_mfma_f32_16x16x32_f16 v[116:119], v[154:157], v[194:197], v[116:119]
	v_mfma_f32_16x16x32_f16 v[96:99], v[162:165], v[206:209], v[96:99]
	v_mfma_f32_16x16x32_f16 v[100:103], v[154:157], v[206:209], v[100:103]
	v_mfma_f32_16x16x32_f16 v[80:83], v[162:165], v[214:217], v[80:83]
	v_mfma_f32_16x16x32_f16 v[84:87], v[154:157], v[214:217], v[84:87]
	s_setprio 0
	s_setprio 1
	v_mfma_f32_16x16x32_f16 v[104:107], v[174:177], v[182:185], v[104:107]
	v_mfma_f32_16x16x32_f16 v[108:111], v[166:169], v[182:185], v[108:111]
	v_mfma_f32_16x16x32_f16 v[88:91], v[174:177], v[190:193], v[88:91]
	v_mfma_f32_16x16x32_f16 v[92:95], v[166:169], v[190:193], v[92:95]
	v_mfma_f32_16x16x32_f16 v[72:75], v[174:177], v[198:201], v[72:75]
	v_mfma_f32_16x16x32_f16 v[76:79], v[166:169], v[198:201], v[76:79]
	v_mfma_f32_16x16x32_f16 v[64:67], v[174:177], v[210:213], v[64:67]
	v_mfma_f32_16x16x32_f16 v[68:71], v[166:169], v[210:213], v[68:71]
	v_mfma_f32_16x16x32_f16 v[104:107], v[178:181], v[186:189], v[104:107]
	v_mfma_f32_16x16x32_f16 v[108:111], v[170:173], v[186:189], v[108:111]
	v_mfma_f32_16x16x32_f16 v[88:91], v[178:181], v[194:197], v[88:91]
	v_mfma_f32_16x16x32_f16 v[92:95], v[170:173], v[194:197], v[92:95]
	v_mfma_f32_16x16x32_f16 v[72:75], v[178:181], v[206:209], v[72:75]
	v_mfma_f32_16x16x32_f16 v[76:79], v[170:173], v[206:209], v[76:79]
	v_mfma_f32_16x16x32_f16 v[64:67], v[178:181], v[214:217], v[64:67]
	v_mfma_f32_16x16x32_f16 v[68:71], v[170:173], v[214:217], v[68:71]
	s_setprio 0
	s_barrier
	s_add_i32 s63, s44, s34
	s_add_u32 s98, s24, s8
	s_addc_u32 s99, s25, s9
	s_mov_b32 m0, s63
	ds_read_b128 v[182:185], v149 offset:16384
	ds_read_b128 v[186:189], v149 offset:17408
	ds_read_b128 v[190:193], v149 offset:18432
	ds_read_b128 v[194:197], v149 offset:19456
	ds_read_b128 v[198:201], v149 offset:20480
	ds_read_b128 v[206:209], v149 offset:21504
	ds_read_b128 v[210:213], v149 offset:22528
	ds_read_b128 v[214:217], v149 offset:23552
	global_load_lds_dwordx4 v132, s[24:25]
	s_add_i32 m0, s63, 0x2000
	s_add_u32 s66, s24, 0x80000
	s_addc_u32 s67, s25, 0
	s_add_i32 s63, s45, s34
	global_load_lds_dwordx4 v128, s[24:25]
	s_mov_b32 m0, s63
	s_nop 0
	global_load_lds_dwordx4 v132, s[66:67]
	s_add_i32 m0, s63, 0x2000
	s_nop 0
	global_load_lds_dwordx4 v128, s[66:67]
	s_add_u32 s100, s26, s8
	s_addc_u32 s101, s27, s9
	s_mov_b32 m0, s13
	s_nop 0
	global_load_lds_dwordx4 v134, s[26:27]
	s_mov_b32 m0, s37
	s_nop 0
	global_load_lds_dwordx4 v130, s[26:27]
	s_waitcnt vmcnt(8)
	s_waitcnt lgkmcnt(0)
	s_barrier
	s_setprio 1
	s_waitcnt lgkmcnt(0)
	v_mfma_f32_16x16x32_f16 v[56:59], v[158:161], v[182:185], v[56:59]
	v_mfma_f32_16x16x32_f16 v[60:63], v[150:153], v[182:185], v[60:63]
	v_mfma_f32_16x16x32_f16 v[48:51], v[158:161], v[190:193], v[48:51]
	v_mfma_f32_16x16x32_f16 v[52:55], v[150:153], v[190:193], v[52:55]
	v_mfma_f32_16x16x32_f16 v[32:35], v[158:161], v[198:201], v[32:35]
	v_mfma_f32_16x16x32_f16 v[36:39], v[150:153], v[198:201], v[36:39]
	v_mfma_f32_16x16x32_f16 v[16:19], v[158:161], v[210:213], v[16:19]
	v_mfma_f32_16x16x32_f16 v[20:23], v[150:153], v[210:213], v[20:23]
	v_mfma_f32_16x16x32_f16 v[56:59], v[162:165], v[186:189], v[56:59]
	v_mfma_f32_16x16x32_f16 v[60:63], v[154:157], v[186:189], v[60:63]
	v_mfma_f32_16x16x32_f16 v[48:51], v[162:165], v[194:197], v[48:51]
	v_mfma_f32_16x16x32_f16 v[52:55], v[154:157], v[194:197], v[52:55]
	v_mfma_f32_16x16x32_f16 v[32:35], v[162:165], v[206:209], v[32:35]
	v_mfma_f32_16x16x32_f16 v[36:39], v[154:157], v[206:209], v[36:39]
	v_mfma_f32_16x16x32_f16 v[16:19], v[162:165], v[214:217], v[16:19]
	v_mfma_f32_16x16x32_f16 v[20:23], v[154:157], v[214:217], v[20:23]
	s_setprio 0
	s_setprio 1
	v_mfma_f32_16x16x32_f16 v[40:43], v[174:177], v[182:185], v[40:43]
	v_mfma_f32_16x16x32_f16 v[44:47], v[166:169], v[182:185], v[44:47]
	v_mfma_f32_16x16x32_f16 v[24:27], v[174:177], v[190:193], v[24:27]
	v_mfma_f32_16x16x32_f16 v[28:31], v[166:169], v[190:193], v[28:31]
	v_mfma_f32_16x16x32_f16 v[8:11], v[174:177], v[198:201], v[8:11]
	v_mfma_f32_16x16x32_f16 v[12:15], v[166:169], v[198:201], v[12:15]
	v_mfma_f32_16x16x32_f16 v[0:3], v[174:177], v[210:213], v[0:3]
	v_mfma_f32_16x16x32_f16 v[4:7], v[166:169], v[210:213], v[4:7]
	v_mfma_f32_16x16x32_f16 v[40:43], v[178:181], v[186:189], v[40:43]
	v_mfma_f32_16x16x32_f16 v[44:47], v[170:173], v[186:189], v[44:47]
	v_mfma_f32_16x16x32_f16 v[24:27], v[178:181], v[194:197], v[24:27]
	v_mfma_f32_16x16x32_f16 v[28:31], v[170:173], v[194:197], v[28:31]
	v_mfma_f32_16x16x32_f16 v[8:11], v[178:181], v[206:209], v[8:11]
	v_mfma_f32_16x16x32_f16 v[12:15], v[170:173], v[206:209], v[12:15]
	v_mfma_f32_16x16x32_f16 v[0:3], v[178:181], v[214:217], v[0:3]
	v_mfma_f32_16x16x32_f16 v[4:7], v[170:173], v[214:217], v[4:7]
	s_setprio 0
	s_barrier
; #define PG8_STAGE(bufoff, gbase, voff) do { _Pragma("unroll") for (int _i = 0; _i < 2; ++_i) \
;         __builtin_amdgcn_global_load_lds((const unsigned*)((const char*)(gbase) + (voff)[_i]), (PG8_LAS unsigned*)(lds + (bufoff) + ldsw + _i * 8192), 16, 0, 0); } while (0)
; #define PG8_LDA(dst, b, h) do { _Pragma("unroll") for (int m = 0; m < 4; ++m) _Pragma("unroll") for (int k = 0; k < 2; ++k) dst[m][k] = *(const PG8_LAS bf16x8*)(lds + PG8_SA(b, h) + aoff + m * 2048 + k * 1024); } while (0)
; #define PG8_LDB(dst, b, h) do { _Pragma("unroll") for (int n = 0; n < 2; ++n) _Pragma("unroll") for (int k = 0; k < 2; ++k) dst[n][k] = *(const PG8_LAS bf16x8*)(lds + PG8_SB(b, h) + boff + n * 2048 + k * 1024); } while (0)
; #define PG8_MMA(ai, bj, At, Bt) do { __builtin_amdgcn_s_setprio(1); _Pragma("unroll") for (int m = 0; m < 4; ++m) _Pragma("unroll") for (int n = 0; n < 2; ++n) _Pragma("unroll") for (int k = 0; k < 2; ++k) \
;         acc[ai][bj][m][n] = __builtin_amdgcn_mfma_f32_16x16x32_f16(Bt[n][k], At[m][k], acc[ai][bj][m][n], 0, 0, 0); __builtin_amdgcn_s_setprio(0); } while (0)
; #define PG8_WAIT_V(n) asm volatile("s_waitcnt vmcnt(" #n ")" ::: "memory")
; #define PG8_WAIT_L(n) asm volatile("s_waitcnt lgkmcnt(" #n ")" ::: "memory")
; #define PG8_BAR __builtin_amdgcn_s_barrier()
; #define PG8_SCHED __builtin_amdgcn_sched_barrier(0)
; template <class Epi, class Sched, bool ALIGN_EPI = false, bool SP2 = false>
; __device__ __forceinline__ void gemm_phase(PG8_LAS unsigned char* lds, const Gemm g, const Sched& S, const Epi& E) {
;     ...
;             PG8_LDB(B0, 1, 0); PG8_LDB(B1, 1, 1); PG8_SCHED; PG8_LDA(At, 1, 0); PG8_STAGE(PG8_SA(0, 1), a2 + hstep, voffA);
;             PG8_WAIT_V(8); PG8_WAIT_L(0); PG8_BAR; PG8_MMA(0, 0, At, B0); PG8_MMA(0, 1, At, B1); PG8_BAR; PG8_SCHED;
;             PG8_LDA(At, 1, 1); PG8_STAGE(PG8_SB(1, 0), b3, voffB); PG8_STAGE(PG8_SB(1, 1), b3 + hstep, voffB); PG8_STAGE(PG8_SA(1, 0), a3, voffA);
;             PG8_WAIT_V(8); PG8_WAIT_L(0); PG8_BAR; PG8_MMA(1, 0, At, B0); PG8_MMA(1, 1, At, B1); PG8_BAR; PG8_SCHED;
	s_add_i32 s63, 0, 0x18000
	s_add_i32 s66, 0, 0x1c000
	v_add_u32_e32 v162, s63, v145
	v_add_u32_e32 v178, s66, v145
	ds_read_b128 v[150:153], v162
	ds_read_b128 v[154:157], v162 offset:1024
	ds_read_b128 v[158:161], v162 offset:2048
	ds_read_b128 v[162:165], v162 offset:3072
	ds_read_b128 v[166:169], v178
	ds_read_b128 v[170:173], v178 offset:1024
	ds_read_b128 v[174:177], v178 offset:2048
	ds_read_b128 v[178:181], v178 offset:3072
	s_add_u32 s26, s26, 0x80000
	s_addc_u32 s27, s27, 0
	s_mov_b32 m0, s38
	ds_read_b128 v[182:185], v149 offset:32768
	ds_read_b128 v[186:189], v149 offset:33792
	ds_read_b128 v[190:193], v149 offset:34816
	ds_read_b128 v[194:197], v149 offset:35840
	ds_read_b128 v[198:201], v149 offset:36864
	ds_read_b128 v[206:209], v149 offset:37888
	ds_read_b128 v[210:213], v149 offset:38912
	ds_read_b128 v[214:217], v149 offset:39936
	global_load_lds_dwordx4 v134, s[26:27]
	s_mov_b32 m0, s39
	s_nop 0
	global_load_lds_dwordx4 v130, s[26:27]
	s_waitcnt vmcnt(8)
	s_waitcnt lgkmcnt(0)
	s_barrier
	s_setprio 1
	s_waitcnt lgkmcnt(0)
	v_mfma_f32_16x16x32_f16 v[120:123], v[158:161], v[182:185], v[120:123]
	v_mfma_f32_16x16x32_f16 v[124:127], v[150:153], v[182:185], v[124:127]
	v_mfma_f32_16x16x32_f16 v[112:115], v[158:161], v[190:193], v[112:115]
	v_mfma_f32_16x16x32_f16 v[116:119], v[150:153], v[190:193], v[116:119]
	v_mfma_f32_16x16x32_f16 v[96:99], v[158:161], v[198:201], v[96:99]
	v_mfma_f32_16x16x32_f16 v[100:103], v[150:153], v[198:201], v[100:103]
	v_mfma_f32_16x16x32_f16 v[80:83], v[158:161], v[210:213], v[80:83]
	v_mfma_f32_16x16x32_f16 v[84:87], v[150:153], v[210:213], v[84:87]
	v_mfma_f32_16x16x32_f16 v[120:123], v[162:165], v[186:189], v[120:123]
	v_mfma_f32_16x16x32_f16 v[124:127], v[154:157], v[186:189], v[124:127]
	v_mfma_f32_16x16x32_f16 v[112:115], v[162:165], v[194:197], v[112:115]
	v_mfma_f32_16x16x32_f16 v[116:119], v[154:157], v[194:197], v[116:119]
	v_mfma_f32_16x16x32_f16 v[96:99], v[162:165], v[206:209], v[96:99]
	v_mfma_f32_16x16x32_f16 v[100:103], v[154:157], v[206:209], v[100:103]
	v_mfma_f32_16x16x32_f16 v[80:83], v[162:165], v[214:217], v[80:83]
	v_mfma_f32_16x16x32_f16 v[84:87], v[154:157], v[214:217], v[84:87]
	s_setprio 0
	s_setprio 1
	v_mfma_f32_16x16x32_f16 v[104:107], v[174:177], v[182:185], v[104:107]
	v_mfma_f32_16x16x32_f16 v[108:111], v[166:169], v[182:185], v[108:111]
	v_mfma_f32_16x16x32_f16 v[88:91], v[174:177], v[190:193], v[88:91]
	v_mfma_f32_16x16x32_f16 v[92:95], v[166:169], v[190:193], v[92:95]
	v_mfma_f32_16x16x32_f16 v[72:75], v[174:177], v[198:201], v[72:75]
	v_mfma_f32_16x16x32_f16 v[76:79], v[166:169], v[198:201], v[76:79]
	v_mfma_f32_16x16x32_f16 v[64:67], v[174:177], v[210:213], v[64:67]
	v_mfma_f32_16x16x32_f16 v[68:71], v[166:169], v[210:213], v[68:71]
	v_mfma_f32_16x16x32_f16 v[104:107], v[178:181], v[186:189], v[104:107]
	v_mfma_f32_16x16x32_f16 v[108:111], v[170:173], v[186:189], v[108:111]
	v_mfma_f32_16x16x32_f16 v[88:91], v[178:181], v[194:197], v[88:91]
	v_mfma_f32_16x16x32_f16 v[92:95], v[170:173], v[194:197], v[92:95]
	v_mfma_f32_16x16x32_f16 v[72:75], v[178:181], v[206:209], v[72:75]
	v_mfma_f32_16x16x32_f16 v[76:79], v[170:173], v[206:209], v[76:79]
	v_mfma_f32_16x16x32_f16 v[64:67], v[178:181], v[214:217], v[64:67]
	v_mfma_f32_16x16x32_f16 v[68:71], v[170:173], v[214:217], v[68:71]
	s_setprio 0
	s_barrier
	s_add_i32 s26, s63, s34
	s_mov_b32 m0, s26
	ds_read_b128 v[182:185], v149 offset:49152
	ds_read_b128 v[186:189], v149 offset:50176
	ds_read_b128 v[190:193], v149 offset:51200
	ds_read_b128 v[194:197], v149 offset:52224
	ds_read_b128 v[198:201], v149 offset:53248
	ds_read_b128 v[206:209], v149 offset:54272
	ds_read_b128 v[210:213], v149 offset:55296
	ds_read_b128 v[214:217], v149 offset:56320
	global_load_lds_dwordx4 v132, s[98:99]
	s_add_i32 m0, s26, 0x2000
	s_add_u32 s24, s24, 0x80080
	s_addc_u32 s25, s25, 0
	s_add_i32 s26, s66, s34
	global_load_lds_dwordx4 v128, s[98:99]
	s_mov_b32 m0, s26
	s_nop 0
	global_load_lds_dwordx4 v132, s[24:25]
	s_add_i32 m0, s26, 0x2000
	s_nop 0
	global_load_lds_dwordx4 v128, s[24:25]
	s_mov_b32 m0, s41
	s_nop 0
	global_load_lds_dwordx4 v134, s[100:101]
	s_mov_b32 m0, s42
	s_nop 0
	global_load_lds_dwordx4 v130, s[100:101]
	s_waitcnt vmcnt(8)
	s_waitcnt lgkmcnt(0)
	s_barrier
	s_setprio 1
	s_waitcnt lgkmcnt(0)
	v_mfma_f32_16x16x32_f16 v[56:59], v[158:161], v[182:185], v[56:59]
	v_mfma_f32_16x16x32_f16 v[60:63], v[150:153], v[182:185], v[60:63]
	v_mfma_f32_16x16x32_f16 v[48:51], v[158:161], v[190:193], v[48:51]
	v_mfma_f32_16x16x32_f16 v[52:55], v[150:153], v[190:193], v[52:55]
	v_mfma_f32_16x16x32_f16 v[32:35], v[158:161], v[198:201], v[32:35]
	v_mfma_f32_16x16x32_f16 v[36:39], v[150:153], v[198:201], v[36:39]
	v_mfma_f32_16x16x32_f16 v[16:19], v[158:161], v[210:213], v[16:19]
	v_mfma_f32_16x16x32_f16 v[20:23], v[150:153], v[210:213], v[20:23]
	v_mfma_f32_16x16x32_f16 v[56:59], v[162:165], v[186:189], v[56:59]
	v_mfma_f32_16x16x32_f16 v[60:63], v[154:157], v[186:189], v[60:63]
	v_mfma_f32_16x16x32_f16 v[48:51], v[162:165], v[194:197], v[48:51]
	v_mfma_f32_16x16x32_f16 v[52:55], v[154:157], v[194:197], v[52:55]
	v_mfma_f32_16x16x32_f16 v[32:35], v[162:165], v[206:209], v[32:35]
	v_mfma_f32_16x16x32_f16 v[36:39], v[154:157], v[206:209], v[36:39]
	v_mfma_f32_16x16x32_f16 v[16:19], v[162:165], v[214:217], v[16:19]
	v_mfma_f32_16x16x32_f16 v[20:23], v[154:157], v[214:217], v[20:23]
	s_setprio 0
	s_setprio 1
	v_mfma_f32_16x16x32_f16 v[40:43], v[174:177], v[182:185], v[40:43]
	v_mfma_f32_16x16x32_f16 v[44:47], v[166:169], v[182:185], v[44:47]
	v_mfma_f32_16x16x32_f16 v[24:27], v[174:177], v[190:193], v[24:27]
	v_mfma_f32_16x16x32_f16 v[28:31], v[166:169], v[190:193], v[28:31]
	v_mfma_f32_16x16x32_f16 v[8:11], v[174:177], v[198:201], v[8:11]
	v_mfma_f32_16x16x32_f16 v[12:15], v[166:169], v[198:201], v[12:15]
	v_mfma_f32_16x16x32_f16 v[0:3], v[174:177], v[210:213], v[0:3]
	v_mfma_f32_16x16x32_f16 v[4:7], v[166:169], v[210:213], v[4:7]
	v_mfma_f32_16x16x32_f16 v[40:43], v[178:181], v[186:189], v[40:43]
	v_mfma_f32_16x16x32_f16 v[44:47], v[170:173], v[186:189], v[44:47]
	v_mfma_f32_16x16x32_f16 v[24:27], v[178:181], v[194:197], v[24:27]
	v_mfma_f32_16x16x32_f16 v[28:31], v[170:173], v[194:197], v[28:31]
	v_mfma_f32_16x16x32_f16 v[8:11], v[178:181], v[206:209], v[8:11]
	v_mfma_f32_16x16x32_f16 v[12:15], v[170:173], v[206:209], v[12:15]
	v_mfma_f32_16x16x32_f16 v[0:3], v[178:181], v[214:217], v[0:3]
	v_mfma_f32_16x16x32_f16 v[4:7], v[170:173], v[214:217], v[4:7]
	s_setprio 0
	s_barrier
	s_add_i32 s62, s62, 2
	s_add_u32 s60, s60, 0x100
	s_addc_u32 s61, s61, 0
	s_add_u32 s22, s22, 0x100
	s_addc_u32 s23, s23, 0
	s_cmp_gt_u32 s62, 29
	s_cbranch_scc0 .LBB0_146
	s_and_b64 vcc, exec, s[10:11]
	s_cbranch_vccz .LBB0_149
	s_barrier

; #define PG8_STAGE(bufoff, gbase, voff) do { _Pragma("unroll") for (int _i = 0; _i < 2; ++_i) \
;         __builtin_amdgcn_global_load_lds((const unsigned*)((const char*)(gbase) + (voff)[_i]), (PG8_LAS unsigned*)(lds + (bufoff) + ldsw + _i * 8192), 16, 0, 0); } while (0)
; #define PG8_LDA(dst, b, h) do { _Pragma("unroll") for (int m = 0; m < 4; ++m) _Pragma("unroll") for (int k = 0; k < 2; ++k) dst[m][k] = *(const PG8_LAS bf16x8*)(lds + PG8_SA(b, h) + aoff + m * 2048 + k * 1024); } while (0)
; #define PG8_LDB(dst, b, h) do { _Pragma("unroll") for (int n = 0; n < 2; ++n) _Pragma("unroll") for (int k = 0; k < 2; ++k) dst[n][k] = *(const PG8_LAS bf16x8*)(lds + PG8_SB(b, h) + boff + n * 2048 + k * 1024); } while (0)
; #define PG8_MMA(ai, bj, At, Bt) do { __builtin_amdgcn_s_setprio(1); _Pragma("unroll") for (int m = 0; m < 4; ++m) _Pragma("unroll") for (int n = 0; n < 2; ++n) _Pragma("unroll") for (int k = 0; k < 2; ++k) \
;         acc[ai][bj][m][n] = __builtin_amdgcn_mfma_f32_16x16x32_f16(Bt[n][k], At[m][k], acc[ai][bj][m][n], 0, 0, 0); __builtin_amdgcn_s_setprio(0); } while (0)
; #define PG8_WAIT_V(n) asm volatile("s_waitcnt vmcnt(" #n ")" ::: "memory")
; #define PG8_WAIT_L(n) asm volatile("s_waitcnt lgkmcnt(" #n ")" ::: "memory")
; #define PG8_BAR __builtin_amdgcn_s_barrier()
; #define PG8_SCHED __builtin_amdgcn_sched_barrier(0)
; template <class Epi, class Sched, bool ALIGN_EPI = false, bool SP2 = false>
; __device__ __forceinline__ void gemm_phase(PG8_LAS unsigned char* lds, const Gemm g, const Sched& S, const Epi& E) {
;     ...
;             const char* a2 = last ? nA : cA + (size_t)(t + 2) * kstep; const char* b2 = last ? nB : cB + (size_t)(t + 2) * kstep;
;             const char* a3 = a2 + kstep; const char* b3 = b2 + kstep;
;             if (last && has_next) S.a_ready(nxt);
;             if constexpr (SP2) {
;             PG8_LDB(B0, 0, 0); PG8_LDB(B1, 0, 1); PG8_SCHED; PG8_LDA(At, 0, 0); PG8_STAGE(PG8_SA(1, 1), a1 + hstep, voffA);
;             PG8_WAIT_V(8); PG8_WAIT_L(0); PG8_BAR; PG8_MMA(0, 0, At, B0); PG8_MMA(0, 1, At, B1); PG8_BAR; PG8_SCHED;
;             PG8_LDA(At, 0, 1); PG8_STAGE(PG8_SB(0, 0), b2, voffB); PG8_STAGE(PG8_SB(0, 1), b2 + hstep, voffB); PG8_STAGE(PG8_SA(0, 0), a2, voffA);
;             PG8_WAIT_V(8); PG8_WAIT_L(0); PG8_BAR; PG8_MMA(1, 0, At, B0); PG8_MMA(1, 1, At, B1); PG8_BAR; PG8_SCHED;
.LBB0_485:
	ds_read_b128 v[128:131], v163
	ds_read_b128 v[132:135], v163 offset:1024
	ds_read_b128 v[152:155], v163 offset:2048
	ds_read_b128 v[156:159], v163 offset:3072
	ds_read_b128 v[166:169], v164
	ds_read_b128 v[170:173], v164 offset:1024
	ds_read_b128 v[174:177], v164 offset:2048
	ds_read_b128 v[178:181], v164 offset:3072
	s_add_u32 s26, s24, 0x100
	s_addc_u32 s27, s25, 0
	s_cmp_eq_u32 s65, 20
	s_cselect_b32 s31, s1, s27
	s_cselect_b32 s30, s0, s26
	s_cselect_b32 s29, s23, s64
	s_cselect_b32 s28, s22, s63
	s_add_i32 m0, s37, 0xc000
	ds_read_b128 v[182:185], v165
	ds_read_b128 v[186:189], v165 offset:1024
	ds_read_b128 v[190:193], v165 offset:2048
	ds_read_b128 v[194:197], v165 offset:3072
	ds_read_b128 v[198:201], v165 offset:4096
	ds_read_b128 v[208:211], v165 offset:5120
	ds_read_b128 v[212:215], v165 offset:6144
	ds_read_b128 v[216:219], v165 offset:7168
	global_load_lds_dwordx4 v146, s[24:25]
	s_add_i32 m0, s37, 0xe000
	s_nop 0
	global_load_lds_dwordx4 v144, s[24:25]
	s_waitcnt vmcnt(8)
	s_waitcnt lgkmcnt(0)
	s_barrier
	s_setprio 1
	s_waitcnt lgkmcnt(0)
	v_mfma_f32_16x16x32_f16 v[120:123], v[152:155], v[182:185], v[120:123]
	v_mfma_f32_16x16x32_f16 v[124:127], v[128:131], v[182:185], v[124:127]
	v_mfma_f32_16x16x32_f16 v[104:107], v[152:155], v[190:193], v[104:107]
	v_mfma_f32_16x16x32_f16 v[108:111], v[128:131], v[190:193], v[108:111]
	v_mfma_f32_16x16x32_f16 v[88:91], v[152:155], v[198:201], v[88:91]
	v_mfma_f32_16x16x32_f16 v[92:95], v[128:131], v[198:201], v[92:95]
	v_mfma_f32_16x16x32_f16 v[72:75], v[152:155], v[212:215], v[72:75]
	v_mfma_f32_16x16x32_f16 v[76:79], v[128:131], v[212:215], v[76:79]
	v_mfma_f32_16x16x32_f16 v[120:123], v[156:159], v[186:189], v[120:123]
	v_mfma_f32_16x16x32_f16 v[124:127], v[132:135], v[186:189], v[124:127]
	v_mfma_f32_16x16x32_f16 v[104:107], v[156:159], v[194:197], v[104:107]
	v_mfma_f32_16x16x32_f16 v[108:111], v[132:135], v[194:197], v[108:111]
	v_mfma_f32_16x16x32_f16 v[88:91], v[156:159], v[208:211], v[88:91]
	v_mfma_f32_16x16x32_f16 v[92:95], v[132:135], v[208:211], v[92:95]
	v_mfma_f32_16x16x32_f16 v[72:75], v[156:159], v[216:219], v[72:75]
	v_mfma_f32_16x16x32_f16 v[76:79], v[132:135], v[216:219], v[76:79]
	s_setprio 0
	s_setprio 1
	v_mfma_f32_16x16x32_f16 v[112:115], v[174:177], v[182:185], v[112:115]
	v_mfma_f32_16x16x32_f16 v[116:119], v[166:169], v[182:185], v[116:119]
	v_mfma_f32_16x16x32_f16 v[96:99], v[174:177], v[190:193], v[96:99]
	v_mfma_f32_16x16x32_f16 v[100:103], v[166:169], v[190:193], v[100:103]
	v_mfma_f32_16x16x32_f16 v[80:83], v[174:177], v[198:201], v[80:83]
	v_mfma_f32_16x16x32_f16 v[84:87], v[166:169], v[198:201], v[84:87]
	v_mfma_f32_16x16x32_f16 v[64:67], v[174:177], v[212:215], v[64:67]
	v_mfma_f32_16x16x32_f16 v[68:71], v[166:169], v[212:215], v[68:71]
	v_mfma_f32_16x16x32_f16 v[112:115], v[178:181], v[186:189], v[112:115]
	v_mfma_f32_16x16x32_f16 v[116:119], v[170:173], v[186:189], v[116:119]
	v_mfma_f32_16x16x32_f16 v[96:99], v[178:181], v[194:197], v[96:99]
	v_mfma_f32_16x16x32_f16 v[100:103], v[170:173], v[194:197], v[100:103]
	v_mfma_f32_16x16x32_f16 v[80:83], v[178:181], v[208:211], v[80:83]
	v_mfma_f32_16x16x32_f16 v[84:87], v[170:173], v[208:211], v[84:87]
	v_mfma_f32_16x16x32_f16 v[64:67], v[178:181], v[216:219], v[64:67]
	v_mfma_f32_16x16x32_f16 v[68:71], v[170:173], v[216:219], v[68:71]
	s_setprio 0
	s_barrier
	s_add_i32 s24, s45, s36
	s_add_u32 s98, s28, s16
	s_addc_u32 s99, s29, s17
	s_mov_b32 m0, s24
	ds_read_b128 v[182:185], v165 offset:16384
	ds_read_b128 v[186:189], v165 offset:17408
	ds_read_b128 v[190:193], v165 offset:18432
	ds_read_b128 v[194:197], v165 offset:19456
	ds_read_b128 v[198:201], v165 offset:20480
	ds_read_b128 v[208:211], v165 offset:21504
	ds_read_b128 v[212:215], v165 offset:22528
	ds_read_b128 v[216:219], v165 offset:23552
	global_load_lds_dwordx4 v138, s[28:29]
	s_add_i32 m0, s24, 0x2000
	s_add_u32 s24, s28, 0x60000
	s_addc_u32 s25, s29, 0
	s_add_i32 s66, s52, s36
	global_load_lds_dwordx4 v142, s[28:29]
	s_mov_b32 m0, s66
	s_nop 0
	global_load_lds_dwordx4 v138, s[24:25]
	s_add_i32 m0, s66, 0x2000
	s_nop 0
	global_load_lds_dwordx4 v142, s[24:25]
	s_add_u32 s100, s30, s16
	s_addc_u32 s101, s31, s17
	s_mov_b32 m0, s37
	s_nop 0
	global_load_lds_dwordx4 v136, s[30:31]
	s_mov_b32 m0, s38
	s_nop 0
	global_load_lds_dwordx4 v140, s[30:31]
	s_waitcnt vmcnt(8)
	s_waitcnt lgkmcnt(0)
	s_barrier
	s_setprio 1
	s_waitcnt lgkmcnt(0)
	v_mfma_f32_16x16x32_f16 v[56:59], v[152:155], v[182:185], v[56:59]
	v_mfma_f32_16x16x32_f16 v[60:63], v[128:131], v[182:185], v[60:63]
	v_mfma_f32_16x16x32_f16 v[40:43], v[152:155], v[190:193], v[40:43]
	v_mfma_f32_16x16x32_f16 v[44:47], v[128:131], v[190:193], v[44:47]
	v_mfma_f32_16x16x32_f16 v[24:27], v[152:155], v[198:201], v[24:27]
	v_mfma_f32_16x16x32_f16 v[28:31], v[128:131], v[198:201], v[28:31]
	v_mfma_f32_16x16x32_f16 v[8:11], v[152:155], v[212:215], v[8:11]
	v_mfma_f32_16x16x32_f16 v[12:15], v[128:131], v[212:215], v[12:15]
	v_mfma_f32_16x16x32_f16 v[56:59], v[156:159], v[186:189], v[56:59]
	v_mfma_f32_16x16x32_f16 v[60:63], v[132:135], v[186:189], v[60:63]
	v_mfma_f32_16x16x32_f16 v[40:43], v[156:159], v[194:197], v[40:43]
	v_mfma_f32_16x16x32_f16 v[44:47], v[132:135], v[194:197], v[44:47]
	v_mfma_f32_16x16x32_f16 v[24:27], v[156:159], v[208:211], v[24:27]
	v_mfma_f32_16x16x32_f16 v[28:31], v[132:135], v[208:211], v[28:31]
	v_mfma_f32_16x16x32_f16 v[8:11], v[156:159], v[216:219], v[8:11]
	v_mfma_f32_16x16x32_f16 v[12:15], v[132:135], v[216:219], v[12:15]
	s_setprio 0
	s_setprio 1
	v_mfma_f32_16x16x32_f16 v[48:51], v[174:177], v[182:185], v[48:51]
	v_mfma_f32_16x16x32_f16 v[52:55], v[166:169], v[182:185], v[52:55]
	v_mfma_f32_16x16x32_f16 v[32:35], v[174:177], v[190:193], v[32:35]
	v_mfma_f32_16x16x32_f16 v[36:39], v[166:169], v[190:193], v[36:39]
	v_mfma_f32_16x16x32_f16 v[16:19], v[174:177], v[198:201], v[16:19]
	v_mfma_f32_16x16x32_f16 v[20:23], v[166:169], v[198:201], v[20:23]
	v_mfma_f32_16x16x32_f16 v[0:3], v[174:177], v[212:215], v[0:3]
	v_mfma_f32_16x16x32_f16 v[4:7], v[166:169], v[212:215], v[4:7]
	v_mfma_f32_16x16x32_f16 v[48:51], v[178:181], v[186:189], v[48:51]
	v_mfma_f32_16x16x32_f16 v[52:55], v[170:173], v[186:189], v[52:55]
	v_mfma_f32_16x16x32_f16 v[32:35], v[178:181], v[194:197], v[32:35]
	v_mfma_f32_16x16x32_f16 v[36:39], v[170:173], v[194:197], v[36:39]
	v_mfma_f32_16x16x32_f16 v[16:19], v[178:181], v[208:211], v[16:19]
	v_mfma_f32_16x16x32_f16 v[20:23], v[170:173], v[208:211], v[20:23]
	v_mfma_f32_16x16x32_f16 v[0:3], v[178:181], v[216:219], v[0:3]
	v_mfma_f32_16x16x32_f16 v[4:7], v[170:173], v[216:219], v[4:7]
	s_setprio 0
	s_barrier
; #define PG8_STAGE(bufoff, gbase, voff) do { _Pragma("unroll") for (int _i = 0; _i < 2; ++_i) \
;         __builtin_amdgcn_global_load_lds((const unsigned*)((const char*)(gbase) + (voff)[_i]), (PG8_LAS unsigned*)(lds + (bufoff) + ldsw + _i * 8192), 16, 0, 0); } while (0)
; #define PG8_LDA(dst, b, h) do { _Pragma("unroll") for (int m = 0; m < 4; ++m) _Pragma("unroll") for (int k = 0; k < 2; ++k) dst[m][k] = *(const PG8_LAS bf16x8*)(lds + PG8_SA(b, h) + aoff + m * 2048 + k * 1024); } while (0)
; #define PG8_LDB(dst, b, h) do { _Pragma("unroll") for (int n = 0; n < 2; ++n) _Pragma("unroll") for (int k = 0; k < 2; ++k) dst[n][k] = *(const PG8_LAS bf16x8*)(lds + PG8_SB(b, h) + boff + n * 2048 + k * 1024); } while (0)
; #define PG8_MMA(ai, bj, At, Bt) do { __builtin_amdgcn_s_setprio(1); _Pragma("unroll") for (int m = 0; m < 4; ++m) _Pragma("unroll") for (int n = 0; n < 2; ++n) _Pragma("unroll") for (int k = 0; k < 2; ++k) \
;         acc[ai][bj][m][n] = __builtin_amdgcn_mfma_f32_16x16x32_f16(Bt[n][k], At[m][k], acc[ai][bj][m][n], 0, 0, 0); __builtin_amdgcn_s_setprio(0); } while (0)
; #define PG8_WAIT_V(n) asm volatile("s_waitcnt vmcnt(" #n ")" ::: "memory")
; #define PG8_WAIT_L(n) asm volatile("s_waitcnt lgkmcnt(" #n ")" ::: "memory")
; #define PG8_BAR __builtin_amdgcn_s_barrier()
; #define PG8_SCHED __builtin_amdgcn_sched_barrier(0)
; template <class Epi, class Sched, bool ALIGN_EPI = false, bool SP2 = false>
; __device__ __forceinline__ void gemm_phase(PG8_LAS unsigned char* lds, const Gemm g, const Sched& S, const Epi& E) {
;     ...
;             PG8_LDB(B0, 1, 0); PG8_LDB(B1, 1, 1); PG8_SCHED; PG8_LDA(At, 1, 0); PG8_STAGE(PG8_SA(0, 1), a2 + hstep, voffA);
;             PG8_WAIT_V(8); PG8_WAIT_L(0); PG8_BAR; PG8_MMA(0, 0, At, B0); PG8_MMA(0, 1, At, B1); PG8_BAR; PG8_SCHED;
;             PG8_LDA(At, 1, 1); PG8_STAGE(PG8_SB(1, 0), b3, voffB); PG8_STAGE(PG8_SB(1, 1), b3 + hstep, voffB); PG8_STAGE(PG8_SA(1, 0), a3, voffA);
;             PG8_WAIT_V(8); PG8_WAIT_L(0); PG8_BAR; PG8_MMA(1, 0, At, B0); PG8_MMA(1, 1, At, B1); PG8_BAR; PG8_SCHED;
	s_add_i32 s66, 0, 0x18000
	s_add_i32 s67, 0, 0x1c000
	v_add_u32_e32 v156, s66, v161
	v_add_u32_e32 v178, s67, v161
	ds_read_b128 v[128:131], v156
	ds_read_b128 v[132:135], v156 offset:1024
	ds_read_b128 v[152:155], v156 offset:2048
	ds_read_b128 v[156:159], v156 offset:3072
	ds_read_b128 v[166:169], v178
	ds_read_b128 v[170:173], v178 offset:1024
	ds_read_b128 v[174:177], v178 offset:2048
	ds_read_b128 v[178:181], v178 offset:3072
	s_add_u32 s24, s30, 0x60000
	s_addc_u32 s25, s31, 0
	s_mov_b32 m0, s39
	ds_read_b128 v[182:185], v165 offset:32768
	ds_read_b128 v[186:189], v165 offset:33792
	ds_read_b128 v[190:193], v165 offset:34816
	ds_read_b128 v[194:197], v165 offset:35840
	ds_read_b128 v[198:201], v165 offset:36864
	ds_read_b128 v[208:211], v165 offset:37888
	ds_read_b128 v[212:215], v165 offset:38912
	ds_read_b128 v[216:219], v165 offset:39936
	global_load_lds_dwordx4 v136, s[24:25]
	s_mov_b32 m0, s40
	s_nop 0
	global_load_lds_dwordx4 v140, s[24:25]
	s_waitcnt vmcnt(8)
	s_waitcnt lgkmcnt(0)
	s_barrier
	s_setprio 1
	s_waitcnt lgkmcnt(0)
	v_mfma_f32_16x16x32_f16 v[120:123], v[152:155], v[182:185], v[120:123]
	v_mfma_f32_16x16x32_f16 v[124:127], v[128:131], v[182:185], v[124:127]
	v_mfma_f32_16x16x32_f16 v[104:107], v[152:155], v[190:193], v[104:107]
	v_mfma_f32_16x16x32_f16 v[108:111], v[128:131], v[190:193], v[108:111]
	v_mfma_f32_16x16x32_f16 v[88:91], v[152:155], v[198:201], v[88:91]
	v_mfma_f32_16x16x32_f16 v[92:95], v[128:131], v[198:201], v[92:95]
	v_mfma_f32_16x16x32_f16 v[72:75], v[152:155], v[212:215], v[72:75]
	v_mfma_f32_16x16x32_f16 v[76:79], v[128:131], v[212:215], v[76:79]
	v_mfma_f32_16x16x32_f16 v[120:123], v[156:159], v[186:189], v[120:123]
	v_mfma_f32_16x16x32_f16 v[124:127], v[132:135], v[186:189], v[124:127]
	v_mfma_f32_16x16x32_f16 v[104:107], v[156:159], v[194:197], v[104:107]
	v_mfma_f32_16x16x32_f16 v[108:111], v[132:135], v[194:197], v[108:111]
	v_mfma_f32_16x16x32_f16 v[88:91], v[156:159], v[208:211], v[88:91]
	v_mfma_f32_16x16x32_f16 v[92:95], v[132:135], v[208:211], v[92:95]
	v_mfma_f32_16x16x32_f16 v[72:75], v[156:159], v[216:219], v[72:75]
	v_mfma_f32_16x16x32_f16 v[76:79], v[132:135], v[216:219], v[76:79]
	s_setprio 0
	s_setprio 1
	v_mfma_f32_16x16x32_f16 v[112:115], v[174:177], v[182:185], v[112:115]
	v_mfma_f32_16x16x32_f16 v[116:119], v[166:169], v[182:185], v[116:119]
	v_mfma_f32_16x16x32_f16 v[96:99], v[174:177], v[190:193], v[96:99]
	v_mfma_f32_16x16x32_f16 v[100:103], v[166:169], v[190:193], v[100:103]
	v_mfma_f32_16x16x32_f16 v[80:83], v[174:177], v[198:201], v[80:83]
	v_mfma_f32_16x16x32_f16 v[84:87], v[166:169], v[198:201], v[84:87]
	v_mfma_f32_16x16x32_f16 v[64:67], v[174:177], v[212:215], v[64:67]
	v_mfma_f32_16x16x32_f16 v[68:71], v[166:169], v[212:215], v[68:71]
	v_mfma_f32_16x16x32_f16 v[112:115], v[178:181], v[186:189], v[112:115]
	v_mfma_f32_16x16x32_f16 v[116:119], v[170:173], v[186:189], v[116:119]
	v_mfma_f32_16x16x32_f16 v[96:99], v[178:181], v[194:197], v[96:99]
	v_mfma_f32_16x16x32_f16 v[100:103], v[170:173], v[194:197], v[100:103]
	v_mfma_f32_16x16x32_f16 v[80:83], v[178:181], v[208:211], v[80:83]
	v_mfma_f32_16x16x32_f16 v[84:87], v[170:173], v[208:211], v[84:87]
	v_mfma_f32_16x16x32_f16 v[64:67], v[178:181], v[216:219], v[64:67]
	v_mfma_f32_16x16x32_f16 v[68:71], v[170:173], v[216:219], v[68:71]
	s_setprio 0
	s_barrier
	s_add_i32 s24, s66, s36
	s_mov_b32 m0, s24
	ds_read_b128 v[182:185], v165 offset:49152
	ds_read_b128 v[186:189], v165 offset:50176
	ds_read_b128 v[190:193], v165 offset:51200
	ds_read_b128 v[194:197], v165 offset:52224
	ds_read_b128 v[198:201], v165 offset:53248
	ds_read_b128 v[208:211], v165 offset:54272
	ds_read_b128 v[212:215], v165 offset:55296
	ds_read_b128 v[216:219], v165 offset:56320
	global_load_lds_dwordx4 v138, s[98:99]
	s_add_i32 m0, s24, 0x2000
	s_add_u32 s24, s28, 0x60080
	s_addc_u32 s25, s29, 0
	s_add_i32 s28, s67, s36
	global_load_lds_dwordx4 v142, s[98:99]
	s_mov_b32 m0, s28
	s_nop 0
	global_load_lds_dwordx4 v138, s[24:25]
	s_add_i32 m0, s28, 0x2000
	s_nop 0
	global_load_lds_dwordx4 v142, s[24:25]
	s_mov_b32 m0, s42
	s_nop 0
	global_load_lds_dwordx4 v136, s[100:101]
	s_mov_b32 m0, s43
	s_nop 0
	global_load_lds_dwordx4 v140, s[100:101]
	s_waitcnt vmcnt(8)
	s_waitcnt lgkmcnt(0)
	s_barrier
	s_setprio 1
	s_waitcnt lgkmcnt(0)
	v_mfma_f32_16x16x32_f16 v[56:59], v[152:155], v[182:185], v[56:59]
	v_mfma_f32_16x16x32_f16 v[60:63], v[128:131], v[182:185], v[60:63]
	v_mfma_f32_16x16x32_f16 v[40:43], v[152:155], v[190:193], v[40:43]
	v_mfma_f32_16x16x32_f16 v[44:47], v[128:131], v[190:193], v[44:47]
	v_mfma_f32_16x16x32_f16 v[24:27], v[152:155], v[198:201], v[24:27]
	v_mfma_f32_16x16x32_f16 v[28:31], v[128:131], v[198:201], v[28:31]
	v_mfma_f32_16x16x32_f16 v[8:11], v[152:155], v[212:215], v[8:11]
	v_mfma_f32_16x16x32_f16 v[12:15], v[128:131], v[212:215], v[12:15]
	v_mfma_f32_16x16x32_f16 v[56:59], v[156:159], v[186:189], v[56:59]
	v_mfma_f32_16x16x32_f16 v[60:63], v[132:135], v[186:189], v[60:63]
	v_mfma_f32_16x16x32_f16 v[40:43], v[156:159], v[194:197], v[40:43]
	v_mfma_f32_16x16x32_f16 v[44:47], v[132:135], v[194:197], v[44:47]
	v_mfma_f32_16x16x32_f16 v[24:27], v[156:159], v[208:211], v[24:27]
	v_mfma_f32_16x16x32_f16 v[28:31], v[132:135], v[208:211], v[28:31]
	v_mfma_f32_16x16x32_f16 v[8:11], v[156:159], v[216:219], v[8:11]
	v_mfma_f32_16x16x32_f16 v[12:15], v[132:135], v[216:219], v[12:15]
	s_setprio 0
	s_setprio 1
	v_mfma_f32_16x16x32_f16 v[48:51], v[174:177], v[182:185], v[48:51]
	v_mfma_f32_16x16x32_f16 v[52:55], v[166:169], v[182:185], v[52:55]
	v_mfma_f32_16x16x32_f16 v[32:35], v[174:177], v[190:193], v[32:35]
	v_mfma_f32_16x16x32_f16 v[36:39], v[166:169], v[190:193], v[36:39]
	v_mfma_f32_16x16x32_f16 v[16:19], v[174:177], v[198:201], v[16:19]
	v_mfma_f32_16x16x32_f16 v[20:23], v[166:169], v[198:201], v[20:23]
	v_mfma_f32_16x16x32_f16 v[0:3], v[174:177], v[212:215], v[0:3]
	v_mfma_f32_16x16x32_f16 v[4:7], v[166:169], v[212:215], v[4:7]
	v_mfma_f32_16x16x32_f16 v[48:51], v[178:181], v[186:189], v[48:51]
	v_mfma_f32_16x16x32_f16 v[52:55], v[170:173], v[186:189], v[52:55]
	v_mfma_f32_16x16x32_f16 v[32:35], v[178:181], v[194:197], v[32:35]
	v_mfma_f32_16x16x32_f16 v[36:39], v[170:173], v[194:197], v[36:39]
	v_mfma_f32_16x16x32_f16 v[16:19], v[178:181], v[208:211], v[16:19]
	v_mfma_f32_16x16x32_f16 v[20:23], v[170:173], v[208:211], v[20:23]
	v_mfma_f32_16x16x32_f16 v[0:3], v[178:181], v[216:219], v[0:3]
	v_mfma_f32_16x16x32_f16 v[4:7], v[170:173], v[216:219], v[4:7]
	s_setprio 0
	s_barrier
	s_add_i32 s65, s65, 2
	s_add_u32 s63, s63, 0x100
	s_addc_u32 s64, s64, 0
	s_cmp_gt_u32 s65, 21
	s_mov_b64 s[24:25], s[26:27]
	s_cbranch_scc0 .LBB0_485
	s_and_b64 vcc, exec, s[18:19]
	s_cbranch_vccz .LBB0_488
	s_barrier

; #define PG8_STAGE(bufoff, gbase, voff) do { _Pragma("unroll") for (int _i = 0; _i < 2; ++_i) \
;         __builtin_amdgcn_global_load_lds((const unsigned*)((const char*)(gbase) + (voff)[_i]), (PG8_LAS unsigned*)(lds + (bufoff) + ldsw + _i * 8192), 16, 0, 0); } while (0)
; #define PG8_LDA(dst, b, h) do { _Pragma("unroll") for (int m = 0; m < 4; ++m) _Pragma("unroll") for (int k = 0; k < 2; ++k) dst[m][k] = *(const PG8_LAS bf16x8*)(lds + PG8_SA(b, h) + aoff + m * 2048 + k * 1024); } while (0)
; #define PG8_LDB(dst, b, h) do { _Pragma("unroll") for (int n = 0; n < 2; ++n) _Pragma("unroll") for (int k = 0; k < 2; ++k) dst[n][k] = *(const PG8_LAS bf16x8*)(lds + PG8_SB(b, h) + boff + n * 2048 + k * 1024); } while (0)
; #define PG8_MMA(ai, bj, At, Bt) do { __builtin_amdgcn_s_setprio(1); _Pragma("unroll") for (int m = 0; m < 4; ++m) _Pragma("unroll") for (int n = 0; n < 2; ++n) _Pragma("unroll") for (int k = 0; k < 2; ++k) \
;         acc[ai][bj][m][n] = __builtin_amdgcn_mfma_f32_16x16x32_f16(Bt[n][k], At[m][k], acc[ai][bj][m][n], 0, 0, 0); __builtin_amdgcn_s_setprio(0); } while (0)
; #define PG8_WAIT_V(n) asm volatile("s_waitcnt vmcnt(" #n ")" ::: "memory")
; #define PG8_WAIT_L(n) asm volatile("s_waitcnt lgkmcnt(" #n ")" ::: "memory")
; #define PG8_BAR __builtin_amdgcn_s_barrier()
; #define PG8_SCHED __builtin_amdgcn_sched_barrier(0)
; template <class Epi, class Sched, bool ALIGN_EPI = false, bool SP2 = false>
; __device__ __forceinline__ void gemm_phase(PG8_LAS unsigned char* lds, const Gemm g, const Sched& S, const Epi& E) {
;     ...
;             const char* a2 = last ? nA : cA + (size_t)(t + 2) * kstep; const char* b2 = last ? nB : cB + (size_t)(t + 2) * kstep;
;             const char* a3 = a2 + kstep; const char* b3 = b2 + kstep;
;             if (last && has_next) S.a_ready(nxt);
;             if constexpr (SP2) {
;             PG8_LDB(B0, 0, 0); PG8_LDB(B1, 0, 1); PG8_SCHED; PG8_LDA(At, 0, 0); PG8_STAGE(PG8_SA(1, 1), a1 + hstep, voffA);
;             PG8_WAIT_V(8); PG8_WAIT_L(0); PG8_BAR; PG8_MMA(0, 0, At, B0); PG8_MMA(0, 1, At, B1); PG8_BAR; PG8_SCHED;
;             PG8_LDA(At, 0, 1); PG8_STAGE(PG8_SB(0, 0), b2, voffB); PG8_STAGE(PG8_SB(0, 1), b2 + hstep, voffB); PG8_STAGE(PG8_SA(0, 0), a2, voffA);
;             PG8_WAIT_V(8); PG8_WAIT_L(0); PG8_BAR; PG8_MMA(1, 0, At, B0); PG8_MMA(1, 1, At, B1); PG8_BAR; PG8_SCHED;
.LBB0_577:
	ds_read_b128 v[128:131], v198
	ds_read_b128 v[132:135], v198 offset:1024
	ds_read_b128 v[136:139], v198 offset:2048
	ds_read_b128 v[140:143], v198 offset:3072
	ds_read_b128 v[144:147], v199
	ds_read_b128 v[148:151], v199 offset:1024
	ds_read_b128 v[152:155], v199 offset:2048
	ds_read_b128 v[156:159], v199 offset:3072
	s_add_u32 s42, s40, 0xfff80080
	s_addc_u32 s43, s41, -1
	s_cmp_eq_u32 s91, 28
	s_cselect_b32 s45, s31, s43
	s_cselect_b32 s44, s87, s42
	s_cselect_b32 s43, s29, s90
	s_cselect_b32 s42, s88, s89
	s_add_i32 m0, s39, 0xc000
	ds_read_b128 v[176:179], v200
	ds_read_b128 v[180:183], v200 offset:1024
	ds_read_b128 v[184:187], v200 offset:2048
	ds_read_b128 v[188:191], v200 offset:3072
	ds_read_b128 v[208:211], v200 offset:4096
	ds_read_b128 v[212:215], v200 offset:5120
	ds_read_b128 v[216:219], v200 offset:6144
	ds_read_b128 v[220:223], v200 offset:7168
	global_load_lds_dwordx4 v170, s[40:41]
	s_add_i32 m0, s39, 0xe000
	s_nop 0
	global_load_lds_dwordx4 v168, s[40:41]
	s_waitcnt vmcnt(8)
	s_waitcnt lgkmcnt(0)
	s_barrier
	s_setprio 1
	s_waitcnt lgkmcnt(0)
	v_mfma_f32_16x16x32_f16 v[120:123], v[136:139], v[176:179], v[120:123]
	v_mfma_f32_16x16x32_f16 v[124:127], v[128:131], v[176:179], v[124:127]
	v_mfma_f32_16x16x32_f16 v[104:107], v[136:139], v[184:187], v[104:107]
	v_mfma_f32_16x16x32_f16 v[108:111], v[128:131], v[184:187], v[108:111]
	v_mfma_f32_16x16x32_f16 v[88:91], v[136:139], v[208:211], v[88:91]
	v_mfma_f32_16x16x32_f16 v[92:95], v[128:131], v[208:211], v[92:95]
	v_mfma_f32_16x16x32_f16 v[72:75], v[136:139], v[216:219], v[72:75]
	v_mfma_f32_16x16x32_f16 v[76:79], v[128:131], v[216:219], v[76:79]
	v_mfma_f32_16x16x32_f16 v[120:123], v[140:143], v[180:183], v[120:123]
	v_mfma_f32_16x16x32_f16 v[124:127], v[132:135], v[180:183], v[124:127]
	v_mfma_f32_16x16x32_f16 v[104:107], v[140:143], v[188:191], v[104:107]
	v_mfma_f32_16x16x32_f16 v[108:111], v[132:135], v[188:191], v[108:111]
	v_mfma_f32_16x16x32_f16 v[88:91], v[140:143], v[212:215], v[88:91]
	v_mfma_f32_16x16x32_f16 v[92:95], v[132:135], v[212:215], v[92:95]
	v_mfma_f32_16x16x32_f16 v[72:75], v[140:143], v[220:223], v[72:75]
	v_mfma_f32_16x16x32_f16 v[76:79], v[132:135], v[220:223], v[76:79]
	s_setprio 0
	s_setprio 1
	v_mfma_f32_16x16x32_f16 v[112:115], v[152:155], v[176:179], v[112:115]
	v_mfma_f32_16x16x32_f16 v[116:119], v[144:147], v[176:179], v[116:119]
	v_mfma_f32_16x16x32_f16 v[96:99], v[152:155], v[184:187], v[96:99]
	v_mfma_f32_16x16x32_f16 v[100:103], v[144:147], v[184:187], v[100:103]
	v_mfma_f32_16x16x32_f16 v[80:83], v[152:155], v[208:211], v[80:83]
	v_mfma_f32_16x16x32_f16 v[84:87], v[144:147], v[208:211], v[84:87]
	v_mfma_f32_16x16x32_f16 v[64:67], v[152:155], v[216:219], v[64:67]
	v_mfma_f32_16x16x32_f16 v[68:71], v[144:147], v[216:219], v[68:71]
	v_mfma_f32_16x16x32_f16 v[112:115], v[156:159], v[180:183], v[112:115]
	v_mfma_f32_16x16x32_f16 v[116:119], v[148:151], v[180:183], v[116:119]
	v_mfma_f32_16x16x32_f16 v[96:99], v[156:159], v[188:191], v[96:99]
	v_mfma_f32_16x16x32_f16 v[100:103], v[148:151], v[188:191], v[100:103]
	v_mfma_f32_16x16x32_f16 v[80:83], v[156:159], v[212:215], v[80:83]
	v_mfma_f32_16x16x32_f16 v[84:87], v[148:151], v[212:215], v[84:87]
	v_mfma_f32_16x16x32_f16 v[64:67], v[156:159], v[220:223], v[64:67]
	v_mfma_f32_16x16x32_f16 v[68:71], v[148:151], v[220:223], v[68:71]
	s_setprio 0
	s_barrier
	s_add_i32 s92, s74, s63
	s_add_u32 s98, s42, s16
	s_addc_u32 s99, s43, s17
	s_mov_b32 m0, s92
	ds_read_b128 v[176:179], v200 offset:16384
	ds_read_b128 v[180:183], v200 offset:17408
	ds_read_b128 v[184:187], v200 offset:18432
	ds_read_b128 v[188:191], v200 offset:19456
	ds_read_b128 v[208:211], v200 offset:20480
	ds_read_b128 v[212:215], v200 offset:21504
	ds_read_b128 v[216:219], v200 offset:22528
	ds_read_b128 v[220:223], v200 offset:23552
	global_load_lds_dwordx4 v162, s[42:43]
	s_add_i32 m0, s92, 0x2000
	s_add_u32 s92, s42, 0x80000
	s_addc_u32 s93, s43, 0
	s_add_i32 s94, s75, s63
	global_load_lds_dwordx4 v166, s[42:43]
	s_mov_b32 m0, s94
	s_nop 0
	global_load_lds_dwordx4 v162, s[92:93]
	s_add_i32 m0, s94, 0x2000
	s_nop 0
	global_load_lds_dwordx4 v166, s[92:93]
	s_add_u32 s100, s44, s16
	s_addc_u32 s101, s45, s17
	s_mov_b32 m0, s39
	s_nop 0
	global_load_lds_dwordx4 v160, s[44:45]
	s_mov_b32 m0, s64
	s_nop 0
	global_load_lds_dwordx4 v164, s[44:45]
	s_waitcnt vmcnt(8)
	s_waitcnt lgkmcnt(0)
	s_barrier
	s_setprio 1
	s_waitcnt lgkmcnt(0)
	v_mfma_f32_16x16x32_f16 v[56:59], v[136:139], v[176:179], v[56:59]
	v_mfma_f32_16x16x32_f16 v[60:63], v[128:131], v[176:179], v[60:63]
	v_mfma_f32_16x16x32_f16 v[40:43], v[136:139], v[184:187], v[40:43]
	v_mfma_f32_16x16x32_f16 v[44:47], v[128:131], v[184:187], v[44:47]
	v_mfma_f32_16x16x32_f16 v[24:27], v[136:139], v[208:211], v[24:27]
	v_mfma_f32_16x16x32_f16 v[28:31], v[128:131], v[208:211], v[28:31]
	v_mfma_f32_16x16x32_f16 v[8:11], v[136:139], v[216:219], v[8:11]
	v_mfma_f32_16x16x32_f16 v[12:15], v[128:131], v[216:219], v[12:15]
	v_mfma_f32_16x16x32_f16 v[56:59], v[140:143], v[180:183], v[56:59]
	v_mfma_f32_16x16x32_f16 v[60:63], v[132:135], v[180:183], v[60:63]
	v_mfma_f32_16x16x32_f16 v[40:43], v[140:143], v[188:191], v[40:43]
	v_mfma_f32_16x16x32_f16 v[44:47], v[132:135], v[188:191], v[44:47]
	v_mfma_f32_16x16x32_f16 v[24:27], v[140:143], v[212:215], v[24:27]
	v_mfma_f32_16x16x32_f16 v[28:31], v[132:135], v[212:215], v[28:31]
	v_mfma_f32_16x16x32_f16 v[8:11], v[140:143], v[220:223], v[8:11]
	v_mfma_f32_16x16x32_f16 v[12:15], v[132:135], v[220:223], v[12:15]
	s_setprio 0
	s_setprio 1
	v_mfma_f32_16x16x32_f16 v[48:51], v[152:155], v[176:179], v[48:51]
	v_mfma_f32_16x16x32_f16 v[52:55], v[144:147], v[176:179], v[52:55]
	v_mfma_f32_16x16x32_f16 v[32:35], v[152:155], v[184:187], v[32:35]
	v_mfma_f32_16x16x32_f16 v[36:39], v[144:147], v[184:187], v[36:39]
	v_mfma_f32_16x16x32_f16 v[16:19], v[152:155], v[208:211], v[16:19]
	v_mfma_f32_16x16x32_f16 v[20:23], v[144:147], v[208:211], v[20:23]
	v_mfma_f32_16x16x32_f16 v[0:3], v[152:155], v[216:219], v[0:3]
	v_mfma_f32_16x16x32_f16 v[4:7], v[144:147], v[216:219], v[4:7]
	v_mfma_f32_16x16x32_f16 v[48:51], v[156:159], v[180:183], v[48:51]
	v_mfma_f32_16x16x32_f16 v[52:55], v[148:151], v[180:183], v[52:55]
	v_mfma_f32_16x16x32_f16 v[32:35], v[156:159], v[188:191], v[32:35]
	v_mfma_f32_16x16x32_f16 v[36:39], v[148:151], v[188:191], v[36:39]
	v_mfma_f32_16x16x32_f16 v[16:19], v[156:159], v[212:215], v[16:19]
	v_mfma_f32_16x16x32_f16 v[20:23], v[148:151], v[212:215], v[20:23]
	v_mfma_f32_16x16x32_f16 v[0:3], v[156:159], v[220:223], v[0:3]
	v_mfma_f32_16x16x32_f16 v[4:7], v[148:151], v[220:223], v[4:7]
	s_setprio 0
	s_barrier
; #define PG8_STAGE(bufoff, gbase, voff) do { _Pragma("unroll") for (int _i = 0; _i < 2; ++_i) \
;         __builtin_amdgcn_global_load_lds((const unsigned*)((const char*)(gbase) + (voff)[_i]), (PG8_LAS unsigned*)(lds + (bufoff) + ldsw + _i * 8192), 16, 0, 0); } while (0)
; #define PG8_LDA(dst, b, h) do { _Pragma("unroll") for (int m = 0; m < 4; ++m) _Pragma("unroll") for (int k = 0; k < 2; ++k) dst[m][k] = *(const PG8_LAS bf16x8*)(lds + PG8_SA(b, h) + aoff + m * 2048 + k * 1024); } while (0)
; #define PG8_LDB(dst, b, h) do { _Pragma("unroll") for (int n = 0; n < 2; ++n) _Pragma("unroll") for (int k = 0; k < 2; ++k) dst[n][k] = *(const PG8_LAS bf16x8*)(lds + PG8_SB(b, h) + boff + n * 2048 + k * 1024); } while (0)
; #define PG8_MMA(ai, bj, At, Bt) do { __builtin_amdgcn_s_setprio(1); _Pragma("unroll") for (int m = 0; m < 4; ++m) _Pragma("unroll") for (int n = 0; n < 2; ++n) _Pragma("unroll") for (int k = 0; k < 2; ++k) \
;         acc[ai][bj][m][n] = __builtin_amdgcn_mfma_f32_16x16x32_f16(Bt[n][k], At[m][k], acc[ai][bj][m][n], 0, 0, 0); __builtin_amdgcn_s_setprio(0); } while (0)
; #define PG8_WAIT_V(n) asm volatile("s_waitcnt vmcnt(" #n ")" ::: "memory")
; #define PG8_WAIT_L(n) asm volatile("s_waitcnt lgkmcnt(" #n ")" ::: "memory")
; #define PG8_BAR __builtin_amdgcn_s_barrier()
; #define PG8_SCHED __builtin_amdgcn_sched_barrier(0)
; template <class Epi, class Sched, bool ALIGN_EPI = false, bool SP2 = false>
; __device__ __forceinline__ void gemm_phase(PG8_LAS unsigned char* lds, const Gemm g, const Sched& S, const Epi& E) {
;     ...
;             PG8_LDB(B0, 1, 0); PG8_LDB(B1, 1, 1); PG8_SCHED; PG8_LDA(At, 1, 0); PG8_STAGE(PG8_SA(0, 1), a2 + hstep, voffA);
;             PG8_WAIT_V(8); PG8_WAIT_L(0); PG8_BAR; PG8_MMA(0, 0, At, B0); PG8_MMA(0, 1, At, B1); PG8_BAR; PG8_SCHED;
;             PG8_LDA(At, 1, 1); PG8_STAGE(PG8_SB(1, 0), b3, voffB); PG8_STAGE(PG8_SB(1, 1), b3 + hstep, voffB); PG8_STAGE(PG8_SA(1, 0), a3, voffA);
;             PG8_WAIT_V(8); PG8_WAIT_L(0); PG8_BAR; PG8_MMA(1, 0, At, B0); PG8_MMA(1, 1, At, B1); PG8_BAR; PG8_SCHED;
	s_add_i32 s92, 0, 0x18000
	s_add_i32 s93, 0, 0x1c000
	v_add_u32_e32 v140, s92, v196
	v_add_u32_e32 v156, s93, v196
	ds_read_b128 v[128:131], v140
	ds_read_b128 v[132:135], v140 offset:1024
	ds_read_b128 v[136:139], v140 offset:2048
	ds_read_b128 v[140:143], v140 offset:3072
	ds_read_b128 v[144:147], v156
	ds_read_b128 v[148:151], v156 offset:1024
	ds_read_b128 v[152:155], v156 offset:2048
	ds_read_b128 v[156:159], v156 offset:3072
	s_add_u32 s44, s44, 0x80000
	s_addc_u32 s45, s45, 0
	s_mov_b32 m0, s65
	ds_read_b128 v[176:179], v200 offset:32768
	ds_read_b128 v[180:183], v200 offset:33792
	ds_read_b128 v[184:187], v200 offset:34816
	ds_read_b128 v[188:191], v200 offset:35840
	ds_read_b128 v[208:211], v200 offset:36864
	ds_read_b128 v[212:215], v200 offset:37888
	ds_read_b128 v[216:219], v200 offset:38912
	ds_read_b128 v[220:223], v200 offset:39936
	global_load_lds_dwordx4 v160, s[44:45]
	s_mov_b32 m0, s66
	s_nop 0
	global_load_lds_dwordx4 v164, s[44:45]
	s_waitcnt vmcnt(8)
	s_waitcnt lgkmcnt(0)
	s_barrier
	s_setprio 1
	s_waitcnt lgkmcnt(0)
	v_mfma_f32_16x16x32_f16 v[120:123], v[136:139], v[176:179], v[120:123]
	v_mfma_f32_16x16x32_f16 v[124:127], v[128:131], v[176:179], v[124:127]
	v_mfma_f32_16x16x32_f16 v[104:107], v[136:139], v[184:187], v[104:107]
	v_mfma_f32_16x16x32_f16 v[108:111], v[128:131], v[184:187], v[108:111]
	v_mfma_f32_16x16x32_f16 v[88:91], v[136:139], v[208:211], v[88:91]
	v_mfma_f32_16x16x32_f16 v[92:95], v[128:131], v[208:211], v[92:95]
	v_mfma_f32_16x16x32_f16 v[72:75], v[136:139], v[216:219], v[72:75]
	v_mfma_f32_16x16x32_f16 v[76:79], v[128:131], v[216:219], v[76:79]
	v_mfma_f32_16x16x32_f16 v[120:123], v[140:143], v[180:183], v[120:123]
	v_mfma_f32_16x16x32_f16 v[124:127], v[132:135], v[180:183], v[124:127]
	v_mfma_f32_16x16x32_f16 v[104:107], v[140:143], v[188:191], v[104:107]
	v_mfma_f32_16x16x32_f16 v[108:111], v[132:135], v[188:191], v[108:111]
	v_mfma_f32_16x16x32_f16 v[88:91], v[140:143], v[212:215], v[88:91]
	v_mfma_f32_16x16x32_f16 v[92:95], v[132:135], v[212:215], v[92:95]
	v_mfma_f32_16x16x32_f16 v[72:75], v[140:143], v[220:223], v[72:75]
	v_mfma_f32_16x16x32_f16 v[76:79], v[132:135], v[220:223], v[76:79]
	s_setprio 0
	s_setprio 1
	v_mfma_f32_16x16x32_f16 v[112:115], v[152:155], v[176:179], v[112:115]
	v_mfma_f32_16x16x32_f16 v[116:119], v[144:147], v[176:179], v[116:119]
	v_mfma_f32_16x16x32_f16 v[96:99], v[152:155], v[184:187], v[96:99]
	v_mfma_f32_16x16x32_f16 v[100:103], v[144:147], v[184:187], v[100:103]
	v_mfma_f32_16x16x32_f16 v[80:83], v[152:155], v[208:211], v[80:83]
	v_mfma_f32_16x16x32_f16 v[84:87], v[144:147], v[208:211], v[84:87]
	v_mfma_f32_16x16x32_f16 v[64:67], v[152:155], v[216:219], v[64:67]
	v_mfma_f32_16x16x32_f16 v[68:71], v[144:147], v[216:219], v[68:71]
	v_mfma_f32_16x16x32_f16 v[112:115], v[156:159], v[180:183], v[112:115]
	v_mfma_f32_16x16x32_f16 v[116:119], v[148:151], v[180:183], v[116:119]
	v_mfma_f32_16x16x32_f16 v[96:99], v[156:159], v[188:191], v[96:99]
	v_mfma_f32_16x16x32_f16 v[100:103], v[148:151], v[188:191], v[100:103]
	v_mfma_f32_16x16x32_f16 v[80:83], v[156:159], v[212:215], v[80:83]
	v_mfma_f32_16x16x32_f16 v[84:87], v[148:151], v[212:215], v[84:87]
	v_mfma_f32_16x16x32_f16 v[64:67], v[156:159], v[220:223], v[64:67]
	v_mfma_f32_16x16x32_f16 v[68:71], v[148:151], v[220:223], v[68:71]
	s_setprio 0
	s_barrier
	s_add_i32 s44, s92, s63
	s_mov_b32 m0, s44
	ds_read_b128 v[176:179], v200 offset:49152
	ds_read_b128 v[180:183], v200 offset:50176
	ds_read_b128 v[184:187], v200 offset:51200
	ds_read_b128 v[188:191], v200 offset:52224
	ds_read_b128 v[208:211], v200 offset:53248
	ds_read_b128 v[212:215], v200 offset:54272
	ds_read_b128 v[216:219], v200 offset:55296
	ds_read_b128 v[220:223], v200 offset:56320
	global_load_lds_dwordx4 v162, s[98:99]
	s_add_i32 m0, s44, 0x2000
	s_add_u32 s42, s42, 0x80080
	s_addc_u32 s43, s43, 0
	s_add_i32 s44, s93, s63
	global_load_lds_dwordx4 v166, s[98:99]
	s_mov_b32 m0, s44
	s_nop 0
	global_load_lds_dwordx4 v162, s[42:43]
	s_add_i32 m0, s44, 0x2000
	s_nop 0
	global_load_lds_dwordx4 v166, s[42:43]
	s_mov_b32 m0, s68
	s_nop 0
	global_load_lds_dwordx4 v160, s[100:101]
	s_mov_b32 m0, s69
	s_nop 0
	global_load_lds_dwordx4 v164, s[100:101]
	s_waitcnt vmcnt(8)
	s_waitcnt lgkmcnt(0)
	s_barrier
	s_setprio 1
	s_waitcnt lgkmcnt(0)
	v_mfma_f32_16x16x32_f16 v[56:59], v[136:139], v[176:179], v[56:59]
	v_mfma_f32_16x16x32_f16 v[60:63], v[128:131], v[176:179], v[60:63]
	v_mfma_f32_16x16x32_f16 v[40:43], v[136:139], v[184:187], v[40:43]
	v_mfma_f32_16x16x32_f16 v[44:47], v[128:131], v[184:187], v[44:47]
	v_mfma_f32_16x16x32_f16 v[24:27], v[136:139], v[208:211], v[24:27]
	v_mfma_f32_16x16x32_f16 v[28:31], v[128:131], v[208:211], v[28:31]
	v_mfma_f32_16x16x32_f16 v[8:11], v[136:139], v[216:219], v[8:11]
	v_mfma_f32_16x16x32_f16 v[12:15], v[128:131], v[216:219], v[12:15]
	v_mfma_f32_16x16x32_f16 v[56:59], v[140:143], v[180:183], v[56:59]
	v_mfma_f32_16x16x32_f16 v[60:63], v[132:135], v[180:183], v[60:63]
	v_mfma_f32_16x16x32_f16 v[40:43], v[140:143], v[188:191], v[40:43]
	v_mfma_f32_16x16x32_f16 v[44:47], v[132:135], v[188:191], v[44:47]
	v_mfma_f32_16x16x32_f16 v[24:27], v[140:143], v[212:215], v[24:27]
	v_mfma_f32_16x16x32_f16 v[28:31], v[132:135], v[212:215], v[28:31]
	v_mfma_f32_16x16x32_f16 v[8:11], v[140:143], v[220:223], v[8:11]
	v_mfma_f32_16x16x32_f16 v[12:15], v[132:135], v[220:223], v[12:15]
	s_setprio 0
	s_setprio 1
	v_mfma_f32_16x16x32_f16 v[48:51], v[152:155], v[176:179], v[48:51]
	v_mfma_f32_16x16x32_f16 v[52:55], v[144:147], v[176:179], v[52:55]
	v_mfma_f32_16x16x32_f16 v[32:35], v[152:155], v[184:187], v[32:35]
	v_mfma_f32_16x16x32_f16 v[36:39], v[144:147], v[184:187], v[36:39]
	v_mfma_f32_16x16x32_f16 v[16:19], v[152:155], v[208:211], v[16:19]
	v_mfma_f32_16x16x32_f16 v[20:23], v[144:147], v[208:211], v[20:23]
	v_mfma_f32_16x16x32_f16 v[0:3], v[152:155], v[216:219], v[0:3]
	v_mfma_f32_16x16x32_f16 v[4:7], v[144:147], v[216:219], v[4:7]
	v_mfma_f32_16x16x32_f16 v[48:51], v[156:159], v[180:183], v[48:51]
	v_mfma_f32_16x16x32_f16 v[52:55], v[148:151], v[180:183], v[52:55]
	v_mfma_f32_16x16x32_f16 v[32:35], v[156:159], v[188:191], v[32:35]
	v_mfma_f32_16x16x32_f16 v[36:39], v[148:151], v[188:191], v[36:39]
	v_mfma_f32_16x16x32_f16 v[16:19], v[156:159], v[212:215], v[16:19]
	v_mfma_f32_16x16x32_f16 v[20:23], v[148:151], v[212:215], v[20:23]
	v_mfma_f32_16x16x32_f16 v[0:3], v[156:159], v[220:223], v[0:3]
	v_mfma_f32_16x16x32_f16 v[4:7], v[148:151], v[220:223], v[4:7]
	s_setprio 0
	s_barrier
	s_add_i32 s91, s91, 2
	s_add_u32 s89, s89, 0x100
	s_addc_u32 s90, s90, 0
	s_add_u32 s40, s40, 0x100
	s_addc_u32 s41, s41, 0
	s_cmp_gt_u32 s91, 29
	s_cbranch_scc0 .LBB0_577
	s_and_b64 vcc, exec, s[18:19]
	s_cbranch_vccz .LBB0_580
	s_barrier

; #define PG8_STAGE(bufoff, gbase, voff) do { _Pragma("unroll") for (int _i = 0; _i < 2; ++_i) \
;         __builtin_amdgcn_global_load_lds((const unsigned*)((const char*)(gbase) + (voff)[_i]), (PG8_LAS unsigned*)(lds + (bufoff) + ldsw + _i * 8192), 16, 0, 0); } while (0)
; #define PG8_LDA(dst, b, h) do { _Pragma("unroll") for (int m = 0; m < 4; ++m) _Pragma("unroll") for (int k = 0; k < 2; ++k) dst[m][k] = *(const PG8_LAS bf16x8*)(lds + PG8_SA(b, h) + aoff + m * 2048 + k * 1024); } while (0)
; #define PG8_LDB(dst, b, h) do { _Pragma("unroll") for (int n = 0; n < 2; ++n) _Pragma("unroll") for (int k = 0; k < 2; ++k) dst[n][k] = *(const PG8_LAS bf16x8*)(lds + PG8_SB(b, h) + boff + n * 2048 + k * 1024); } while (0)
; #define PG8_MMA(ai, bj, At, Bt) do { __builtin_amdgcn_s_setprio(1); _Pragma("unroll") for (int m = 0; m < 4; ++m) _Pragma("unroll") for (int n = 0; n < 2; ++n) _Pragma("unroll") for (int k = 0; k < 2; ++k) \
;         acc[ai][bj][m][n] = __builtin_amdgcn_mfma_f32_16x16x32_f16(Bt[n][k], At[m][k], acc[ai][bj][m][n], 0, 0, 0); __builtin_amdgcn_s_setprio(0); } while (0)
; #define PG8_WAIT_V(n) asm volatile("s_waitcnt vmcnt(" #n ")" ::: "memory")
; #define PG8_WAIT_L(n) asm volatile("s_waitcnt lgkmcnt(" #n ")" ::: "memory")
; #define PG8_BAR __builtin_amdgcn_s_barrier()
; #define PG8_SCHED __builtin_amdgcn_sched_barrier(0)
; template <class Epi, class Sched, bool ALIGN_EPI = false, bool SP2 = false>
; __device__ __forceinline__ void gemm_phase(PG8_LAS unsigned char* lds, const Gemm g, const Sched& S, const Epi& E) {
;     ...
;             const char* a2 = last ? nA : cA + (size_t)(t + 2) * kstep; const char* b2 = last ? nB : cB + (size_t)(t + 2) * kstep;
;             const char* a3 = a2 + kstep; const char* b3 = b2 + kstep;
;             if (last && has_next) S.a_ready(nxt);
;             if constexpr (SP2) {
;             PG8_LDB(B0, 0, 0); PG8_LDB(B1, 0, 1); PG8_SCHED; PG8_LDA(At, 0, 0); PG8_STAGE(PG8_SA(1, 1), a1 + hstep, voffA);
;             PG8_WAIT_V(8); PG8_WAIT_L(0); PG8_BAR; PG8_MMA(0, 0, At, B0); PG8_MMA(0, 1, At, B1); PG8_BAR; PG8_SCHED;
;             PG8_LDA(At, 0, 1); PG8_STAGE(PG8_SB(0, 0), b2, voffB); PG8_STAGE(PG8_SB(0, 1), b2 + hstep, voffB); PG8_STAGE(PG8_SA(0, 0), a2, voffA);
;             PG8_WAIT_V(8); PG8_WAIT_L(0); PG8_BAR; PG8_MMA(1, 0, At, B0); PG8_MMA(1, 1, At, B1); PG8_BAR; PG8_SCHED;
.LBB0_655:
	ds_read_b128 v[128:131], v211
	ds_read_b128 v[132:135], v211 offset:1024
	ds_read_b128 v[136:139], v211 offset:2048
	ds_read_b128 v[140:143], v211 offset:3072
	ds_read_b128 v[144:147], v212
	ds_read_b128 v[148:151], v212 offset:1024
	ds_read_b128 v[152:155], v212 offset:2048
	ds_read_b128 v[156:159], v212 offset:3072
	s_add_u32 s42, s40, 0xffe00080
	s_addc_u32 s43, s41, -1
	s_cmpk_eq_i32 s86, 0x7c
	s_cselect_b32 s45, s29, s43
	s_cselect_b32 s44, s37, s42
	s_cselect_b32 s43, s27, s83
	s_cselect_b32 s42, s81, s82
	s_add_i32 m0, s39, 0xc000
	ds_read_b128 v[160:163], v213
	ds_read_b128 v[164:167], v213 offset:1024
	ds_read_b128 v[184:187], v213 offset:2048
	ds_read_b128 v[188:191], v213 offset:3072
	ds_read_b128 v[192:195], v213 offset:4096
	ds_read_b128 v[196:199], v213 offset:5120
	ds_read_b128 v[200:203], v213 offset:6144
	ds_read_b128 v[214:217], v213 offset:7168
	global_load_lds_dwordx4 v178, s[40:41]
	s_add_i32 m0, s39, 0xe000
	s_nop 0
	global_load_lds_dwordx4 v176, s[40:41]
	s_waitcnt vmcnt(8)
	s_waitcnt lgkmcnt(0)
	s_barrier
	s_setprio 1
	s_waitcnt lgkmcnt(0)
	v_mfma_f32_16x16x32_f16 v[120:123], v[136:139], v[160:163], v[120:123]
	v_mfma_f32_16x16x32_f16 v[124:127], v[128:131], v[160:163], v[124:127]
	v_mfma_f32_16x16x32_f16 v[104:107], v[136:139], v[184:187], v[104:107]
	v_mfma_f32_16x16x32_f16 v[108:111], v[128:131], v[184:187], v[108:111]
	v_mfma_f32_16x16x32_f16 v[88:91], v[136:139], v[192:195], v[88:91]
	v_mfma_f32_16x16x32_f16 v[92:95], v[128:131], v[192:195], v[92:95]
	v_mfma_f32_16x16x32_f16 v[72:75], v[136:139], v[200:203], v[72:75]
	v_mfma_f32_16x16x32_f16 v[76:79], v[128:131], v[200:203], v[76:79]
	v_mfma_f32_16x16x32_f16 v[120:123], v[140:143], v[164:167], v[120:123]
	v_mfma_f32_16x16x32_f16 v[124:127], v[132:135], v[164:167], v[124:127]
	v_mfma_f32_16x16x32_f16 v[104:107], v[140:143], v[188:191], v[104:107]
	v_mfma_f32_16x16x32_f16 v[108:111], v[132:135], v[188:191], v[108:111]
	v_mfma_f32_16x16x32_f16 v[88:91], v[140:143], v[196:199], v[88:91]
	v_mfma_f32_16x16x32_f16 v[92:95], v[132:135], v[196:199], v[92:95]
	v_mfma_f32_16x16x32_f16 v[72:75], v[140:143], v[214:217], v[72:75]
	v_mfma_f32_16x16x32_f16 v[76:79], v[132:135], v[214:217], v[76:79]
	s_setprio 0
	s_setprio 1
	v_mfma_f32_16x16x32_f16 v[112:115], v[152:155], v[160:163], v[112:115]
	v_mfma_f32_16x16x32_f16 v[116:119], v[144:147], v[160:163], v[116:119]
	v_mfma_f32_16x16x32_f16 v[96:99], v[152:155], v[184:187], v[96:99]
	v_mfma_f32_16x16x32_f16 v[100:103], v[144:147], v[184:187], v[100:103]
	v_mfma_f32_16x16x32_f16 v[80:83], v[152:155], v[192:195], v[80:83]
	v_mfma_f32_16x16x32_f16 v[84:87], v[144:147], v[192:195], v[84:87]
	v_mfma_f32_16x16x32_f16 v[64:67], v[152:155], v[200:203], v[64:67]
	v_mfma_f32_16x16x32_f16 v[68:71], v[144:147], v[200:203], v[68:71]
	v_mfma_f32_16x16x32_f16 v[112:115], v[156:159], v[164:167], v[112:115]
	v_mfma_f32_16x16x32_f16 v[116:119], v[148:151], v[164:167], v[116:119]
	v_mfma_f32_16x16x32_f16 v[96:99], v[156:159], v[188:191], v[96:99]
	v_mfma_f32_16x16x32_f16 v[100:103], v[148:151], v[188:191], v[100:103]
	v_mfma_f32_16x16x32_f16 v[80:83], v[156:159], v[196:199], v[80:83]
	v_mfma_f32_16x16x32_f16 v[84:87], v[148:151], v[196:199], v[84:87]
	v_mfma_f32_16x16x32_f16 v[64:67], v[156:159], v[214:217], v[64:67]
	v_mfma_f32_16x16x32_f16 v[68:71], v[148:151], v[214:217], v[68:71]
	s_setprio 0
	s_barrier
	s_add_i32 s87, s69, s61
	s_add_u32 s98, s42, s18
	s_addc_u32 s99, s43, s19
	s_mov_b32 m0, s87
	ds_read_b128 v[160:163], v213 offset:16384
	ds_read_b128 v[164:167], v213 offset:17408
	ds_read_b128 v[184:187], v213 offset:18432
	ds_read_b128 v[188:191], v213 offset:19456
	ds_read_b128 v[192:195], v213 offset:20480
	ds_read_b128 v[196:199], v213 offset:21504
	ds_read_b128 v[200:203], v213 offset:22528
	ds_read_b128 v[214:217], v213 offset:23552
	global_load_lds_dwordx4 v170, s[42:43]
	s_add_i32 m0, s87, 0x2000
	s_add_u32 s88, s42, 0x200000
	s_addc_u32 s89, s43, 0
	s_add_i32 s87, s74, s61
	global_load_lds_dwordx4 v174, s[42:43]
	s_mov_b32 m0, s87
	s_nop 0
	global_load_lds_dwordx4 v170, s[88:89]
	s_add_i32 m0, s87, 0x2000
	s_nop 0
	global_load_lds_dwordx4 v174, s[88:89]
	s_add_u32 s100, s44, s18
	s_addc_u32 s101, s45, s19
	s_mov_b32 m0, s39
	s_nop 0
	global_load_lds_dwordx4 v168, s[44:45]
	s_mov_b32 m0, s62
	s_nop 0
	global_load_lds_dwordx4 v172, s[44:45]
	s_waitcnt vmcnt(8)
	s_waitcnt lgkmcnt(0)
	s_barrier
	s_setprio 1
	s_waitcnt lgkmcnt(0)
	v_mfma_f32_16x16x32_f16 v[56:59], v[136:139], v[160:163], v[56:59]
	v_mfma_f32_16x16x32_f16 v[60:63], v[128:131], v[160:163], v[60:63]
	v_mfma_f32_16x16x32_f16 v[40:43], v[136:139], v[184:187], v[40:43]
	v_mfma_f32_16x16x32_f16 v[44:47], v[128:131], v[184:187], v[44:47]
	v_mfma_f32_16x16x32_f16 v[24:27], v[136:139], v[192:195], v[24:27]
	v_mfma_f32_16x16x32_f16 v[28:31], v[128:131], v[192:195], v[28:31]
	v_mfma_f32_16x16x32_f16 v[8:11], v[136:139], v[200:203], v[8:11]
	v_mfma_f32_16x16x32_f16 v[12:15], v[128:131], v[200:203], v[12:15]
	v_mfma_f32_16x16x32_f16 v[56:59], v[140:143], v[164:167], v[56:59]
	v_mfma_f32_16x16x32_f16 v[60:63], v[132:135], v[164:167], v[60:63]
	v_mfma_f32_16x16x32_f16 v[40:43], v[140:143], v[188:191], v[40:43]
	v_mfma_f32_16x16x32_f16 v[44:47], v[132:135], v[188:191], v[44:47]
	v_mfma_f32_16x16x32_f16 v[24:27], v[140:143], v[196:199], v[24:27]
	v_mfma_f32_16x16x32_f16 v[28:31], v[132:135], v[196:199], v[28:31]
	v_mfma_f32_16x16x32_f16 v[8:11], v[140:143], v[214:217], v[8:11]
	v_mfma_f32_16x16x32_f16 v[12:15], v[132:135], v[214:217], v[12:15]
	s_setprio 0
	s_setprio 1
	v_mfma_f32_16x16x32_f16 v[48:51], v[152:155], v[160:163], v[48:51]
	v_mfma_f32_16x16x32_f16 v[52:55], v[144:147], v[160:163], v[52:55]
	v_mfma_f32_16x16x32_f16 v[32:35], v[152:155], v[184:187], v[32:35]
	v_mfma_f32_16x16x32_f16 v[36:39], v[144:147], v[184:187], v[36:39]
	v_mfma_f32_16x16x32_f16 v[16:19], v[152:155], v[192:195], v[16:19]
	v_mfma_f32_16x16x32_f16 v[20:23], v[144:147], v[192:195], v[20:23]
	v_mfma_f32_16x16x32_f16 v[0:3], v[152:155], v[200:203], v[0:3]
	v_mfma_f32_16x16x32_f16 v[4:7], v[144:147], v[200:203], v[4:7]
	v_mfma_f32_16x16x32_f16 v[48:51], v[156:159], v[164:167], v[48:51]
	v_mfma_f32_16x16x32_f16 v[52:55], v[148:151], v[164:167], v[52:55]
	v_mfma_f32_16x16x32_f16 v[32:35], v[156:159], v[188:191], v[32:35]
	v_mfma_f32_16x16x32_f16 v[36:39], v[148:151], v[188:191], v[36:39]
	v_mfma_f32_16x16x32_f16 v[16:19], v[156:159], v[196:199], v[16:19]
	v_mfma_f32_16x16x32_f16 v[20:23], v[148:151], v[196:199], v[20:23]
	v_mfma_f32_16x16x32_f16 v[0:3], v[156:159], v[214:217], v[0:3]
	v_mfma_f32_16x16x32_f16 v[4:7], v[148:151], v[214:217], v[4:7]
	s_setprio 0
	s_barrier
; #define PG8_STAGE(bufoff, gbase, voff) do { _Pragma("unroll") for (int _i = 0; _i < 2; ++_i) \
;         __builtin_amdgcn_global_load_lds((const unsigned*)((const char*)(gbase) + (voff)[_i]), (PG8_LAS unsigned*)(lds + (bufoff) + ldsw + _i * 8192), 16, 0, 0); } while (0)
; #define PG8_LDA(dst, b, h) do { _Pragma("unroll") for (int m = 0; m < 4; ++m) _Pragma("unroll") for (int k = 0; k < 2; ++k) dst[m][k] = *(const PG8_LAS bf16x8*)(lds + PG8_SA(b, h) + aoff + m * 2048 + k * 1024); } while (0)
; #define PG8_LDB(dst, b, h) do { _Pragma("unroll") for (int n = 0; n < 2; ++n) _Pragma("unroll") for (int k = 0; k < 2; ++k) dst[n][k] = *(const PG8_LAS bf16x8*)(lds + PG8_SB(b, h) + boff + n * 2048 + k * 1024); } while (0)
; #define PG8_MMA(ai, bj, At, Bt) do { __builtin_amdgcn_s_setprio(1); _Pragma("unroll") for (int m = 0; m < 4; ++m) _Pragma("unroll") for (int n = 0; n < 2; ++n) _Pragma("unroll") for (int k = 0; k < 2; ++k) \
;         acc[ai][bj][m][n] = __builtin_amdgcn_mfma_f32_16x16x32_f16(Bt[n][k], At[m][k], acc[ai][bj][m][n], 0, 0, 0); __builtin_amdgcn_s_setprio(0); } while (0)
; #define PG8_WAIT_V(n) asm volatile("s_waitcnt vmcnt(" #n ")" ::: "memory")
; #define PG8_WAIT_L(n) asm volatile("s_waitcnt lgkmcnt(" #n ")" ::: "memory")
; #define PG8_BAR __builtin_amdgcn_s_barrier()
; #define PG8_SCHED __builtin_amdgcn_sched_barrier(0)
; template <class Epi, class Sched, bool ALIGN_EPI = false, bool SP2 = false>
; __device__ __forceinline__ void gemm_phase(PG8_LAS unsigned char* lds, const Gemm g, const Sched& S, const Epi& E) {
;     ...
;             PG8_LDB(B0, 1, 0); PG8_LDB(B1, 1, 1); PG8_SCHED; PG8_LDA(At, 1, 0); PG8_STAGE(PG8_SA(0, 1), a2 + hstep, voffA);
;             PG8_WAIT_V(8); PG8_WAIT_L(0); PG8_BAR; PG8_MMA(0, 0, At, B0); PG8_MMA(0, 1, At, B1); PG8_BAR; PG8_SCHED;
;             PG8_LDA(At, 1, 1); PG8_STAGE(PG8_SB(1, 0), b3, voffB); PG8_STAGE(PG8_SB(1, 1), b3 + hstep, voffB); PG8_STAGE(PG8_SA(1, 0), a3, voffA);
;             PG8_WAIT_V(8); PG8_WAIT_L(0); PG8_BAR; PG8_MMA(1, 0, At, B0); PG8_MMA(1, 1, At, B1); PG8_BAR; PG8_SCHED;
	s_add_i32 s87, 0, 0x18000
	s_add_i32 s88, 0, 0x1c000
	v_add_u32_e32 v140, s87, v209
	v_add_u32_e32 v156, s88, v209
	ds_read_b128 v[128:131], v140
	ds_read_b128 v[132:135], v140 offset:1024
	ds_read_b128 v[136:139], v140 offset:2048
	ds_read_b128 v[140:143], v140 offset:3072
	ds_read_b128 v[144:147], v156
	ds_read_b128 v[148:151], v156 offset:1024
	ds_read_b128 v[152:155], v156 offset:2048
	ds_read_b128 v[156:159], v156 offset:3072
	s_add_u32 s44, s44, 0x200000
	s_addc_u32 s45, s45, 0
	s_mov_b32 m0, s63
	ds_read_b128 v[160:163], v213 offset:32768
	ds_read_b128 v[164:167], v213 offset:33792
	ds_read_b128 v[184:187], v213 offset:34816
	ds_read_b128 v[188:191], v213 offset:35840
	ds_read_b128 v[192:195], v213 offset:36864
	ds_read_b128 v[196:199], v213 offset:37888
	ds_read_b128 v[200:203], v213 offset:38912
	ds_read_b128 v[214:217], v213 offset:39936
	global_load_lds_dwordx4 v168, s[44:45]
	s_mov_b32 m0, s64
	s_nop 0
	global_load_lds_dwordx4 v172, s[44:45]
	s_waitcnt vmcnt(8)
	s_waitcnt lgkmcnt(0)
	s_barrier
	s_setprio 1
	s_waitcnt lgkmcnt(0)
	v_mfma_f32_16x16x32_f16 v[120:123], v[136:139], v[160:163], v[120:123]
	v_mfma_f32_16x16x32_f16 v[124:127], v[128:131], v[160:163], v[124:127]
	v_mfma_f32_16x16x32_f16 v[104:107], v[136:139], v[184:187], v[104:107]
	v_mfma_f32_16x16x32_f16 v[108:111], v[128:131], v[184:187], v[108:111]
	v_mfma_f32_16x16x32_f16 v[88:91], v[136:139], v[192:195], v[88:91]
	v_mfma_f32_16x16x32_f16 v[92:95], v[128:131], v[192:195], v[92:95]
	v_mfma_f32_16x16x32_f16 v[72:75], v[136:139], v[200:203], v[72:75]
	v_mfma_f32_16x16x32_f16 v[76:79], v[128:131], v[200:203], v[76:79]
	v_mfma_f32_16x16x32_f16 v[120:123], v[140:143], v[164:167], v[120:123]
	v_mfma_f32_16x16x32_f16 v[124:127], v[132:135], v[164:167], v[124:127]
	v_mfma_f32_16x16x32_f16 v[104:107], v[140:143], v[188:191], v[104:107]
	v_mfma_f32_16x16x32_f16 v[108:111], v[132:135], v[188:191], v[108:111]
	v_mfma_f32_16x16x32_f16 v[88:91], v[140:143], v[196:199], v[88:91]
	v_mfma_f32_16x16x32_f16 v[92:95], v[132:135], v[196:199], v[92:95]
	v_mfma_f32_16x16x32_f16 v[72:75], v[140:143], v[214:217], v[72:75]
	v_mfma_f32_16x16x32_f16 v[76:79], v[132:135], v[214:217], v[76:79]
	s_setprio 0
	s_setprio 1
	v_mfma_f32_16x16x32_f16 v[112:115], v[152:155], v[160:163], v[112:115]
	v_mfma_f32_16x16x32_f16 v[116:119], v[144:147], v[160:163], v[116:119]
	v_mfma_f32_16x16x32_f16 v[96:99], v[152:155], v[184:187], v[96:99]
	v_mfma_f32_16x16x32_f16 v[100:103], v[144:147], v[184:187], v[100:103]
	v_mfma_f32_16x16x32_f16 v[80:83], v[152:155], v[192:195], v[80:83]
	v_mfma_f32_16x16x32_f16 v[84:87], v[144:147], v[192:195], v[84:87]
	v_mfma_f32_16x16x32_f16 v[64:67], v[152:155], v[200:203], v[64:67]
	v_mfma_f32_16x16x32_f16 v[68:71], v[144:147], v[200:203], v[68:71]
	v_mfma_f32_16x16x32_f16 v[112:115], v[156:159], v[164:167], v[112:115]
	v_mfma_f32_16x16x32_f16 v[116:119], v[148:151], v[164:167], v[116:119]
	v_mfma_f32_16x16x32_f16 v[96:99], v[156:159], v[188:191], v[96:99]
	v_mfma_f32_16x16x32_f16 v[100:103], v[148:151], v[188:191], v[100:103]
	v_mfma_f32_16x16x32_f16 v[80:83], v[156:159], v[196:199], v[80:83]
	v_mfma_f32_16x16x32_f16 v[84:87], v[148:151], v[196:199], v[84:87]
	v_mfma_f32_16x16x32_f16 v[64:67], v[156:159], v[214:217], v[64:67]
	v_mfma_f32_16x16x32_f16 v[68:71], v[148:151], v[214:217], v[68:71]
	s_setprio 0
	s_barrier
	s_add_i32 s44, s87, s61
	s_mov_b32 m0, s44
	ds_read_b128 v[160:163], v213 offset:49152
	ds_read_b128 v[164:167], v213 offset:50176
	ds_read_b128 v[184:187], v213 offset:51200
	ds_read_b128 v[188:191], v213 offset:52224
	ds_read_b128 v[192:195], v213 offset:53248
	ds_read_b128 v[196:199], v213 offset:54272
	ds_read_b128 v[200:203], v213 offset:55296
	ds_read_b128 v[214:217], v213 offset:56320
	global_load_lds_dwordx4 v170, s[98:99]
	s_add_i32 m0, s44, 0x2000
	s_add_u32 s42, s42, 0x200080
	s_addc_u32 s43, s43, 0
	s_add_i32 s44, s88, s61
	global_load_lds_dwordx4 v174, s[98:99]
	s_mov_b32 m0, s44
	s_nop 0
	global_load_lds_dwordx4 v170, s[42:43]
	s_add_i32 m0, s44, 0x2000
	s_nop 0
	global_load_lds_dwordx4 v174, s[42:43]
	s_mov_b32 m0, s66
	s_nop 0
	global_load_lds_dwordx4 v168, s[100:101]
	s_mov_b32 m0, s67
	s_nop 0
	global_load_lds_dwordx4 v172, s[100:101]
	s_waitcnt vmcnt(8)
	s_waitcnt lgkmcnt(0)
	s_barrier
	s_setprio 1
	s_waitcnt lgkmcnt(0)
	v_mfma_f32_16x16x32_f16 v[56:59], v[136:139], v[160:163], v[56:59]
	v_mfma_f32_16x16x32_f16 v[60:63], v[128:131], v[160:163], v[60:63]
	v_mfma_f32_16x16x32_f16 v[40:43], v[136:139], v[184:187], v[40:43]
	v_mfma_f32_16x16x32_f16 v[44:47], v[128:131], v[184:187], v[44:47]
	v_mfma_f32_16x16x32_f16 v[24:27], v[136:139], v[192:195], v[24:27]
	v_mfma_f32_16x16x32_f16 v[28:31], v[128:131], v[192:195], v[28:31]
	v_mfma_f32_16x16x32_f16 v[8:11], v[136:139], v[200:203], v[8:11]
	v_mfma_f32_16x16x32_f16 v[12:15], v[128:131], v[200:203], v[12:15]
	v_mfma_f32_16x16x32_f16 v[56:59], v[140:143], v[164:167], v[56:59]
	v_mfma_f32_16x16x32_f16 v[60:63], v[132:135], v[164:167], v[60:63]
	v_mfma_f32_16x16x32_f16 v[40:43], v[140:143], v[188:191], v[40:43]
	v_mfma_f32_16x16x32_f16 v[44:47], v[132:135], v[188:191], v[44:47]
	v_mfma_f32_16x16x32_f16 v[24:27], v[140:143], v[196:199], v[24:27]
	v_mfma_f32_16x16x32_f16 v[28:31], v[132:135], v[196:199], v[28:31]
	v_mfma_f32_16x16x32_f16 v[8:11], v[140:143], v[214:217], v[8:11]
	v_mfma_f32_16x16x32_f16 v[12:15], v[132:135], v[214:217], v[12:15]
	s_setprio 0
	s_setprio 1
	v_mfma_f32_16x16x32_f16 v[48:51], v[152:155], v[160:163], v[48:51]
	v_mfma_f32_16x16x32_f16 v[52:55], v[144:147], v[160:163], v[52:55]
	v_mfma_f32_16x16x32_f16 v[32:35], v[152:155], v[184:187], v[32:35]
	v_mfma_f32_16x16x32_f16 v[36:39], v[144:147], v[184:187], v[36:39]
	v_mfma_f32_16x16x32_f16 v[16:19], v[152:155], v[192:195], v[16:19]
	v_mfma_f32_16x16x32_f16 v[20:23], v[144:147], v[192:195], v[20:23]
	v_mfma_f32_16x16x32_f16 v[0:3], v[152:155], v[200:203], v[0:3]
	v_mfma_f32_16x16x32_f16 v[4:7], v[144:147], v[200:203], v[4:7]
	v_mfma_f32_16x16x32_f16 v[48:51], v[156:159], v[164:167], v[48:51]
	v_mfma_f32_16x16x32_f16 v[52:55], v[148:151], v[164:167], v[52:55]
	v_mfma_f32_16x16x32_f16 v[32:35], v[156:159], v[188:191], v[32:35]
	v_mfma_f32_16x16x32_f16 v[36:39], v[148:151], v[188:191], v[36:39]
	v_mfma_f32_16x16x32_f16 v[16:19], v[156:159], v[196:199], v[16:19]
	v_mfma_f32_16x16x32_f16 v[20:23], v[148:151], v[196:199], v[20:23]
	v_mfma_f32_16x16x32_f16 v[0:3], v[156:159], v[214:217], v[0:3]
	v_mfma_f32_16x16x32_f16 v[4:7], v[148:151], v[214:217], v[4:7]
	s_setprio 0
	s_barrier
	s_add_i32 s86, s86, 2
	s_add_u32 s82, s82, 0x100
	s_addc_u32 s83, s83, 0
	s_add_u32 s40, s40, 0x100
	s_addc_u32 s41, s41, 0
	s_cmpk_gt_u32 s86, 0x7d
	s_cbranch_scc0 .LBB0_655
	s_and_b64 vcc, exec, s[20:21]
	s_cbranch_vccz .LBB0_658
	s_barrier

; #define PG8_STAGE(bufoff, gbase, voff) do { _Pragma("unroll") for (int _i = 0; _i < 2; ++_i) \
;         __builtin_amdgcn_global_load_lds((const unsigned*)((const char*)(gbase) + (voff)[_i]), (PG8_LAS unsigned*)(lds + (bufoff) + ldsw + _i * 8192), 16, 0, 0); } while (0)
; #define PG8_LDA(dst, b, h) do { _Pragma("unroll") for (int m = 0; m < 4; ++m) _Pragma("unroll") for (int k = 0; k < 2; ++k) dst[m][k] = *(const PG8_LAS bf16x8*)(lds + PG8_SA(b, h) + aoff + m * 2048 + k * 1024); } while (0)
; #define PG8_LDB(dst, b, h) do { _Pragma("unroll") for (int n = 0; n < 2; ++n) _Pragma("unroll") for (int k = 0; k < 2; ++k) dst[n][k] = *(const PG8_LAS bf16x8*)(lds + PG8_SB(b, h) + boff + n * 2048 + k * 1024); } while (0)
; #define PG8_MMA(ai, bj, At, Bt) do { __builtin_amdgcn_s_setprio(1); _Pragma("unroll") for (int m = 0; m < 4; ++m) _Pragma("unroll") for (int n = 0; n < 2; ++n) _Pragma("unroll") for (int k = 0; k < 2; ++k) \
;         acc[ai][bj][m][n] = __builtin_amdgcn_mfma_f32_16x16x32_f16(Bt[n][k], At[m][k], acc[ai][bj][m][n], 0, 0, 0); __builtin_amdgcn_s_setprio(0); } while (0)
; #define PG8_WAIT_V(n) asm volatile("s_waitcnt vmcnt(" #n ")" ::: "memory")
; #define PG8_WAIT_L(n) asm volatile("s_waitcnt lgkmcnt(" #n ")" ::: "memory")
; #define PG8_BAR __builtin_amdgcn_s_barrier()
; #define PG8_SCHED __builtin_amdgcn_sched_barrier(0)
; template <class Epi, class Sched, bool ALIGN_EPI = false, bool SP2 = false>
; __device__ __forceinline__ void gemm_phase(PG8_LAS unsigned char* lds, const Gemm g, const Sched& S, const Epi& E) {
;     ...
;             const char* a2 = last ? nA : cA + (size_t)(t + 2) * kstep; const char* b2 = last ? nB : cB + (size_t)(t + 2) * kstep;
;             const char* a3 = a2 + kstep; const char* b3 = b2 + kstep;
;             if (last && has_next) S.a_ready(nxt);
;             if constexpr (SP2) {
;             PG8_LDB(B0, 0, 0); PG8_LDB(B1, 0, 1); PG8_SCHED; PG8_LDA(At, 0, 0); PG8_STAGE(PG8_SA(1, 1), a1 + hstep, voffA);
;             PG8_WAIT_V(8); PG8_WAIT_L(0); PG8_BAR; PG8_MMA(0, 0, At, B0); PG8_MMA(0, 1, At, B1); PG8_BAR; PG8_SCHED;
;             PG8_LDA(At, 0, 1); PG8_STAGE(PG8_SB(0, 0), b2, voffB); PG8_STAGE(PG8_SB(0, 1), b2 + hstep, voffB); PG8_STAGE(PG8_SA(0, 0), a2, voffA);
;             PG8_WAIT_V(8); PG8_WAIT_L(0); PG8_BAR; PG8_MMA(1, 0, At, B0); PG8_MMA(1, 1, At, B1); PG8_BAR; PG8_SCHED;
.LBB0_747:
	ds_read_b128 v[128:131], v191
	ds_read_b128 v[132:135], v191 offset:1024
	ds_read_b128 v[136:139], v191 offset:2048
	ds_read_b128 v[140:143], v191 offset:3072
	ds_read_b128 v[144:147], v192
	ds_read_b128 v[148:151], v192 offset:1024
	ds_read_b128 v[152:155], v192 offset:2048
	ds_read_b128 v[156:159], v192 offset:3072
	s_add_u32 s48, s44, 0xfff80080
	s_addc_u32 s49, s45, -1
	s_cmp_eq_u32 s90, 28
	s_cselect_b32 s51, s37, s49
	s_cselect_b32 s50, s86, s48
	s_cselect_b32 s49, s35, s89
	s_cselect_b32 s48, s87, s88
	s_add_i32 m0, s43, 0xc000
	ds_read_b128 v[176:179], v193
	ds_read_b128 v[180:183], v193 offset:1024
	ds_read_b128 v[184:187], v193 offset:2048
	ds_read_b128 v[194:197], v193 offset:3072
	ds_read_b128 v[198:201], v193 offset:4096
	ds_read_b128 v[208:211], v193 offset:5120
	ds_read_b128 v[212:215], v193 offset:6144
	ds_read_b128 v[216:219], v193 offset:7168
	global_load_lds_dwordx4 v170, s[44:45]
	s_add_i32 m0, s43, 0xe000
	s_nop 0
	global_load_lds_dwordx4 v168, s[44:45]
	s_waitcnt vmcnt(8)
	s_waitcnt lgkmcnt(0)
	s_barrier
	s_setprio 1
	s_waitcnt lgkmcnt(0)
	v_mfma_f32_16x16x32_f16 v[120:123], v[136:139], v[176:179], v[120:123]
	v_mfma_f32_16x16x32_f16 v[124:127], v[128:131], v[176:179], v[124:127]
	v_mfma_f32_16x16x32_f16 v[104:107], v[136:139], v[184:187], v[104:107]
	v_mfma_f32_16x16x32_f16 v[112:115], v[128:131], v[184:187], v[112:115]
	v_mfma_f32_16x16x32_f16 v[88:91], v[136:139], v[198:201], v[88:91]
	v_mfma_f32_16x16x32_f16 v[96:99], v[128:131], v[198:201], v[96:99]
	v_mfma_f32_16x16x32_f16 v[72:75], v[136:139], v[212:215], v[72:75]
	v_mfma_f32_16x16x32_f16 v[80:83], v[128:131], v[212:215], v[80:83]
	v_mfma_f32_16x16x32_f16 v[120:123], v[140:143], v[180:183], v[120:123]
	v_mfma_f32_16x16x32_f16 v[124:127], v[132:135], v[180:183], v[124:127]
	v_mfma_f32_16x16x32_f16 v[104:107], v[140:143], v[194:197], v[104:107]
	v_mfma_f32_16x16x32_f16 v[112:115], v[132:135], v[194:197], v[112:115]
	v_mfma_f32_16x16x32_f16 v[88:91], v[140:143], v[208:211], v[88:91]
	v_mfma_f32_16x16x32_f16 v[96:99], v[132:135], v[208:211], v[96:99]
	v_mfma_f32_16x16x32_f16 v[72:75], v[140:143], v[216:219], v[72:75]
	v_mfma_f32_16x16x32_f16 v[80:83], v[132:135], v[216:219], v[80:83]
	s_setprio 0
	s_setprio 1
	v_mfma_f32_16x16x32_f16 v[108:111], v[152:155], v[176:179], v[108:111]
	v_mfma_f32_16x16x32_f16 v[116:119], v[144:147], v[176:179], v[116:119]
	v_mfma_f32_16x16x32_f16 v[92:95], v[152:155], v[184:187], v[92:95]
	v_mfma_f32_16x16x32_f16 v[100:103], v[144:147], v[184:187], v[100:103]
	v_mfma_f32_16x16x32_f16 v[76:79], v[152:155], v[198:201], v[76:79]
	v_mfma_f32_16x16x32_f16 v[84:87], v[144:147], v[198:201], v[84:87]
	v_mfma_f32_16x16x32_f16 v[64:67], v[152:155], v[212:215], v[64:67]
	v_mfma_f32_16x16x32_f16 v[68:71], v[144:147], v[212:215], v[68:71]
	v_mfma_f32_16x16x32_f16 v[108:111], v[156:159], v[180:183], v[108:111]
	v_mfma_f32_16x16x32_f16 v[116:119], v[148:151], v[180:183], v[116:119]
	v_mfma_f32_16x16x32_f16 v[92:95], v[156:159], v[194:197], v[92:95]
	v_mfma_f32_16x16x32_f16 v[100:103], v[148:151], v[194:197], v[100:103]
	v_mfma_f32_16x16x32_f16 v[76:79], v[156:159], v[208:211], v[76:79]
	v_mfma_f32_16x16x32_f16 v[84:87], v[148:151], v[208:211], v[84:87]
	v_mfma_f32_16x16x32_f16 v[64:67], v[156:159], v[216:219], v[64:67]
	v_mfma_f32_16x16x32_f16 v[68:71], v[148:151], v[216:219], v[68:71]
	s_setprio 0
	s_barrier
	s_add_i32 s91, s68, s61
	s_add_u32 s98, s48, s18
	s_addc_u32 s99, s49, s19
	s_mov_b32 m0, s91
	ds_read_b128 v[176:179], v193 offset:16384
	ds_read_b128 v[180:183], v193 offset:17408
	ds_read_b128 v[184:187], v193 offset:18432
	ds_read_b128 v[194:197], v193 offset:19456
	ds_read_b128 v[198:201], v193 offset:20480
	ds_read_b128 v[208:211], v193 offset:21504
	ds_read_b128 v[212:215], v193 offset:22528
	ds_read_b128 v[216:219], v193 offset:23552
	global_load_lds_dwordx4 v162, s[48:49]
	s_add_i32 m0, s91, 0x2000
	s_add_u32 s92, s48, 0x80000
	s_addc_u32 s93, s49, 0
	s_add_i32 s91, s69, s61
	global_load_lds_dwordx4 v166, s[48:49]
	s_mov_b32 m0, s91
	s_nop 0
	global_load_lds_dwordx4 v162, s[92:93]
	s_add_i32 m0, s91, 0x2000
	s_nop 0
	global_load_lds_dwordx4 v166, s[92:93]
	s_add_u32 s100, s50, s18
	s_addc_u32 s101, s51, s19
	s_mov_b32 m0, s43
	s_nop 0
	global_load_lds_dwordx4 v160, s[50:51]
	s_mov_b32 m0, s62
	s_nop 0
	global_load_lds_dwordx4 v164, s[50:51]
	s_waitcnt vmcnt(8)
	s_waitcnt lgkmcnt(0)
	s_barrier
	s_setprio 1
	s_waitcnt lgkmcnt(0)
	v_mfma_f32_16x16x32_f16 v[56:59], v[136:139], v[176:179], v[56:59]
	v_mfma_f32_16x16x32_f16 v[60:63], v[128:131], v[176:179], v[60:63]
	v_mfma_f32_16x16x32_f16 v[44:47], v[136:139], v[184:187], v[44:47]
	v_mfma_f32_16x16x32_f16 v[52:55], v[128:131], v[184:187], v[52:55]
	v_mfma_f32_16x16x32_f16 v[28:31], v[136:139], v[198:201], v[28:31]
	v_mfma_f32_16x16x32_f16 v[36:39], v[128:131], v[198:201], v[36:39]
	v_mfma_f32_16x16x32_f16 v[12:15], v[136:139], v[212:215], v[12:15]
	v_mfma_f32_16x16x32_f16 v[20:23], v[128:131], v[212:215], v[20:23]
	v_mfma_f32_16x16x32_f16 v[56:59], v[140:143], v[180:183], v[56:59]
	v_mfma_f32_16x16x32_f16 v[60:63], v[132:135], v[180:183], v[60:63]
	v_mfma_f32_16x16x32_f16 v[44:47], v[140:143], v[194:197], v[44:47]
	v_mfma_f32_16x16x32_f16 v[52:55], v[132:135], v[194:197], v[52:55]
	v_mfma_f32_16x16x32_f16 v[28:31], v[140:143], v[208:211], v[28:31]
	v_mfma_f32_16x16x32_f16 v[36:39], v[132:135], v[208:211], v[36:39]
	v_mfma_f32_16x16x32_f16 v[12:15], v[140:143], v[216:219], v[12:15]
	v_mfma_f32_16x16x32_f16 v[20:23], v[132:135], v[216:219], v[20:23]
	s_setprio 0
	s_setprio 1
	v_mfma_f32_16x16x32_f16 v[40:43], v[152:155], v[176:179], v[40:43]
	v_mfma_f32_16x16x32_f16 v[48:51], v[144:147], v[176:179], v[48:51]
	v_mfma_f32_16x16x32_f16 v[24:27], v[152:155], v[184:187], v[24:27]
	v_mfma_f32_16x16x32_f16 v[32:35], v[144:147], v[184:187], v[32:35]
	v_mfma_f32_16x16x32_f16 v[8:11], v[152:155], v[198:201], v[8:11]
	v_mfma_f32_16x16x32_f16 v[16:19], v[144:147], v[198:201], v[16:19]
	v_mfma_f32_16x16x32_f16 v[0:3], v[152:155], v[212:215], v[0:3]
	v_mfma_f32_16x16x32_f16 v[4:7], v[144:147], v[212:215], v[4:7]
	v_mfma_f32_16x16x32_f16 v[40:43], v[156:159], v[180:183], v[40:43]
	v_mfma_f32_16x16x32_f16 v[48:51], v[148:151], v[180:183], v[48:51]
	v_mfma_f32_16x16x32_f16 v[24:27], v[156:159], v[194:197], v[24:27]
	v_mfma_f32_16x16x32_f16 v[32:35], v[148:151], v[194:197], v[32:35]
	v_mfma_f32_16x16x32_f16 v[8:11], v[156:159], v[208:211], v[8:11]
	v_mfma_f32_16x16x32_f16 v[16:19], v[148:151], v[208:211], v[16:19]
	v_mfma_f32_16x16x32_f16 v[0:3], v[156:159], v[216:219], v[0:3]
	v_mfma_f32_16x16x32_f16 v[4:7], v[148:151], v[216:219], v[4:7]
	s_setprio 0
	s_barrier
; #define PG8_STAGE(bufoff, gbase, voff) do { _Pragma("unroll") for (int _i = 0; _i < 2; ++_i) \
;         __builtin_amdgcn_global_load_lds((const unsigned*)((const char*)(gbase) + (voff)[_i]), (PG8_LAS unsigned*)(lds + (bufoff) + ldsw + _i * 8192), 16, 0, 0); } while (0)
; #define PG8_LDA(dst, b, h) do { _Pragma("unroll") for (int m = 0; m < 4; ++m) _Pragma("unroll") for (int k = 0; k < 2; ++k) dst[m][k] = *(const PG8_LAS bf16x8*)(lds + PG8_SA(b, h) + aoff + m * 2048 + k * 1024); } while (0)
; #define PG8_LDB(dst, b, h) do { _Pragma("unroll") for (int n = 0; n < 2; ++n) _Pragma("unroll") for (int k = 0; k < 2; ++k) dst[n][k] = *(const PG8_LAS bf16x8*)(lds + PG8_SB(b, h) + boff + n * 2048 + k * 1024); } while (0)
; #define PG8_MMA(ai, bj, At, Bt) do { __builtin_amdgcn_s_setprio(1); _Pragma("unroll") for (int m = 0; m < 4; ++m) _Pragma("unroll") for (int n = 0; n < 2; ++n) _Pragma("unroll") for (int k = 0; k < 2; ++k) \
;         acc[ai][bj][m][n] = __builtin_amdgcn_mfma_f32_16x16x32_f16(Bt[n][k], At[m][k], acc[ai][bj][m][n], 0, 0, 0); __builtin_amdgcn_s_setprio(0); } while (0)
; #define PG8_WAIT_V(n) asm volatile("s_waitcnt vmcnt(" #n ")" ::: "memory")
; #define PG8_WAIT_L(n) asm volatile("s_waitcnt lgkmcnt(" #n ")" ::: "memory")
; #define PG8_BAR __builtin_amdgcn_s_barrier()
; #define PG8_SCHED __builtin_amdgcn_sched_barrier(0)
; template <class Epi, class Sched, bool ALIGN_EPI = false, bool SP2 = false>
; __device__ __forceinline__ void gemm_phase(PG8_LAS unsigned char* lds, const Gemm g, const Sched& S, const Epi& E) {
;     ...
;             PG8_LDB(B0, 1, 0); PG8_LDB(B1, 1, 1); PG8_SCHED; PG8_LDA(At, 1, 0); PG8_STAGE(PG8_SA(0, 1), a2 + hstep, voffA);
;             PG8_WAIT_V(8); PG8_WAIT_L(0); PG8_BAR; PG8_MMA(0, 0, At, B0); PG8_MMA(0, 1, At, B1); PG8_BAR; PG8_SCHED;
;             PG8_LDA(At, 1, 1); PG8_STAGE(PG8_SB(1, 0), b3, voffB); PG8_STAGE(PG8_SB(1, 1), b3 + hstep, voffB); PG8_STAGE(PG8_SA(1, 0), a3, voffA);
;             PG8_WAIT_V(8); PG8_WAIT_L(0); PG8_BAR; PG8_MMA(1, 0, At, B0); PG8_MMA(1, 1, At, B1); PG8_BAR; PG8_SCHED;
	s_add_i32 s91, 0, 0x18000
	s_add_i32 s92, 0, 0x1c000
	v_add_u32_e32 v140, s91, v189
	v_add_u32_e32 v156, s92, v189
	ds_read_b128 v[128:131], v140
	ds_read_b128 v[132:135], v140 offset:1024
	ds_read_b128 v[136:139], v140 offset:2048
	ds_read_b128 v[140:143], v140 offset:3072
	ds_read_b128 v[144:147], v156
	ds_read_b128 v[148:151], v156 offset:1024
	ds_read_b128 v[152:155], v156 offset:2048
	ds_read_b128 v[156:159], v156 offset:3072
	s_add_u32 s50, s50, 0x80000
	s_addc_u32 s51, s51, 0
	s_mov_b32 m0, s63
	ds_read_b128 v[176:179], v193 offset:32768
	ds_read_b128 v[180:183], v193 offset:33792
	ds_read_b128 v[184:187], v193 offset:34816
	ds_read_b128 v[194:197], v193 offset:35840
	ds_read_b128 v[198:201], v193 offset:36864
	ds_read_b128 v[208:211], v193 offset:37888
	ds_read_b128 v[212:215], v193 offset:38912
	ds_read_b128 v[216:219], v193 offset:39936
	global_load_lds_dwordx4 v160, s[50:51]
	s_mov_b32 m0, s64
	s_nop 0
	global_load_lds_dwordx4 v164, s[50:51]
	s_waitcnt vmcnt(8)
	s_waitcnt lgkmcnt(0)
	s_barrier
	s_setprio 1
	s_waitcnt lgkmcnt(0)
	v_mfma_f32_16x16x32_f16 v[120:123], v[136:139], v[176:179], v[120:123]
	v_mfma_f32_16x16x32_f16 v[124:127], v[128:131], v[176:179], v[124:127]
	v_mfma_f32_16x16x32_f16 v[104:107], v[136:139], v[184:187], v[104:107]
	v_mfma_f32_16x16x32_f16 v[112:115], v[128:131], v[184:187], v[112:115]
	v_mfma_f32_16x16x32_f16 v[88:91], v[136:139], v[198:201], v[88:91]
	v_mfma_f32_16x16x32_f16 v[96:99], v[128:131], v[198:201], v[96:99]
	v_mfma_f32_16x16x32_f16 v[72:75], v[136:139], v[212:215], v[72:75]
	v_mfma_f32_16x16x32_f16 v[80:83], v[128:131], v[212:215], v[80:83]
	v_mfma_f32_16x16x32_f16 v[120:123], v[140:143], v[180:183], v[120:123]
	v_mfma_f32_16x16x32_f16 v[124:127], v[132:135], v[180:183], v[124:127]
	v_mfma_f32_16x16x32_f16 v[104:107], v[140:143], v[194:197], v[104:107]
	v_mfma_f32_16x16x32_f16 v[112:115], v[132:135], v[194:197], v[112:115]
	v_mfma_f32_16x16x32_f16 v[88:91], v[140:143], v[208:211], v[88:91]
	v_mfma_f32_16x16x32_f16 v[96:99], v[132:135], v[208:211], v[96:99]
	v_mfma_f32_16x16x32_f16 v[72:75], v[140:143], v[216:219], v[72:75]
	v_mfma_f32_16x16x32_f16 v[80:83], v[132:135], v[216:219], v[80:83]
	s_setprio 0
	s_setprio 1
	v_mfma_f32_16x16x32_f16 v[108:111], v[152:155], v[176:179], v[108:111]
	v_mfma_f32_16x16x32_f16 v[116:119], v[144:147], v[176:179], v[116:119]
	v_mfma_f32_16x16x32_f16 v[92:95], v[152:155], v[184:187], v[92:95]
	v_mfma_f32_16x16x32_f16 v[100:103], v[144:147], v[184:187], v[100:103]
	v_mfma_f32_16x16x32_f16 v[76:79], v[152:155], v[198:201], v[76:79]
	v_mfma_f32_16x16x32_f16 v[84:87], v[144:147], v[198:201], v[84:87]
	v_mfma_f32_16x16x32_f16 v[64:67], v[152:155], v[212:215], v[64:67]
	v_mfma_f32_16x16x32_f16 v[68:71], v[144:147], v[212:215], v[68:71]
	v_mfma_f32_16x16x32_f16 v[108:111], v[156:159], v[180:183], v[108:111]
	v_mfma_f32_16x16x32_f16 v[116:119], v[148:151], v[180:183], v[116:119]
	v_mfma_f32_16x16x32_f16 v[92:95], v[156:159], v[194:197], v[92:95]
	v_mfma_f32_16x16x32_f16 v[100:103], v[148:151], v[194:197], v[100:103]
	v_mfma_f32_16x16x32_f16 v[76:79], v[156:159], v[208:211], v[76:79]
	v_mfma_f32_16x16x32_f16 v[84:87], v[148:151], v[208:211], v[84:87]
	v_mfma_f32_16x16x32_f16 v[64:67], v[156:159], v[216:219], v[64:67]
	v_mfma_f32_16x16x32_f16 v[68:71], v[148:151], v[216:219], v[68:71]
	s_setprio 0
	s_barrier
	s_add_i32 s50, s91, s61
	s_mov_b32 m0, s50
	ds_read_b128 v[176:179], v193 offset:49152
	ds_read_b128 v[180:183], v193 offset:50176
	ds_read_b128 v[184:187], v193 offset:51200
	ds_read_b128 v[194:197], v193 offset:52224
	ds_read_b128 v[198:201], v193 offset:53248
	ds_read_b128 v[208:211], v193 offset:54272
	ds_read_b128 v[212:215], v193 offset:55296
	ds_read_b128 v[216:219], v193 offset:56320
	global_load_lds_dwordx4 v162, s[98:99]
	s_add_i32 m0, s50, 0x2000
	s_add_u32 s48, s48, 0x80080
	s_addc_u32 s49, s49, 0
	s_add_i32 s50, s92, s61
	global_load_lds_dwordx4 v166, s[98:99]
	s_mov_b32 m0, s50
	s_nop 0
	global_load_lds_dwordx4 v162, s[48:49]
	s_add_i32 m0, s50, 0x2000
	s_nop 0
	global_load_lds_dwordx4 v166, s[48:49]
	s_mov_b32 m0, s66
	s_nop 0
	global_load_lds_dwordx4 v160, s[100:101]
	s_mov_b32 m0, s67
	s_nop 0
	global_load_lds_dwordx4 v164, s[100:101]
	s_waitcnt vmcnt(8)
	s_waitcnt lgkmcnt(0)
	s_barrier
	s_setprio 1
	s_waitcnt lgkmcnt(0)
	v_mfma_f32_16x16x32_f16 v[56:59], v[136:139], v[176:179], v[56:59]
	v_mfma_f32_16x16x32_f16 v[60:63], v[128:131], v[176:179], v[60:63]
	v_mfma_f32_16x16x32_f16 v[44:47], v[136:139], v[184:187], v[44:47]
	v_mfma_f32_16x16x32_f16 v[52:55], v[128:131], v[184:187], v[52:55]
	v_mfma_f32_16x16x32_f16 v[28:31], v[136:139], v[198:201], v[28:31]
	v_mfma_f32_16x16x32_f16 v[36:39], v[128:131], v[198:201], v[36:39]
	v_mfma_f32_16x16x32_f16 v[12:15], v[136:139], v[212:215], v[12:15]
	v_mfma_f32_16x16x32_f16 v[20:23], v[128:131], v[212:215], v[20:23]
	v_mfma_f32_16x16x32_f16 v[56:59], v[140:143], v[180:183], v[56:59]
	v_mfma_f32_16x16x32_f16 v[60:63], v[132:135], v[180:183], v[60:63]
	v_mfma_f32_16x16x32_f16 v[44:47], v[140:143], v[194:197], v[44:47]
	v_mfma_f32_16x16x32_f16 v[52:55], v[132:135], v[194:197], v[52:55]
	v_mfma_f32_16x16x32_f16 v[28:31], v[140:143], v[208:211], v[28:31]
	v_mfma_f32_16x16x32_f16 v[36:39], v[132:135], v[208:211], v[36:39]
	v_mfma_f32_16x16x32_f16 v[12:15], v[140:143], v[216:219], v[12:15]
	v_mfma_f32_16x16x32_f16 v[20:23], v[132:135], v[216:219], v[20:23]
	s_setprio 0
	s_setprio 1
	v_mfma_f32_16x16x32_f16 v[40:43], v[152:155], v[176:179], v[40:43]
	v_mfma_f32_16x16x32_f16 v[48:51], v[144:147], v[176:179], v[48:51]
	v_mfma_f32_16x16x32_f16 v[24:27], v[152:155], v[184:187], v[24:27]
	v_mfma_f32_16x16x32_f16 v[32:35], v[144:147], v[184:187], v[32:35]
	v_mfma_f32_16x16x32_f16 v[8:11], v[152:155], v[198:201], v[8:11]
	v_mfma_f32_16x16x32_f16 v[16:19], v[144:147], v[198:201], v[16:19]
	v_mfma_f32_16x16x32_f16 v[0:3], v[152:155], v[212:215], v[0:3]
	v_mfma_f32_16x16x32_f16 v[4:7], v[144:147], v[212:215], v[4:7]
	v_mfma_f32_16x16x32_f16 v[40:43], v[156:159], v[180:183], v[40:43]
	v_mfma_f32_16x16x32_f16 v[48:51], v[148:151], v[180:183], v[48:51]
	v_mfma_f32_16x16x32_f16 v[24:27], v[156:159], v[194:197], v[24:27]
	v_mfma_f32_16x16x32_f16 v[32:35], v[148:151], v[194:197], v[32:35]
	v_mfma_f32_16x16x32_f16 v[8:11], v[156:159], v[208:211], v[8:11]
	v_mfma_f32_16x16x32_f16 v[16:19], v[148:151], v[208:211], v[16:19]
	v_mfma_f32_16x16x32_f16 v[0:3], v[156:159], v[216:219], v[0:3]
	v_mfma_f32_16x16x32_f16 v[4:7], v[148:151], v[216:219], v[4:7]
	s_setprio 0
	s_barrier
	s_add_i32 s90, s90, 2
	s_add_u32 s88, s88, 0x100
	s_addc_u32 s89, s89, 0
	s_add_u32 s44, s44, 0x100
	s_addc_u32 s45, s45, 0
	s_cmp_gt_u32 s90, 29
	s_cbranch_scc0 .LBB0_747
	s_and_b64 vcc, exec, s[20:21]
	s_cbranch_vccz .LBB0_750
	s_barrier

; #define PG8_STAGE(bufoff, gbase, voff) do { _Pragma("unroll") for (int _i = 0; _i < 2; ++_i) \
;         __builtin_amdgcn_global_load_lds((const unsigned*)((const char*)(gbase) + (voff)[_i]), (PG8_LAS unsigned*)(lds + (bufoff) + ldsw + _i * 8192), 16, 0, 0); } while (0)
; #define PG8_LDA(dst, b, h) do { _Pragma("unroll") for (int m = 0; m < 4; ++m) _Pragma("unroll") for (int k = 0; k < 2; ++k) dst[m][k] = *(const PG8_LAS bf16x8*)(lds + PG8_SA(b, h) + aoff + m * 2048 + k * 1024); } while (0)
; #define PG8_LDB(dst, b, h) do { _Pragma("unroll") for (int n = 0; n < 2; ++n) _Pragma("unroll") for (int k = 0; k < 2; ++k) dst[n][k] = *(const PG8_LAS bf16x8*)(lds + PG8_SB(b, h) + boff + n * 2048 + k * 1024); } while (0)
; #define PG8_MMA(ai, bj, At, Bt) do { __builtin_amdgcn_s_setprio(1); _Pragma("unroll") for (int m = 0; m < 4; ++m) _Pragma("unroll") for (int n = 0; n < 2; ++n) _Pragma("unroll") for (int k = 0; k < 2; ++k) \
;         acc[ai][bj][m][n] = __builtin_amdgcn_mfma_f32_16x16x32_f16(Bt[n][k], At[m][k], acc[ai][bj][m][n], 0, 0, 0); __builtin_amdgcn_s_setprio(0); } while (0)
; #define PG8_WAIT_V(n) asm volatile("s_waitcnt vmcnt(" #n ")" ::: "memory")
; #define PG8_WAIT_L(n) asm volatile("s_waitcnt lgkmcnt(" #n ")" ::: "memory")
; #define PG8_BAR __builtin_amdgcn_s_barrier()
; #define PG8_SCHED __builtin_amdgcn_sched_barrier(0)
; template <class Epi, class Sched, bool ALIGN_EPI = false, bool SP2 = false>
; __device__ __forceinline__ void gemm_phase(PG8_LAS unsigned char* lds, const Gemm g, const Sched& S, const Epi& E) {
;     ...
;             const char* a2 = last ? nA : cA + (size_t)(t + 2) * kstep; const char* b2 = last ? nB : cB + (size_t)(t + 2) * kstep;
;             const char* a3 = a2 + kstep; const char* b3 = b2 + kstep;
;             if (last && has_next) S.a_ready(nxt);
;             if constexpr (SP2) {
;             PG8_LDB(B0, 0, 0); PG8_LDB(B1, 0, 1); PG8_SCHED; PG8_LDA(At, 0, 0); PG8_STAGE(PG8_SA(1, 1), a1 + hstep, voffA);
;             PG8_WAIT_V(8); PG8_WAIT_L(0); PG8_BAR; PG8_MMA(0, 0, At, B0); PG8_MMA(0, 1, At, B1); PG8_BAR; PG8_SCHED;
;             PG8_LDA(At, 0, 1); PG8_STAGE(PG8_SB(0, 0), b2, voffB); PG8_STAGE(PG8_SB(0, 1), b2 + hstep, voffB); PG8_STAGE(PG8_SA(0, 0), a2, voffA);
;             PG8_WAIT_V(8); PG8_WAIT_L(0); PG8_BAR; PG8_MMA(1, 0, At, B0); PG8_MMA(1, 1, At, B1); PG8_BAR; PG8_SCHED;
.LBB0_872:
	ds_read_b128 v[128:131], v187
	ds_read_b128 v[132:135], v187 offset:1024
	ds_read_b128 v[136:139], v187 offset:2048
	ds_read_b128 v[140:143], v187 offset:3072
	ds_read_b128 v[144:147], v188
	ds_read_b128 v[148:151], v188 offset:1024
	ds_read_b128 v[152:155], v188 offset:2048
	ds_read_b128 v[156:159], v188 offset:3072
	s_add_u32 s28, s26, 0xfffe0080
	s_addc_u32 s29, s27, -1
	s_cmp_eq_u32 s65, 4
	s_cselect_b32 s31, s21, s29
	s_cselect_b32 s30, s61, s28
	s_cselect_b32 s29, s19, s64
	s_cselect_b32 s28, s62, s63
	s_add_i32 m0, s39, 0xc000
	ds_read_b128 v[160:163], v189
	ds_read_b128 v[164:167], v189 offset:1024
	ds_read_b128 v[192:195], v189 offset:2048
	ds_read_b128 v[196:199], v189 offset:3072
	ds_read_b128 v[200:203], v189 offset:4096
	ds_read_b128 v[208:211], v189 offset:5120
	ds_read_b128 v[212:215], v189 offset:6144
	ds_read_b128 v[216:219], v189 offset:7168
	global_load_lds_dwordx4 v178, s[26:27]
	s_add_i32 m0, s39, 0xe000
	s_nop 0
	global_load_lds_dwordx4 v176, s[26:27]
	s_waitcnt vmcnt(8)
	s_waitcnt lgkmcnt(0)
	s_barrier
	s_setprio 1
	s_waitcnt lgkmcnt(0)
	v_mfma_f32_16x16x32_f16 v[120:123], v[136:139], v[160:163], v[120:123]
	v_mfma_f32_16x16x32_f16 v[124:127], v[128:131], v[160:163], v[124:127]
	v_mfma_f32_16x16x32_f16 v[104:107], v[136:139], v[192:195], v[104:107]
	v_mfma_f32_16x16x32_f16 v[108:111], v[128:131], v[192:195], v[108:111]
	v_mfma_f32_16x16x32_f16 v[88:91], v[136:139], v[200:203], v[88:91]
	v_mfma_f32_16x16x32_f16 v[92:95], v[128:131], v[200:203], v[92:95]
	v_mfma_f32_16x16x32_f16 v[72:75], v[136:139], v[212:215], v[72:75]
	v_mfma_f32_16x16x32_f16 v[76:79], v[128:131], v[212:215], v[76:79]
	v_mfma_f32_16x16x32_f16 v[120:123], v[140:143], v[164:167], v[120:123]
	v_mfma_f32_16x16x32_f16 v[124:127], v[132:135], v[164:167], v[124:127]
	v_mfma_f32_16x16x32_f16 v[104:107], v[140:143], v[196:199], v[104:107]
	v_mfma_f32_16x16x32_f16 v[108:111], v[132:135], v[196:199], v[108:111]
	v_mfma_f32_16x16x32_f16 v[88:91], v[140:143], v[208:211], v[88:91]
	v_mfma_f32_16x16x32_f16 v[92:95], v[132:135], v[208:211], v[92:95]
	v_mfma_f32_16x16x32_f16 v[72:75], v[140:143], v[216:219], v[72:75]
	v_mfma_f32_16x16x32_f16 v[76:79], v[132:135], v[216:219], v[76:79]
	s_setprio 0
	s_setprio 1
	v_mfma_f32_16x16x32_f16 v[112:115], v[152:155], v[160:163], v[112:115]
	v_mfma_f32_16x16x32_f16 v[116:119], v[144:147], v[160:163], v[116:119]
	v_mfma_f32_16x16x32_f16 v[96:99], v[152:155], v[192:195], v[96:99]
	v_mfma_f32_16x16x32_f16 v[100:103], v[144:147], v[192:195], v[100:103]
	v_mfma_f32_16x16x32_f16 v[80:83], v[152:155], v[200:203], v[80:83]
	v_mfma_f32_16x16x32_f16 v[84:87], v[144:147], v[200:203], v[84:87]
	v_mfma_f32_16x16x32_f16 v[64:67], v[152:155], v[212:215], v[64:67]
	v_mfma_f32_16x16x32_f16 v[68:71], v[144:147], v[212:215], v[68:71]
	v_mfma_f32_16x16x32_f16 v[112:115], v[156:159], v[164:167], v[112:115]
	v_mfma_f32_16x16x32_f16 v[116:119], v[148:151], v[164:167], v[116:119]
	v_mfma_f32_16x16x32_f16 v[96:99], v[156:159], v[196:199], v[96:99]
	v_mfma_f32_16x16x32_f16 v[100:103], v[148:151], v[196:199], v[100:103]
	v_mfma_f32_16x16x32_f16 v[80:83], v[156:159], v[208:211], v[80:83]
	v_mfma_f32_16x16x32_f16 v[84:87], v[148:151], v[208:211], v[84:87]
	v_mfma_f32_16x16x32_f16 v[64:67], v[156:159], v[216:219], v[64:67]
	v_mfma_f32_16x16x32_f16 v[68:71], v[148:151], v[216:219], v[68:71]
	s_setprio 0
	s_barrier
	s_add_i32 s66, s49, s37
	s_add_u32 s98, s28, s14
	s_addc_u32 s99, s29, s15
	s_mov_b32 m0, s66
	ds_read_b128 v[160:163], v189 offset:16384
	ds_read_b128 v[164:167], v189 offset:17408
	ds_read_b128 v[192:195], v189 offset:18432
	ds_read_b128 v[196:199], v189 offset:19456
	ds_read_b128 v[200:203], v189 offset:20480
	ds_read_b128 v[208:211], v189 offset:21504
	ds_read_b128 v[212:215], v189 offset:22528
	ds_read_b128 v[216:219], v189 offset:23552
	global_load_lds_dwordx4 v170, s[28:29]
	s_add_i32 m0, s66, 0x2000
	s_add_u32 s66, s28, 0x20000
	s_addc_u32 s67, s29, 0
	s_add_i32 s68, s50, s37
	global_load_lds_dwordx4 v168, s[28:29]
	s_mov_b32 m0, s68
	s_nop 0
	global_load_lds_dwordx4 v170, s[66:67]
	s_add_i32 m0, s68, 0x2000
	s_nop 0
	global_load_lds_dwordx4 v168, s[66:67]
	s_add_u32 s100, s30, s14
	s_addc_u32 s101, s31, s15
	s_mov_b32 m0, s39
	s_nop 0
	global_load_lds_dwordx4 v170, s[30:31]
	s_mov_b32 m0, s40
	s_nop 0
	global_load_lds_dwordx4 v168, s[30:31]
	s_waitcnt vmcnt(8)
	s_waitcnt lgkmcnt(0)
	s_barrier
	s_setprio 1
	s_waitcnt lgkmcnt(0)
	v_mfma_f32_16x16x32_f16 v[56:59], v[136:139], v[160:163], v[56:59]
	v_mfma_f32_16x16x32_f16 v[60:63], v[128:131], v[160:163], v[60:63]
	v_mfma_f32_16x16x32_f16 v[40:43], v[136:139], v[192:195], v[40:43]
	v_mfma_f32_16x16x32_f16 v[44:47], v[128:131], v[192:195], v[44:47]
	v_mfma_f32_16x16x32_f16 v[24:27], v[136:139], v[200:203], v[24:27]
	v_mfma_f32_16x16x32_f16 v[28:31], v[128:131], v[200:203], v[28:31]
	v_mfma_f32_16x16x32_f16 v[8:11], v[136:139], v[212:215], v[8:11]
	v_mfma_f32_16x16x32_f16 v[12:15], v[128:131], v[212:215], v[12:15]
	v_mfma_f32_16x16x32_f16 v[56:59], v[140:143], v[164:167], v[56:59]
	v_mfma_f32_16x16x32_f16 v[60:63], v[132:135], v[164:167], v[60:63]
	v_mfma_f32_16x16x32_f16 v[40:43], v[140:143], v[196:199], v[40:43]
	v_mfma_f32_16x16x32_f16 v[44:47], v[132:135], v[196:199], v[44:47]
	v_mfma_f32_16x16x32_f16 v[24:27], v[140:143], v[208:211], v[24:27]
	v_mfma_f32_16x16x32_f16 v[28:31], v[132:135], v[208:211], v[28:31]
	v_mfma_f32_16x16x32_f16 v[8:11], v[140:143], v[216:219], v[8:11]
	v_mfma_f32_16x16x32_f16 v[12:15], v[132:135], v[216:219], v[12:15]
	s_setprio 0
	s_setprio 1
	v_mfma_f32_16x16x32_f16 v[48:51], v[152:155], v[160:163], v[48:51]
	v_mfma_f32_16x16x32_f16 v[52:55], v[144:147], v[160:163], v[52:55]
	v_mfma_f32_16x16x32_f16 v[32:35], v[152:155], v[192:195], v[32:35]
	v_mfma_f32_16x16x32_f16 v[36:39], v[144:147], v[192:195], v[36:39]
	v_mfma_f32_16x16x32_f16 v[16:19], v[152:155], v[200:203], v[16:19]
	v_mfma_f32_16x16x32_f16 v[20:23], v[144:147], v[200:203], v[20:23]
	v_mfma_f32_16x16x32_f16 v[0:3], v[152:155], v[212:215], v[0:3]
	v_mfma_f32_16x16x32_f16 v[4:7], v[144:147], v[212:215], v[4:7]
	v_mfma_f32_16x16x32_f16 v[48:51], v[156:159], v[164:167], v[48:51]
	v_mfma_f32_16x16x32_f16 v[52:55], v[148:151], v[164:167], v[52:55]
	v_mfma_f32_16x16x32_f16 v[32:35], v[156:159], v[196:199], v[32:35]
	v_mfma_f32_16x16x32_f16 v[36:39], v[148:151], v[196:199], v[36:39]
	v_mfma_f32_16x16x32_f16 v[16:19], v[156:159], v[208:211], v[16:19]
	v_mfma_f32_16x16x32_f16 v[20:23], v[148:151], v[208:211], v[20:23]
	v_mfma_f32_16x16x32_f16 v[0:3], v[156:159], v[216:219], v[0:3]
	v_mfma_f32_16x16x32_f16 v[4:7], v[148:151], v[216:219], v[4:7]
	s_setprio 0
	s_barrier
; #define PG8_STAGE(bufoff, gbase, voff) do { _Pragma("unroll") for (int _i = 0; _i < 2; ++_i) \
;         __builtin_amdgcn_global_load_lds((const unsigned*)((const char*)(gbase) + (voff)[_i]), (PG8_LAS unsigned*)(lds + (bufoff) + ldsw + _i * 8192), 16, 0, 0); } while (0)
; #define PG8_LDA(dst, b, h) do { _Pragma("unroll") for (int m = 0; m < 4; ++m) _Pragma("unroll") for (int k = 0; k < 2; ++k) dst[m][k] = *(const PG8_LAS bf16x8*)(lds + PG8_SA(b, h) + aoff + m * 2048 + k * 1024); } while (0)
; #define PG8_LDB(dst, b, h) do { _Pragma("unroll") for (int n = 0; n < 2; ++n) _Pragma("unroll") for (int k = 0; k < 2; ++k) dst[n][k] = *(const PG8_LAS bf16x8*)(lds + PG8_SB(b, h) + boff + n * 2048 + k * 1024); } while (0)
; #define PG8_MMA(ai, bj, At, Bt) do { __builtin_amdgcn_s_setprio(1); _Pragma("unroll") for (int m = 0; m < 4; ++m) _Pragma("unroll") for (int n = 0; n < 2; ++n) _Pragma("unroll") for (int k = 0; k < 2; ++k) \
;         acc[ai][bj][m][n] = __builtin_amdgcn_mfma_f32_16x16x32_f16(Bt[n][k], At[m][k], acc[ai][bj][m][n], 0, 0, 0); __builtin_amdgcn_s_setprio(0); } while (0)
; #define PG8_WAIT_V(n) asm volatile("s_waitcnt vmcnt(" #n ")" ::: "memory")
; #define PG8_WAIT_L(n) asm volatile("s_waitcnt lgkmcnt(" #n ")" ::: "memory")
; #define PG8_BAR __builtin_amdgcn_s_barrier()
; #define PG8_SCHED __builtin_amdgcn_sched_barrier(0)
; template <class Epi, class Sched, bool ALIGN_EPI = false, bool SP2 = false>
; __device__ __forceinline__ void gemm_phase(PG8_LAS unsigned char* lds, const Gemm g, const Sched& S, const Epi& E) {
;     ...
;             PG8_LDB(B0, 1, 0); PG8_LDB(B1, 1, 1); PG8_SCHED; PG8_LDA(At, 1, 0); PG8_STAGE(PG8_SA(0, 1), a2 + hstep, voffA);
;             PG8_WAIT_V(8); PG8_WAIT_L(0); PG8_BAR; PG8_MMA(0, 0, At, B0); PG8_MMA(0, 1, At, B1); PG8_BAR; PG8_SCHED;
;             PG8_LDA(At, 1, 1); PG8_STAGE(PG8_SB(1, 0), b3, voffB); PG8_STAGE(PG8_SB(1, 1), b3 + hstep, voffB); PG8_STAGE(PG8_SA(1, 0), a3, voffA);
;             PG8_WAIT_V(8); PG8_WAIT_L(0); PG8_BAR; PG8_MMA(1, 0, At, B0); PG8_MMA(1, 1, At, B1); PG8_BAR; PG8_SCHED;
	s_add_i32 s66, 0, 0x18000
	s_add_i32 s67, 0, 0x1c000
	v_add_u32_e32 v140, s66, v186
	v_add_u32_e32 v156, s67, v186
	ds_read_b128 v[128:131], v140
	ds_read_b128 v[132:135], v140 offset:1024
	ds_read_b128 v[136:139], v140 offset:2048
	ds_read_b128 v[140:143], v140 offset:3072
	ds_read_b128 v[144:147], v156
	ds_read_b128 v[148:151], v156 offset:1024
	ds_read_b128 v[152:155], v156 offset:2048
	ds_read_b128 v[156:159], v156 offset:3072
	s_add_u32 s30, s30, 0x20000
	s_addc_u32 s31, s31, 0
	s_mov_b32 m0, s41
	ds_read_b128 v[160:163], v189 offset:32768
	ds_read_b128 v[164:167], v189 offset:33792
	ds_read_b128 v[192:195], v189 offset:34816
	ds_read_b128 v[196:199], v189 offset:35840
	ds_read_b128 v[200:203], v189 offset:36864
	ds_read_b128 v[208:211], v189 offset:37888
	ds_read_b128 v[212:215], v189 offset:38912
	ds_read_b128 v[216:219], v189 offset:39936
	global_load_lds_dwordx4 v170, s[30:31]
	s_mov_b32 m0, s42
	s_nop 0
	global_load_lds_dwordx4 v168, s[30:31]
	s_waitcnt vmcnt(8)
	s_waitcnt lgkmcnt(0)
	s_barrier
	s_setprio 1
	s_waitcnt lgkmcnt(0)
	v_mfma_f32_16x16x32_f16 v[120:123], v[136:139], v[160:163], v[120:123]
	v_mfma_f32_16x16x32_f16 v[124:127], v[128:131], v[160:163], v[124:127]
	v_mfma_f32_16x16x32_f16 v[104:107], v[136:139], v[192:195], v[104:107]
	v_mfma_f32_16x16x32_f16 v[108:111], v[128:131], v[192:195], v[108:111]
	v_mfma_f32_16x16x32_f16 v[88:91], v[136:139], v[200:203], v[88:91]
	v_mfma_f32_16x16x32_f16 v[92:95], v[128:131], v[200:203], v[92:95]
	v_mfma_f32_16x16x32_f16 v[72:75], v[136:139], v[212:215], v[72:75]
	v_mfma_f32_16x16x32_f16 v[76:79], v[128:131], v[212:215], v[76:79]
	v_mfma_f32_16x16x32_f16 v[120:123], v[140:143], v[164:167], v[120:123]
	v_mfma_f32_16x16x32_f16 v[124:127], v[132:135], v[164:167], v[124:127]
	v_mfma_f32_16x16x32_f16 v[104:107], v[140:143], v[196:199], v[104:107]
	v_mfma_f32_16x16x32_f16 v[108:111], v[132:135], v[196:199], v[108:111]
	v_mfma_f32_16x16x32_f16 v[88:91], v[140:143], v[208:211], v[88:91]
	v_mfma_f32_16x16x32_f16 v[92:95], v[132:135], v[208:211], v[92:95]
	v_mfma_f32_16x16x32_f16 v[72:75], v[140:143], v[216:219], v[72:75]
	v_mfma_f32_16x16x32_f16 v[76:79], v[132:135], v[216:219], v[76:79]
	s_setprio 0
	s_setprio 1
	v_mfma_f32_16x16x32_f16 v[112:115], v[152:155], v[160:163], v[112:115]
	v_mfma_f32_16x16x32_f16 v[116:119], v[144:147], v[160:163], v[116:119]
	v_mfma_f32_16x16x32_f16 v[96:99], v[152:155], v[192:195], v[96:99]
	v_mfma_f32_16x16x32_f16 v[100:103], v[144:147], v[192:195], v[100:103]
	v_mfma_f32_16x16x32_f16 v[80:83], v[152:155], v[200:203], v[80:83]
	v_mfma_f32_16x16x32_f16 v[84:87], v[144:147], v[200:203], v[84:87]
	v_mfma_f32_16x16x32_f16 v[64:67], v[152:155], v[212:215], v[64:67]
	v_mfma_f32_16x16x32_f16 v[68:71], v[144:147], v[212:215], v[68:71]
	v_mfma_f32_16x16x32_f16 v[112:115], v[156:159], v[164:167], v[112:115]
	v_mfma_f32_16x16x32_f16 v[116:119], v[148:151], v[164:167], v[116:119]
	v_mfma_f32_16x16x32_f16 v[96:99], v[156:159], v[196:199], v[96:99]
	v_mfma_f32_16x16x32_f16 v[100:103], v[148:151], v[196:199], v[100:103]
	v_mfma_f32_16x16x32_f16 v[80:83], v[156:159], v[208:211], v[80:83]
	v_mfma_f32_16x16x32_f16 v[84:87], v[148:151], v[208:211], v[84:87]
	v_mfma_f32_16x16x32_f16 v[64:67], v[156:159], v[216:219], v[64:67]
	v_mfma_f32_16x16x32_f16 v[68:71], v[148:151], v[216:219], v[68:71]
	s_setprio 0
	s_barrier
	s_add_i32 s30, s66, s37
	s_mov_b32 m0, s30
	ds_read_b128 v[160:163], v189 offset:49152
	ds_read_b128 v[164:167], v189 offset:50176
	ds_read_b128 v[192:195], v189 offset:51200
	ds_read_b128 v[196:199], v189 offset:52224
	ds_read_b128 v[200:203], v189 offset:53248
	ds_read_b128 v[208:211], v189 offset:54272
	ds_read_b128 v[212:215], v189 offset:55296
	ds_read_b128 v[216:219], v189 offset:56320
	global_load_lds_dwordx4 v170, s[98:99]
	s_add_i32 m0, s30, 0x2000
	s_add_u32 s28, s28, 0x20080
	s_addc_u32 s29, s29, 0
	s_add_i32 s30, s67, s37
	global_load_lds_dwordx4 v168, s[98:99]
	s_mov_b32 m0, s30
	s_nop 0
	global_load_lds_dwordx4 v170, s[28:29]
	s_add_i32 m0, s30, 0x2000
	s_nop 0
	global_load_lds_dwordx4 v168, s[28:29]
	s_mov_b32 m0, s45
	s_nop 0
	global_load_lds_dwordx4 v170, s[100:101]
	s_mov_b32 m0, s48
	s_nop 0
	global_load_lds_dwordx4 v168, s[100:101]
	s_waitcnt vmcnt(8)
	s_waitcnt lgkmcnt(0)
	s_barrier
	s_setprio 1
	s_waitcnt lgkmcnt(0)
	v_mfma_f32_16x16x32_f16 v[56:59], v[136:139], v[160:163], v[56:59]
	v_mfma_f32_16x16x32_f16 v[60:63], v[128:131], v[160:163], v[60:63]
	v_mfma_f32_16x16x32_f16 v[40:43], v[136:139], v[192:195], v[40:43]
	v_mfma_f32_16x16x32_f16 v[44:47], v[128:131], v[192:195], v[44:47]
	v_mfma_f32_16x16x32_f16 v[24:27], v[136:139], v[200:203], v[24:27]
	v_mfma_f32_16x16x32_f16 v[28:31], v[128:131], v[200:203], v[28:31]
	v_mfma_f32_16x16x32_f16 v[8:11], v[136:139], v[212:215], v[8:11]
	v_mfma_f32_16x16x32_f16 v[12:15], v[128:131], v[212:215], v[12:15]
	v_mfma_f32_16x16x32_f16 v[56:59], v[140:143], v[164:167], v[56:59]
	v_mfma_f32_16x16x32_f16 v[60:63], v[132:135], v[164:167], v[60:63]
	v_mfma_f32_16x16x32_f16 v[40:43], v[140:143], v[196:199], v[40:43]
	v_mfma_f32_16x16x32_f16 v[44:47], v[132:135], v[196:199], v[44:47]
	v_mfma_f32_16x16x32_f16 v[24:27], v[140:143], v[208:211], v[24:27]
	v_mfma_f32_16x16x32_f16 v[28:31], v[132:135], v[208:211], v[28:31]
	v_mfma_f32_16x16x32_f16 v[8:11], v[140:143], v[216:219], v[8:11]
	v_mfma_f32_16x16x32_f16 v[12:15], v[132:135], v[216:219], v[12:15]
	s_setprio 0
	s_setprio 1
	v_mfma_f32_16x16x32_f16 v[48:51], v[152:155], v[160:163], v[48:51]
	v_mfma_f32_16x16x32_f16 v[52:55], v[144:147], v[160:163], v[52:55]
	v_mfma_f32_16x16x32_f16 v[32:35], v[152:155], v[192:195], v[32:35]
	v_mfma_f32_16x16x32_f16 v[36:39], v[144:147], v[192:195], v[36:39]
	v_mfma_f32_16x16x32_f16 v[16:19], v[152:155], v[200:203], v[16:19]
	v_mfma_f32_16x16x32_f16 v[20:23], v[144:147], v[200:203], v[20:23]
	v_mfma_f32_16x16x32_f16 v[0:3], v[152:155], v[212:215], v[0:3]
	v_mfma_f32_16x16x32_f16 v[4:7], v[144:147], v[212:215], v[4:7]
	v_mfma_f32_16x16x32_f16 v[48:51], v[156:159], v[164:167], v[48:51]
	v_mfma_f32_16x16x32_f16 v[52:55], v[148:151], v[164:167], v[52:55]
	v_mfma_f32_16x16x32_f16 v[32:35], v[156:159], v[196:199], v[32:35]
	v_mfma_f32_16x16x32_f16 v[36:39], v[148:151], v[196:199], v[36:39]
	v_mfma_f32_16x16x32_f16 v[16:19], v[156:159], v[208:211], v[16:19]
	v_mfma_f32_16x16x32_f16 v[20:23], v[148:151], v[208:211], v[20:23]
	v_mfma_f32_16x16x32_f16 v[0:3], v[156:159], v[216:219], v[0:3]
	v_mfma_f32_16x16x32_f16 v[4:7], v[148:151], v[216:219], v[4:7]
	s_setprio 0
	s_barrier
	s_add_i32 s65, s65, 2
	s_add_u32 s63, s63, 0x100
	s_addc_u32 s64, s64, 0
	s_add_u32 s26, s26, 0x100
	s_addc_u32 s27, s27, 0
	s_cmp_gt_u32 s65, 5
	s_cbranch_scc0 .LBB0_872
	s_and_b64 vcc, exec, s[16:17]
	s_cbranch_vccz .LBB0_875
	s_barrier

; #define PG8_STAGE(bufoff, gbase, voff) do { _Pragma("unroll") for (int _i = 0; _i < 2; ++_i) \
;         __builtin_amdgcn_global_load_lds((const unsigned*)((const char*)(gbase) + (voff)[_i]), (PG8_LAS unsigned*)(lds + (bufoff) + ldsw + _i * 8192), 16, 0, 0); } while (0)
; #define PG8_LDA(dst, b, h) do { _Pragma("unroll") for (int m = 0; m < 4; ++m) _Pragma("unroll") for (int k = 0; k < 2; ++k) dst[m][k] = *(const PG8_LAS bf16x8*)(lds + PG8_SA(b, h) + aoff + m * 2048 + k * 1024); } while (0)
; #define PG8_LDB(dst, b, h) do { _Pragma("unroll") for (int n = 0; n < 2; ++n) _Pragma("unroll") for (int k = 0; k < 2; ++k) dst[n][k] = *(const PG8_LAS bf16x8*)(lds + PG8_SB(b, h) + boff + n * 2048 + k * 1024); } while (0)
; #define PG8_MMA(ai, bj, At, Bt) do { __builtin_amdgcn_s_setprio(1); _Pragma("unroll") for (int m = 0; m < 4; ++m) _Pragma("unroll") for (int n = 0; n < 2; ++n) _Pragma("unroll") for (int k = 0; k < 2; ++k) \
;         acc[ai][bj][m][n] = __builtin_amdgcn_mfma_f32_16x16x32_f16(Bt[n][k], At[m][k], acc[ai][bj][m][n], 0, 0, 0); __builtin_amdgcn_s_setprio(0); } while (0)
; #define PG8_WAIT_V(n) asm volatile("s_waitcnt vmcnt(" #n ")" ::: "memory")
; #define PG8_WAIT_L(n) asm volatile("s_waitcnt lgkmcnt(" #n ")" ::: "memory")
; #define PG8_BAR __builtin_amdgcn_s_barrier()
; #define PG8_SCHED __builtin_amdgcn_sched_barrier(0)
; template <class Epi, class Sched, bool ALIGN_EPI = false, bool SP2 = false>
; __device__ __forceinline__ void gemm_phase(PG8_LAS unsigned char* lds, const Gemm g, const Sched& S, const Epi& E) {
;     ...
;             PG8_LDB(B0, 0, 0); PG8_LDB(B1, 0, 1); PG8_SCHED; PG8_LDA(At, 0, 0); PG8_STAGE(PG8_SA(1, 1), a1 + hstep, voffA);
;             PG8_WAIT_V(8); PG8_WAIT_L(0); PG8_BAR; PG8_MMA(0, 0, At, B0); PG8_MMA(0, 1, At, B1); PG8_BAR; PG8_SCHED;
;             PG8_LDA(At, 0, 1); PG8_STAGE(PG8_SB(0, 0), b2, voffB); PG8_STAGE(PG8_SB(0, 1), b2 + hstep, voffB); PG8_STAGE(PG8_SA(0, 0), a2, voffA);
;             PG8_WAIT_V(8); PG8_WAIT_L(0); PG8_BAR; PG8_MMA(1, 0, At, B0); PG8_MMA(1, 1, At, B1); PG8_BAR; PG8_SCHED;
.LBB0_1075:
	ds_read_b128 v[128:131], v211
	ds_read_b128 v[132:135], v211 offset:1024
	ds_read_b128 v[136:139], v211 offset:2048
	ds_read_b128 v[140:143], v211 offset:3072
	ds_read_b128 v[144:147], v212
	ds_read_b128 v[148:151], v212 offset:1024
	ds_read_b128 v[152:155], v212 offset:2048
	ds_read_b128 v[156:159], v212 offset:3072
	s_add_u32 s42, s40, 0xfff80080
	s_addc_u32 s43, s41, -1
	s_cmp_eq_u32 s70, 28
	s_cselect_b32 s45, s29, s43
	s_cselect_b32 s44, s37, s42
	s_cselect_b32 s43, s27, s69
	s_cselect_b32 s42, s67, s68
	s_add_i32 m0, s39, 0xc000
	ds_read_b128 v[160:163], v213
	ds_read_b128 v[164:167], v213 offset:1024
	ds_read_b128 v[184:187], v213 offset:2048
	ds_read_b128 v[188:191], v213 offset:3072
	ds_read_b128 v[192:195], v213 offset:4096
	ds_read_b128 v[196:199], v213 offset:5120
	ds_read_b128 v[200:203], v213 offset:6144
	ds_read_b128 v[214:217], v213 offset:7168
	global_load_lds_dwordx4 v178, s[40:41]
	s_add_i32 m0, s39, 0xe000
	s_nop 0
	global_load_lds_dwordx4 v176, s[40:41]
	s_waitcnt vmcnt(8)
	s_waitcnt lgkmcnt(0)
	s_barrier
	s_setprio 1
	s_waitcnt lgkmcnt(0)
	v_mfma_f32_16x16x32_f16 v[120:123], v[136:139], v[160:163], v[120:123]
	v_mfma_f32_16x16x32_f16 v[124:127], v[128:131], v[160:163], v[124:127]
	v_mfma_f32_16x16x32_f16 v[104:107], v[136:139], v[184:187], v[104:107]
	v_mfma_f32_16x16x32_f16 v[108:111], v[128:131], v[184:187], v[108:111]
	v_mfma_f32_16x16x32_f16 v[88:91], v[136:139], v[192:195], v[88:91]
	v_mfma_f32_16x16x32_f16 v[92:95], v[128:131], v[192:195], v[92:95]
	v_mfma_f32_16x16x32_f16 v[72:75], v[136:139], v[200:203], v[72:75]
	v_mfma_f32_16x16x32_f16 v[76:79], v[128:131], v[200:203], v[76:79]
	v_mfma_f32_16x16x32_f16 v[120:123], v[140:143], v[164:167], v[120:123]
	v_mfma_f32_16x16x32_f16 v[124:127], v[132:135], v[164:167], v[124:127]
	v_mfma_f32_16x16x32_f16 v[104:107], v[140:143], v[188:191], v[104:107]
	v_mfma_f32_16x16x32_f16 v[108:111], v[132:135], v[188:191], v[108:111]
	v_mfma_f32_16x16x32_f16 v[88:91], v[140:143], v[196:199], v[88:91]
	v_mfma_f32_16x16x32_f16 v[92:95], v[132:135], v[196:199], v[92:95]
	v_mfma_f32_16x16x32_f16 v[72:75], v[140:143], v[214:217], v[72:75]
	v_mfma_f32_16x16x32_f16 v[76:79], v[132:135], v[214:217], v[76:79]
	s_setprio 0
	s_setprio 1
	v_mfma_f32_16x16x32_f16 v[112:115], v[152:155], v[160:163], v[112:115]
	v_mfma_f32_16x16x32_f16 v[116:119], v[144:147], v[160:163], v[116:119]
	v_mfma_f32_16x16x32_f16 v[96:99], v[152:155], v[184:187], v[96:99]
	v_mfma_f32_16x16x32_f16 v[100:103], v[144:147], v[184:187], v[100:103]
	v_mfma_f32_16x16x32_f16 v[80:83], v[152:155], v[192:195], v[80:83]
	v_mfma_f32_16x16x32_f16 v[84:87], v[144:147], v[192:195], v[84:87]
	v_mfma_f32_16x16x32_f16 v[64:67], v[152:155], v[200:203], v[64:67]
	v_mfma_f32_16x16x32_f16 v[68:71], v[144:147], v[200:203], v[68:71]
	v_mfma_f32_16x16x32_f16 v[112:115], v[156:159], v[164:167], v[112:115]
	v_mfma_f32_16x16x32_f16 v[116:119], v[148:151], v[164:167], v[116:119]
	v_mfma_f32_16x16x32_f16 v[96:99], v[156:159], v[188:191], v[96:99]
	v_mfma_f32_16x16x32_f16 v[100:103], v[148:151], v[188:191], v[100:103]
	v_mfma_f32_16x16x32_f16 v[80:83], v[156:159], v[196:199], v[80:83]
	v_mfma_f32_16x16x32_f16 v[84:87], v[148:151], v[196:199], v[84:87]
	v_mfma_f32_16x16x32_f16 v[64:67], v[156:159], v[214:217], v[64:67]
	v_mfma_f32_16x16x32_f16 v[68:71], v[148:151], v[214:217], v[68:71]
	s_setprio 0
	s_barrier
	s_add_i32 s71, s64, s48
	s_add_u32 s98, s42, s18
	s_addc_u32 s99, s43, s19
	s_mov_b32 m0, s71
	ds_read_b128 v[160:163], v213 offset:16384
	ds_read_b128 v[164:167], v213 offset:17408
	ds_read_b128 v[184:187], v213 offset:18432
	ds_read_b128 v[188:191], v213 offset:19456
	ds_read_b128 v[192:195], v213 offset:20480
	ds_read_b128 v[196:199], v213 offset:21504
	ds_read_b128 v[200:203], v213 offset:22528
	ds_read_b128 v[214:217], v213 offset:23552
	global_load_lds_dwordx4 v170, s[42:43]
	s_add_i32 m0, s71, 0x2000
	s_add_u32 s72, s42, 0x80000
	s_addc_u32 s73, s43, 0
	s_add_i32 s71, s65, s48
	global_load_lds_dwordx4 v174, s[42:43]
	s_mov_b32 m0, s71
	s_nop 0
	global_load_lds_dwordx4 v170, s[72:73]
	s_add_i32 m0, s71, 0x2000
	s_nop 0
	global_load_lds_dwordx4 v174, s[72:73]
	s_add_u32 s100, s44, s18
	s_addc_u32 s101, s45, s19
	s_mov_b32 m0, s39
	s_nop 0
	global_load_lds_dwordx4 v168, s[44:45]
	s_mov_b32 m0, s49
	s_nop 0
	global_load_lds_dwordx4 v172, s[44:45]
	s_waitcnt vmcnt(8)
	s_waitcnt lgkmcnt(0)
	s_barrier
	s_setprio 1
	s_waitcnt lgkmcnt(0)
	v_mfma_f32_16x16x32_f16 v[56:59], v[136:139], v[160:163], v[56:59]
	v_mfma_f32_16x16x32_f16 v[60:63], v[128:131], v[160:163], v[60:63]
	v_mfma_f32_16x16x32_f16 v[40:43], v[136:139], v[184:187], v[40:43]
	v_mfma_f32_16x16x32_f16 v[44:47], v[128:131], v[184:187], v[44:47]
	v_mfma_f32_16x16x32_f16 v[24:27], v[136:139], v[192:195], v[24:27]
	v_mfma_f32_16x16x32_f16 v[28:31], v[128:131], v[192:195], v[28:31]
	v_mfma_f32_16x16x32_f16 v[8:11], v[136:139], v[200:203], v[8:11]
	v_mfma_f32_16x16x32_f16 v[12:15], v[128:131], v[200:203], v[12:15]
	v_mfma_f32_16x16x32_f16 v[56:59], v[140:143], v[164:167], v[56:59]
	v_mfma_f32_16x16x32_f16 v[60:63], v[132:135], v[164:167], v[60:63]
	v_mfma_f32_16x16x32_f16 v[40:43], v[140:143], v[188:191], v[40:43]
	v_mfma_f32_16x16x32_f16 v[44:47], v[132:135], v[188:191], v[44:47]
	v_mfma_f32_16x16x32_f16 v[24:27], v[140:143], v[196:199], v[24:27]
	v_mfma_f32_16x16x32_f16 v[28:31], v[132:135], v[196:199], v[28:31]
	v_mfma_f32_16x16x32_f16 v[8:11], v[140:143], v[214:217], v[8:11]
	v_mfma_f32_16x16x32_f16 v[12:15], v[132:135], v[214:217], v[12:15]
	s_setprio 0
	s_setprio 1
	v_mfma_f32_16x16x32_f16 v[48:51], v[152:155], v[160:163], v[48:51]
	v_mfma_f32_16x16x32_f16 v[52:55], v[144:147], v[160:163], v[52:55]
	v_mfma_f32_16x16x32_f16 v[32:35], v[152:155], v[184:187], v[32:35]
	v_mfma_f32_16x16x32_f16 v[36:39], v[144:147], v[184:187], v[36:39]
	v_mfma_f32_16x16x32_f16 v[16:19], v[152:155], v[192:195], v[16:19]
	v_mfma_f32_16x16x32_f16 v[20:23], v[144:147], v[192:195], v[20:23]
	v_mfma_f32_16x16x32_f16 v[0:3], v[152:155], v[200:203], v[0:3]
	v_mfma_f32_16x16x32_f16 v[4:7], v[144:147], v[200:203], v[4:7]
	v_mfma_f32_16x16x32_f16 v[48:51], v[156:159], v[164:167], v[48:51]
	v_mfma_f32_16x16x32_f16 v[52:55], v[148:151], v[164:167], v[52:55]
	v_mfma_f32_16x16x32_f16 v[32:35], v[156:159], v[188:191], v[32:35]
	v_mfma_f32_16x16x32_f16 v[36:39], v[148:151], v[188:191], v[36:39]
	v_mfma_f32_16x16x32_f16 v[16:19], v[156:159], v[196:199], v[16:19]
	v_mfma_f32_16x16x32_f16 v[20:23], v[148:151], v[196:199], v[20:23]
	v_mfma_f32_16x16x32_f16 v[0:3], v[156:159], v[214:217], v[0:3]
	v_mfma_f32_16x16x32_f16 v[4:7], v[148:151], v[214:217], v[4:7]
	s_setprio 0
	s_barrier
; #define PG8_STAGE(bufoff, gbase, voff) do { _Pragma("unroll") for (int _i = 0; _i < 2; ++_i) \
;         __builtin_amdgcn_global_load_lds((const unsigned*)((const char*)(gbase) + (voff)[_i]), (PG8_LAS unsigned*)(lds + (bufoff) + ldsw + _i * 8192), 16, 0, 0); } while (0)
; #define PG8_LDA(dst, b, h) do { _Pragma("unroll") for (int m = 0; m < 4; ++m) _Pragma("unroll") for (int k = 0; k < 2; ++k) dst[m][k] = *(const PG8_LAS bf16x8*)(lds + PG8_SA(b, h) + aoff + m * 2048 + k * 1024); } while (0)
; #define PG8_LDB(dst, b, h) do { _Pragma("unroll") for (int n = 0; n < 2; ++n) _Pragma("unroll") for (int k = 0; k < 2; ++k) dst[n][k] = *(const PG8_LAS bf16x8*)(lds + PG8_SB(b, h) + boff + n * 2048 + k * 1024); } while (0)
; #define PG8_MMA(ai, bj, At, Bt) do { __builtin_amdgcn_s_setprio(1); _Pragma("unroll") for (int m = 0; m < 4; ++m) _Pragma("unroll") for (int n = 0; n < 2; ++n) _Pragma("unroll") for (int k = 0; k < 2; ++k) \
;         acc[ai][bj][m][n] = __builtin_amdgcn_mfma_f32_16x16x32_f16(Bt[n][k], At[m][k], acc[ai][bj][m][n], 0, 0, 0); __builtin_amdgcn_s_setprio(0); } while (0)
; #define PG8_WAIT_V(n) asm volatile("s_waitcnt vmcnt(" #n ")" ::: "memory")
; #define PG8_WAIT_L(n) asm volatile("s_waitcnt lgkmcnt(" #n ")" ::: "memory")
; #define PG8_BAR __builtin_amdgcn_s_barrier()
; #define PG8_SCHED __builtin_amdgcn_sched_barrier(0)
; template <class Epi, class Sched, bool ALIGN_EPI = false, bool SP2 = false>
; __device__ __forceinline__ void gemm_phase(PG8_LAS unsigned char* lds, const Gemm g, const Sched& S, const Epi& E) {
;     ...
;         for (int t = 0; t < nt; t += 2) {
;     ...
;             PG8_LDB(B0, 1, 0); PG8_LDB(B1, 1, 1); PG8_SCHED; PG8_LDA(At, 1, 0); PG8_STAGE(PG8_SA(0, 1), a2 + hstep, voffA);
;             PG8_WAIT_V(8); PG8_WAIT_L(0); PG8_BAR; PG8_MMA(0, 0, At, B0); PG8_MMA(0, 1, At, B1); PG8_BAR; PG8_SCHED;
;             PG8_LDA(At, 1, 1); PG8_STAGE(PG8_SB(1, 0), b3, voffB); PG8_STAGE(PG8_SB(1, 1), b3 + hstep, voffB); PG8_STAGE(PG8_SA(1, 0), a3, voffA);
;             PG8_WAIT_V(8); PG8_WAIT_L(0); PG8_BAR; PG8_MMA(1, 0, At, B0); PG8_MMA(1, 1, At, B1); PG8_BAR; PG8_SCHED;
	s_add_i32 s71, 0, 0x18000
	s_add_i32 s72, 0, 0x1c000
	v_add_u32_e32 v140, s71, v209
	v_add_u32_e32 v156, s72, v209
	ds_read_b128 v[128:131], v140
	ds_read_b128 v[132:135], v140 offset:1024
	ds_read_b128 v[136:139], v140 offset:2048
	ds_read_b128 v[140:143], v140 offset:3072
	ds_read_b128 v[144:147], v156
	ds_read_b128 v[148:151], v156 offset:1024
	ds_read_b128 v[152:155], v156 offset:2048
	ds_read_b128 v[156:159], v156 offset:3072
	s_add_u32 s44, s44, 0x80000
	s_addc_u32 s45, s45, 0
	s_mov_b32 m0, s50
	ds_read_b128 v[160:163], v213 offset:32768
	ds_read_b128 v[164:167], v213 offset:33792
	ds_read_b128 v[184:187], v213 offset:34816
	ds_read_b128 v[188:191], v213 offset:35840
	ds_read_b128 v[192:195], v213 offset:36864
	ds_read_b128 v[196:199], v213 offset:37888
	ds_read_b128 v[200:203], v213 offset:38912
	ds_read_b128 v[214:217], v213 offset:39936
	global_load_lds_dwordx4 v168, s[44:45]
	s_mov_b32 m0, s51
	s_nop 0
	global_load_lds_dwordx4 v172, s[44:45]
	s_waitcnt vmcnt(8)
	s_waitcnt lgkmcnt(0)
	s_barrier
	s_setprio 1
	s_waitcnt lgkmcnt(0)
	v_mfma_f32_16x16x32_f16 v[120:123], v[136:139], v[160:163], v[120:123]
	v_mfma_f32_16x16x32_f16 v[124:127], v[128:131], v[160:163], v[124:127]
	v_mfma_f32_16x16x32_f16 v[104:107], v[136:139], v[184:187], v[104:107]
	v_mfma_f32_16x16x32_f16 v[108:111], v[128:131], v[184:187], v[108:111]
	v_mfma_f32_16x16x32_f16 v[88:91], v[136:139], v[192:195], v[88:91]
	v_mfma_f32_16x16x32_f16 v[92:95], v[128:131], v[192:195], v[92:95]
	v_mfma_f32_16x16x32_f16 v[72:75], v[136:139], v[200:203], v[72:75]
	v_mfma_f32_16x16x32_f16 v[76:79], v[128:131], v[200:203], v[76:79]
	v_mfma_f32_16x16x32_f16 v[120:123], v[140:143], v[164:167], v[120:123]
	v_mfma_f32_16x16x32_f16 v[124:127], v[132:135], v[164:167], v[124:127]
	v_mfma_f32_16x16x32_f16 v[104:107], v[140:143], v[188:191], v[104:107]
	v_mfma_f32_16x16x32_f16 v[108:111], v[132:135], v[188:191], v[108:111]
	v_mfma_f32_16x16x32_f16 v[88:91], v[140:143], v[196:199], v[88:91]
	v_mfma_f32_16x16x32_f16 v[92:95], v[132:135], v[196:199], v[92:95]
	v_mfma_f32_16x16x32_f16 v[72:75], v[140:143], v[214:217], v[72:75]
	v_mfma_f32_16x16x32_f16 v[76:79], v[132:135], v[214:217], v[76:79]
	s_setprio 0
	s_setprio 1
	v_mfma_f32_16x16x32_f16 v[112:115], v[152:155], v[160:163], v[112:115]
	v_mfma_f32_16x16x32_f16 v[116:119], v[144:147], v[160:163], v[116:119]
	v_mfma_f32_16x16x32_f16 v[96:99], v[152:155], v[184:187], v[96:99]
	v_mfma_f32_16x16x32_f16 v[100:103], v[144:147], v[184:187], v[100:103]
	v_mfma_f32_16x16x32_f16 v[80:83], v[152:155], v[192:195], v[80:83]
	v_mfma_f32_16x16x32_f16 v[84:87], v[144:147], v[192:195], v[84:87]
	v_mfma_f32_16x16x32_f16 v[64:67], v[152:155], v[200:203], v[64:67]
	v_mfma_f32_16x16x32_f16 v[68:71], v[144:147], v[200:203], v[68:71]
	v_mfma_f32_16x16x32_f16 v[112:115], v[156:159], v[164:167], v[112:115]
	v_mfma_f32_16x16x32_f16 v[116:119], v[148:151], v[164:167], v[116:119]
	v_mfma_f32_16x16x32_f16 v[96:99], v[156:159], v[188:191], v[96:99]
	v_mfma_f32_16x16x32_f16 v[100:103], v[148:151], v[188:191], v[100:103]
	v_mfma_f32_16x16x32_f16 v[80:83], v[156:159], v[196:199], v[80:83]
	v_mfma_f32_16x16x32_f16 v[84:87], v[148:151], v[196:199], v[84:87]
	v_mfma_f32_16x16x32_f16 v[64:67], v[156:159], v[214:217], v[64:67]
	v_mfma_f32_16x16x32_f16 v[68:71], v[148:151], v[214:217], v[68:71]
	s_setprio 0
	s_barrier
	s_add_i32 s44, s71, s48
	s_mov_b32 m0, s44
	ds_read_b128 v[160:163], v213 offset:49152
	ds_read_b128 v[164:167], v213 offset:50176
	ds_read_b128 v[184:187], v213 offset:51200
	ds_read_b128 v[188:191], v213 offset:52224
	ds_read_b128 v[192:195], v213 offset:53248
	ds_read_b128 v[196:199], v213 offset:54272
	ds_read_b128 v[200:203], v213 offset:55296
	ds_read_b128 v[214:217], v213 offset:56320
	global_load_lds_dwordx4 v170, s[98:99]
	s_add_i32 m0, s44, 0x2000
	s_add_u32 s42, s42, 0x80080
	s_addc_u32 s43, s43, 0
	s_add_i32 s44, s72, s48
	global_load_lds_dwordx4 v174, s[98:99]
	s_mov_b32 m0, s44
	s_nop 0
	global_load_lds_dwordx4 v170, s[42:43]
	s_add_i32 m0, s44, 0x2000
	s_nop 0
	global_load_lds_dwordx4 v174, s[42:43]
	s_mov_b32 m0, s61
	s_nop 0
	global_load_lds_dwordx4 v168, s[100:101]
	s_mov_b32 m0, s62
	s_nop 0
	global_load_lds_dwordx4 v172, s[100:101]
	s_waitcnt vmcnt(8)
	s_waitcnt lgkmcnt(0)
	s_barrier
	s_setprio 1
	s_waitcnt lgkmcnt(0)
	v_mfma_f32_16x16x32_f16 v[56:59], v[136:139], v[160:163], v[56:59]
	v_mfma_f32_16x16x32_f16 v[60:63], v[128:131], v[160:163], v[60:63]
	v_mfma_f32_16x16x32_f16 v[40:43], v[136:139], v[184:187], v[40:43]
	v_mfma_f32_16x16x32_f16 v[44:47], v[128:131], v[184:187], v[44:47]
	v_mfma_f32_16x16x32_f16 v[24:27], v[136:139], v[192:195], v[24:27]
	v_mfma_f32_16x16x32_f16 v[28:31], v[128:131], v[192:195], v[28:31]
	v_mfma_f32_16x16x32_f16 v[8:11], v[136:139], v[200:203], v[8:11]
	v_mfma_f32_16x16x32_f16 v[12:15], v[128:131], v[200:203], v[12:15]
	v_mfma_f32_16x16x32_f16 v[56:59], v[140:143], v[164:167], v[56:59]
	v_mfma_f32_16x16x32_f16 v[60:63], v[132:135], v[164:167], v[60:63]
	v_mfma_f32_16x16x32_f16 v[40:43], v[140:143], v[188:191], v[40:43]
	v_mfma_f32_16x16x32_f16 v[44:47], v[132:135], v[188:191], v[44:47]
	v_mfma_f32_16x16x32_f16 v[24:27], v[140:143], v[196:199], v[24:27]
	v_mfma_f32_16x16x32_f16 v[28:31], v[132:135], v[196:199], v[28:31]
	v_mfma_f32_16x16x32_f16 v[8:11], v[140:143], v[214:217], v[8:11]
	v_mfma_f32_16x16x32_f16 v[12:15], v[132:135], v[214:217], v[12:15]
	s_setprio 0
	s_setprio 1
	v_mfma_f32_16x16x32_f16 v[48:51], v[152:155], v[160:163], v[48:51]
	v_mfma_f32_16x16x32_f16 v[52:55], v[144:147], v[160:163], v[52:55]
	v_mfma_f32_16x16x32_f16 v[32:35], v[152:155], v[184:187], v[32:35]
	v_mfma_f32_16x16x32_f16 v[36:39], v[144:147], v[184:187], v[36:39]
	v_mfma_f32_16x16x32_f16 v[16:19], v[152:155], v[192:195], v[16:19]
	v_mfma_f32_16x16x32_f16 v[20:23], v[144:147], v[192:195], v[20:23]
	v_mfma_f32_16x16x32_f16 v[0:3], v[152:155], v[200:203], v[0:3]
	v_mfma_f32_16x16x32_f16 v[4:7], v[144:147], v[200:203], v[4:7]
	v_mfma_f32_16x16x32_f16 v[48:51], v[156:159], v[164:167], v[48:51]
	v_mfma_f32_16x16x32_f16 v[52:55], v[148:151], v[164:167], v[52:55]
	v_mfma_f32_16x16x32_f16 v[32:35], v[156:159], v[188:191], v[32:35]
	v_mfma_f32_16x16x32_f16 v[36:39], v[148:151], v[188:191], v[36:39]
	v_mfma_f32_16x16x32_f16 v[16:19], v[156:159], v[196:199], v[16:19]
	v_mfma_f32_16x16x32_f16 v[20:23], v[148:151], v[196:199], v[20:23]
	v_mfma_f32_16x16x32_f16 v[0:3], v[156:159], v[214:217], v[0:3]
	v_mfma_f32_16x16x32_f16 v[4:7], v[148:151], v[214:217], v[4:7]
	s_setprio 0
	s_barrier
	s_add_i32 s70, s70, 2
	s_add_u32 s68, s68, 0x100
	s_addc_u32 s69, s69, 0
	s_add_u32 s40, s40, 0x100
	s_addc_u32 s41, s41, 0
	s_cmp_gt_u32 s70, 29
	s_cbranch_scc0 .LBB0_1075
	s_and_b64 vcc, exec, s[20:21]
	s_cbranch_vccz .LBB0_1078
	s_barrier

; #define PG8_STAGE(bufoff, gbase, voff) do { _Pragma("unroll") for (int _i = 0; _i < 2; ++_i) \
;         __builtin_amdgcn_global_load_lds((const unsigned*)((const char*)(gbase) + (voff)[_i]), (PG8_LAS unsigned*)(lds + (bufoff) + ldsw + _i * 8192), 16, 0, 0); } while (0)
; #define PG8_LDA(dst, b, h) do { _Pragma("unroll") for (int m = 0; m < 4; ++m) _Pragma("unroll") for (int k = 0; k < 2; ++k) dst[m][k] = *(const PG8_LAS bf16x8*)(lds + PG8_SA(b, h) + aoff + m * 2048 + k * 1024); } while (0)
; #define PG8_LDB(dst, b, h) do { _Pragma("unroll") for (int n = 0; n < 2; ++n) _Pragma("unroll") for (int k = 0; k < 2; ++k) dst[n][k] = *(const PG8_LAS bf16x8*)(lds + PG8_SB(b, h) + boff + n * 2048 + k * 1024); } while (0)
; #define PG8_MMA(ai, bj, At, Bt) do { __builtin_amdgcn_s_setprio(1); _Pragma("unroll") for (int m = 0; m < 4; ++m) _Pragma("unroll") for (int n = 0; n < 2; ++n) _Pragma("unroll") for (int k = 0; k < 2; ++k) \
;         acc[ai][bj][m][n] = __builtin_amdgcn_mfma_f32_16x16x32_f16(Bt[n][k], At[m][k], acc[ai][bj][m][n], 0, 0, 0); __builtin_amdgcn_s_setprio(0); } while (0)
; #define PG8_WAIT_V(n) asm volatile("s_waitcnt vmcnt(" #n ")" ::: "memory")
; #define PG8_WAIT_L(n) asm volatile("s_waitcnt lgkmcnt(" #n ")" ::: "memory")
; #define PG8_BAR __builtin_amdgcn_s_barrier()
; #define PG8_SCHED __builtin_amdgcn_sched_barrier(0)
; template <class Epi, class Sched, bool ALIGN_EPI = false, bool SP2 = false>
; __device__ __forceinline__ void gemm_phase(PG8_LAS unsigned char* lds, const Gemm g, const Sched& S, const Epi& E) {
;     ...
;             PG8_LDB(B0, 0, 0); PG8_LDB(B1, 0, 1); PG8_SCHED; PG8_LDA(At, 0, 0); PG8_STAGE(PG8_SA(1, 1), a1 + hstep, voffA);
;             PG8_WAIT_V(8); PG8_WAIT_L(0); PG8_BAR; PG8_MMA(0, 0, At, B0); PG8_MMA(0, 1, At, B1); PG8_BAR; PG8_SCHED;
;             PG8_LDA(At, 0, 1); PG8_STAGE(PG8_SB(0, 0), b2, voffB); PG8_STAGE(PG8_SB(0, 1), b2 + hstep, voffB); PG8_STAGE(PG8_SA(0, 0), a2, voffA);
;             PG8_WAIT_V(8); PG8_WAIT_L(0); PG8_BAR; PG8_MMA(1, 0, At, B0); PG8_MMA(1, 1, At, B1); PG8_BAR; PG8_SCHED;
.LBB0_1167:
	ds_read_b128 v[128:131], v198
	ds_read_b128 v[132:135], v198 offset:1024
	ds_read_b128 v[136:139], v198 offset:2048
	ds_read_b128 v[140:143], v198 offset:3072
	ds_read_b128 v[144:147], v199
	ds_read_b128 v[148:151], v199 offset:1024
	ds_read_b128 v[152:155], v199 offset:2048
	ds_read_b128 v[156:159], v199 offset:3072
	s_add_u32 s44, s42, 0xfff80080
	s_addc_u32 s45, s43, -1
	s_cmp_eq_u32 s81, 28
	s_cselect_b32 s49, s35, s45
	s_cselect_b32 s48, s72, s44
	s_cselect_b32 s45, s31, s75
	s_cselect_b32 s44, s73, s74
	s_add_i32 m0, s41, 0xc000
	ds_read_b128 v[176:179], v200
	ds_read_b128 v[180:183], v200 offset:1024
	ds_read_b128 v[184:187], v200 offset:2048
	ds_read_b128 v[188:191], v200 offset:3072
	ds_read_b128 v[208:211], v200 offset:4096
	ds_read_b128 v[212:215], v200 offset:5120
	ds_read_b128 v[216:219], v200 offset:6144
	ds_read_b128 v[220:223], v200 offset:7168
	global_load_lds_dwordx4 v170, s[42:43]
	s_add_i32 m0, s41, 0xe000
	s_nop 0
	global_load_lds_dwordx4 v168, s[42:43]
	s_waitcnt vmcnt(8)
	s_waitcnt lgkmcnt(0)
	s_barrier
	s_setprio 1
	s_waitcnt lgkmcnt(0)
	v_mfma_f32_16x16x32_f16 v[120:123], v[136:139], v[176:179], v[120:123]
	v_mfma_f32_16x16x32_f16 v[124:127], v[128:131], v[176:179], v[124:127]
	v_mfma_f32_16x16x32_f16 v[104:107], v[136:139], v[184:187], v[104:107]
	v_mfma_f32_16x16x32_f16 v[108:111], v[128:131], v[184:187], v[108:111]
	v_mfma_f32_16x16x32_f16 v[88:91], v[136:139], v[208:211], v[88:91]
	v_mfma_f32_16x16x32_f16 v[92:95], v[128:131], v[208:211], v[92:95]
	v_mfma_f32_16x16x32_f16 v[72:75], v[136:139], v[216:219], v[72:75]
	v_mfma_f32_16x16x32_f16 v[76:79], v[128:131], v[216:219], v[76:79]
	v_mfma_f32_16x16x32_f16 v[120:123], v[140:143], v[180:183], v[120:123]
	v_mfma_f32_16x16x32_f16 v[124:127], v[132:135], v[180:183], v[124:127]
	v_mfma_f32_16x16x32_f16 v[104:107], v[140:143], v[188:191], v[104:107]
	v_mfma_f32_16x16x32_f16 v[108:111], v[132:135], v[188:191], v[108:111]
	v_mfma_f32_16x16x32_f16 v[88:91], v[140:143], v[212:215], v[88:91]
	v_mfma_f32_16x16x32_f16 v[92:95], v[132:135], v[212:215], v[92:95]
	v_mfma_f32_16x16x32_f16 v[72:75], v[140:143], v[220:223], v[72:75]
	v_mfma_f32_16x16x32_f16 v[76:79], v[132:135], v[220:223], v[76:79]
	s_setprio 0
	s_setprio 1
	v_mfma_f32_16x16x32_f16 v[112:115], v[152:155], v[176:179], v[112:115]
	v_mfma_f32_16x16x32_f16 v[116:119], v[144:147], v[176:179], v[116:119]
	v_mfma_f32_16x16x32_f16 v[96:99], v[152:155], v[184:187], v[96:99]
	v_mfma_f32_16x16x32_f16 v[100:103], v[144:147], v[184:187], v[100:103]
	v_mfma_f32_16x16x32_f16 v[80:83], v[152:155], v[208:211], v[80:83]
	v_mfma_f32_16x16x32_f16 v[84:87], v[144:147], v[208:211], v[84:87]
	v_mfma_f32_16x16x32_f16 v[64:67], v[152:155], v[216:219], v[64:67]
	v_mfma_f32_16x16x32_f16 v[68:71], v[144:147], v[216:219], v[68:71]
	v_mfma_f32_16x16x32_f16 v[112:115], v[156:159], v[180:183], v[112:115]
	v_mfma_f32_16x16x32_f16 v[116:119], v[148:151], v[180:183], v[116:119]
	v_mfma_f32_16x16x32_f16 v[96:99], v[156:159], v[188:191], v[96:99]
	v_mfma_f32_16x16x32_f16 v[100:103], v[148:151], v[188:191], v[100:103]
	v_mfma_f32_16x16x32_f16 v[80:83], v[156:159], v[212:215], v[80:83]
	v_mfma_f32_16x16x32_f16 v[84:87], v[148:151], v[212:215], v[84:87]
	v_mfma_f32_16x16x32_f16 v[64:67], v[156:159], v[220:223], v[64:67]
	v_mfma_f32_16x16x32_f16 v[68:71], v[148:151], v[220:223], v[68:71]
	s_setprio 0
	s_barrier
	s_add_i32 s82, s65, s52
	s_add_u32 s98, s44, s16
	s_addc_u32 s99, s45, s17
	s_mov_b32 m0, s82
	ds_read_b128 v[176:179], v200 offset:16384
	ds_read_b128 v[180:183], v200 offset:17408
	ds_read_b128 v[184:187], v200 offset:18432
	ds_read_b128 v[188:191], v200 offset:19456
	ds_read_b128 v[208:211], v200 offset:20480
	ds_read_b128 v[212:215], v200 offset:21504
	ds_read_b128 v[216:219], v200 offset:22528
	ds_read_b128 v[220:223], v200 offset:23552
	global_load_lds_dwordx4 v162, s[44:45]
	s_add_i32 m0, s82, 0x2000
	s_add_u32 s82, s44, 0x80000
	s_addc_u32 s83, s45, 0
	s_add_i32 s86, s66, s52
	global_load_lds_dwordx4 v166, s[44:45]
	s_mov_b32 m0, s86
	s_nop 0
	global_load_lds_dwordx4 v162, s[82:83]
	s_add_i32 m0, s86, 0x2000
	s_nop 0
	global_load_lds_dwordx4 v166, s[82:83]
	s_add_u32 s100, s48, s16
	s_addc_u32 s101, s49, s17
	s_mov_b32 m0, s41
	s_nop 0
	global_load_lds_dwordx4 v160, s[48:49]
	s_mov_b32 m0, s53
	s_nop 0
	global_load_lds_dwordx4 v164, s[48:49]
	s_waitcnt vmcnt(8)
	s_waitcnt lgkmcnt(0)
	s_barrier
	s_setprio 1
	s_waitcnt lgkmcnt(0)
	v_mfma_f32_16x16x32_f16 v[56:59], v[136:139], v[176:179], v[56:59]
	v_mfma_f32_16x16x32_f16 v[60:63], v[128:131], v[176:179], v[60:63]
	v_mfma_f32_16x16x32_f16 v[40:43], v[136:139], v[184:187], v[40:43]
	v_mfma_f32_16x16x32_f16 v[44:47], v[128:131], v[184:187], v[44:47]
	v_mfma_f32_16x16x32_f16 v[24:27], v[136:139], v[208:211], v[24:27]
	v_mfma_f32_16x16x32_f16 v[28:31], v[128:131], v[208:211], v[28:31]
	v_mfma_f32_16x16x32_f16 v[8:11], v[136:139], v[216:219], v[8:11]
	v_mfma_f32_16x16x32_f16 v[12:15], v[128:131], v[216:219], v[12:15]
	v_mfma_f32_16x16x32_f16 v[56:59], v[140:143], v[180:183], v[56:59]
	v_mfma_f32_16x16x32_f16 v[60:63], v[132:135], v[180:183], v[60:63]
	v_mfma_f32_16x16x32_f16 v[40:43], v[140:143], v[188:191], v[40:43]
	v_mfma_f32_16x16x32_f16 v[44:47], v[132:135], v[188:191], v[44:47]
	v_mfma_f32_16x16x32_f16 v[24:27], v[140:143], v[212:215], v[24:27]
	v_mfma_f32_16x16x32_f16 v[28:31], v[132:135], v[212:215], v[28:31]
	v_mfma_f32_16x16x32_f16 v[8:11], v[140:143], v[220:223], v[8:11]
	v_mfma_f32_16x16x32_f16 v[12:15], v[132:135], v[220:223], v[12:15]
	s_setprio 0
	s_setprio 1
	v_mfma_f32_16x16x32_f16 v[48:51], v[152:155], v[176:179], v[48:51]
	v_mfma_f32_16x16x32_f16 v[52:55], v[144:147], v[176:179], v[52:55]
	v_mfma_f32_16x16x32_f16 v[32:35], v[152:155], v[184:187], v[32:35]
	v_mfma_f32_16x16x32_f16 v[36:39], v[144:147], v[184:187], v[36:39]
	v_mfma_f32_16x16x32_f16 v[16:19], v[152:155], v[208:211], v[16:19]
	v_mfma_f32_16x16x32_f16 v[20:23], v[144:147], v[208:211], v[20:23]
	v_mfma_f32_16x16x32_f16 v[0:3], v[152:155], v[216:219], v[0:3]
	v_mfma_f32_16x16x32_f16 v[4:7], v[144:147], v[216:219], v[4:7]
	v_mfma_f32_16x16x32_f16 v[48:51], v[156:159], v[180:183], v[48:51]
	v_mfma_f32_16x16x32_f16 v[52:55], v[148:151], v[180:183], v[52:55]
	v_mfma_f32_16x16x32_f16 v[32:35], v[156:159], v[188:191], v[32:35]
	v_mfma_f32_16x16x32_f16 v[36:39], v[148:151], v[188:191], v[36:39]
	v_mfma_f32_16x16x32_f16 v[16:19], v[156:159], v[212:215], v[16:19]
	v_mfma_f32_16x16x32_f16 v[20:23], v[148:151], v[212:215], v[20:23]
	v_mfma_f32_16x16x32_f16 v[0:3], v[156:159], v[220:223], v[0:3]
	v_mfma_f32_16x16x32_f16 v[4:7], v[148:151], v[220:223], v[4:7]
	s_setprio 0
	s_barrier
; #define PG8_STAGE(bufoff, gbase, voff) do { _Pragma("unroll") for (int _i = 0; _i < 2; ++_i) \
;         __builtin_amdgcn_global_load_lds((const unsigned*)((const char*)(gbase) + (voff)[_i]), (PG8_LAS unsigned*)(lds + (bufoff) + ldsw + _i * 8192), 16, 0, 0); } while (0)
; #define PG8_LDA(dst, b, h) do { _Pragma("unroll") for (int m = 0; m < 4; ++m) _Pragma("unroll") for (int k = 0; k < 2; ++k) dst[m][k] = *(const PG8_LAS bf16x8*)(lds + PG8_SA(b, h) + aoff + m * 2048 + k * 1024); } while (0)
; #define PG8_LDB(dst, b, h) do { _Pragma("unroll") for (int n = 0; n < 2; ++n) _Pragma("unroll") for (int k = 0; k < 2; ++k) dst[n][k] = *(const PG8_LAS bf16x8*)(lds + PG8_SB(b, h) + boff + n * 2048 + k * 1024); } while (0)
; #define PG8_MMA(ai, bj, At, Bt) do { __builtin_amdgcn_s_setprio(1); _Pragma("unroll") for (int m = 0; m < 4; ++m) _Pragma("unroll") for (int n = 0; n < 2; ++n) _Pragma("unroll") for (int k = 0; k < 2; ++k) \
;         acc[ai][bj][m][n] = __builtin_amdgcn_mfma_f32_16x16x32_f16(Bt[n][k], At[m][k], acc[ai][bj][m][n], 0, 0, 0); __builtin_amdgcn_s_setprio(0); } while (0)
; #define PG8_WAIT_V(n) asm volatile("s_waitcnt vmcnt(" #n ")" ::: "memory")
; #define PG8_WAIT_L(n) asm volatile("s_waitcnt lgkmcnt(" #n ")" ::: "memory")
; #define PG8_BAR __builtin_amdgcn_s_barrier()
; #define PG8_SCHED __builtin_amdgcn_sched_barrier(0)
; template <class Epi, class Sched, bool ALIGN_EPI = false, bool SP2 = false>
; __device__ __forceinline__ void gemm_phase(PG8_LAS unsigned char* lds, const Gemm g, const Sched& S, const Epi& E) {
;     ...
;         for (int t = 0; t < nt; t += 2) {
;     ...
;             PG8_LDB(B0, 1, 0); PG8_LDB(B1, 1, 1); PG8_SCHED; PG8_LDA(At, 1, 0); PG8_STAGE(PG8_SA(0, 1), a2 + hstep, voffA);
;             PG8_WAIT_V(8); PG8_WAIT_L(0); PG8_BAR; PG8_MMA(0, 0, At, B0); PG8_MMA(0, 1, At, B1); PG8_BAR; PG8_SCHED;
;             PG8_LDA(At, 1, 1); PG8_STAGE(PG8_SB(1, 0), b3, voffB); PG8_STAGE(PG8_SB(1, 1), b3 + hstep, voffB); PG8_STAGE(PG8_SA(1, 0), a3, voffA);
;             PG8_WAIT_V(8); PG8_WAIT_L(0); PG8_BAR; PG8_MMA(1, 0, At, B0); PG8_MMA(1, 1, At, B1); PG8_BAR; PG8_SCHED;
	s_add_i32 s82, 0, 0x18000
	s_add_i32 s83, 0, 0x1c000
	v_add_u32_e32 v140, s82, v196
	v_add_u32_e32 v156, s83, v196
	ds_read_b128 v[128:131], v140
	ds_read_b128 v[132:135], v140 offset:1024
	ds_read_b128 v[136:139], v140 offset:2048
	ds_read_b128 v[140:143], v140 offset:3072
	ds_read_b128 v[144:147], v156
	ds_read_b128 v[148:151], v156 offset:1024
	ds_read_b128 v[152:155], v156 offset:2048
	ds_read_b128 v[156:159], v156 offset:3072
	s_add_u32 s48, s48, 0x80000
	s_addc_u32 s49, s49, 0
	s_mov_b32 m0, s60
	ds_read_b128 v[176:179], v200 offset:32768
	ds_read_b128 v[180:183], v200 offset:33792
	ds_read_b128 v[184:187], v200 offset:34816
	ds_read_b128 v[188:191], v200 offset:35840
	ds_read_b128 v[208:211], v200 offset:36864
	ds_read_b128 v[212:215], v200 offset:37888
	ds_read_b128 v[216:219], v200 offset:38912
	ds_read_b128 v[220:223], v200 offset:39936
	global_load_lds_dwordx4 v160, s[48:49]
	s_mov_b32 m0, s61
	s_nop 0
	global_load_lds_dwordx4 v164, s[48:49]
	s_waitcnt vmcnt(8)
	s_waitcnt lgkmcnt(0)
	s_barrier
	s_setprio 1
	s_waitcnt lgkmcnt(0)
	v_mfma_f32_16x16x32_f16 v[120:123], v[136:139], v[176:179], v[120:123]
	v_mfma_f32_16x16x32_f16 v[124:127], v[128:131], v[176:179], v[124:127]
	v_mfma_f32_16x16x32_f16 v[104:107], v[136:139], v[184:187], v[104:107]
	v_mfma_f32_16x16x32_f16 v[108:111], v[128:131], v[184:187], v[108:111]
	v_mfma_f32_16x16x32_f16 v[88:91], v[136:139], v[208:211], v[88:91]
	v_mfma_f32_16x16x32_f16 v[92:95], v[128:131], v[208:211], v[92:95]
	v_mfma_f32_16x16x32_f16 v[72:75], v[136:139], v[216:219], v[72:75]
	v_mfma_f32_16x16x32_f16 v[76:79], v[128:131], v[216:219], v[76:79]
	v_mfma_f32_16x16x32_f16 v[120:123], v[140:143], v[180:183], v[120:123]
	v_mfma_f32_16x16x32_f16 v[124:127], v[132:135], v[180:183], v[124:127]
	v_mfma_f32_16x16x32_f16 v[104:107], v[140:143], v[188:191], v[104:107]
	v_mfma_f32_16x16x32_f16 v[108:111], v[132:135], v[188:191], v[108:111]
	v_mfma_f32_16x16x32_f16 v[88:91], v[140:143], v[212:215], v[88:91]
	v_mfma_f32_16x16x32_f16 v[92:95], v[132:135], v[212:215], v[92:95]
	v_mfma_f32_16x16x32_f16 v[72:75], v[140:143], v[220:223], v[72:75]
	v_mfma_f32_16x16x32_f16 v[76:79], v[132:135], v[220:223], v[76:79]
	s_setprio 0
	s_setprio 1
	v_mfma_f32_16x16x32_f16 v[112:115], v[152:155], v[176:179], v[112:115]
	v_mfma_f32_16x16x32_f16 v[116:119], v[144:147], v[176:179], v[116:119]
	v_mfma_f32_16x16x32_f16 v[96:99], v[152:155], v[184:187], v[96:99]
	v_mfma_f32_16x16x32_f16 v[100:103], v[144:147], v[184:187], v[100:103]
	v_mfma_f32_16x16x32_f16 v[80:83], v[152:155], v[208:211], v[80:83]
	v_mfma_f32_16x16x32_f16 v[84:87], v[144:147], v[208:211], v[84:87]
	v_mfma_f32_16x16x32_f16 v[64:67], v[152:155], v[216:219], v[64:67]
	v_mfma_f32_16x16x32_f16 v[68:71], v[144:147], v[216:219], v[68:71]
	v_mfma_f32_16x16x32_f16 v[112:115], v[156:159], v[180:183], v[112:115]
	v_mfma_f32_16x16x32_f16 v[116:119], v[148:151], v[180:183], v[116:119]
	v_mfma_f32_16x16x32_f16 v[96:99], v[156:159], v[188:191], v[96:99]
	v_mfma_f32_16x16x32_f16 v[100:103], v[148:151], v[188:191], v[100:103]
	v_mfma_f32_16x16x32_f16 v[80:83], v[156:159], v[212:215], v[80:83]
	v_mfma_f32_16x16x32_f16 v[84:87], v[148:151], v[212:215], v[84:87]
	v_mfma_f32_16x16x32_f16 v[64:67], v[156:159], v[220:223], v[64:67]
	v_mfma_f32_16x16x32_f16 v[68:71], v[148:151], v[220:223], v[68:71]
	s_setprio 0
	s_barrier
	s_add_i32 s48, s82, s52
	s_mov_b32 m0, s48
	ds_read_b128 v[176:179], v200 offset:49152
	ds_read_b128 v[180:183], v200 offset:50176
	ds_read_b128 v[184:187], v200 offset:51200
	ds_read_b128 v[188:191], v200 offset:52224
	ds_read_b128 v[208:211], v200 offset:53248
	ds_read_b128 v[212:215], v200 offset:54272
	ds_read_b128 v[216:219], v200 offset:55296
	ds_read_b128 v[220:223], v200 offset:56320
	global_load_lds_dwordx4 v162, s[98:99]
	s_add_i32 m0, s48, 0x2000
	s_add_u32 s44, s44, 0x80080
	s_addc_u32 s45, s45, 0
	s_add_i32 s48, s83, s52
	global_load_lds_dwordx4 v166, s[98:99]
	s_mov_b32 m0, s48
	s_nop 0
	global_load_lds_dwordx4 v162, s[44:45]
	s_add_i32 m0, s48, 0x2000
	s_nop 0
	global_load_lds_dwordx4 v166, s[44:45]
	s_mov_b32 m0, s63
	s_nop 0
	global_load_lds_dwordx4 v160, s[100:101]
	s_mov_b32 m0, s64
	s_nop 0
	global_load_lds_dwordx4 v164, s[100:101]
	s_waitcnt vmcnt(8)
	s_waitcnt lgkmcnt(0)
	s_barrier
	s_setprio 1
	s_waitcnt lgkmcnt(0)
	v_mfma_f32_16x16x32_f16 v[56:59], v[136:139], v[176:179], v[56:59]
	v_mfma_f32_16x16x32_f16 v[60:63], v[128:131], v[176:179], v[60:63]
	v_mfma_f32_16x16x32_f16 v[40:43], v[136:139], v[184:187], v[40:43]
	v_mfma_f32_16x16x32_f16 v[44:47], v[128:131], v[184:187], v[44:47]
	v_mfma_f32_16x16x32_f16 v[24:27], v[136:139], v[208:211], v[24:27]
	v_mfma_f32_16x16x32_f16 v[28:31], v[128:131], v[208:211], v[28:31]
	v_mfma_f32_16x16x32_f16 v[8:11], v[136:139], v[216:219], v[8:11]
	v_mfma_f32_16x16x32_f16 v[12:15], v[128:131], v[216:219], v[12:15]
	v_mfma_f32_16x16x32_f16 v[56:59], v[140:143], v[180:183], v[56:59]
	v_mfma_f32_16x16x32_f16 v[60:63], v[132:135], v[180:183], v[60:63]
	v_mfma_f32_16x16x32_f16 v[40:43], v[140:143], v[188:191], v[40:43]
	v_mfma_f32_16x16x32_f16 v[44:47], v[132:135], v[188:191], v[44:47]
	v_mfma_f32_16x16x32_f16 v[24:27], v[140:143], v[212:215], v[24:27]
	v_mfma_f32_16x16x32_f16 v[28:31], v[132:135], v[212:215], v[28:31]
	v_mfma_f32_16x16x32_f16 v[8:11], v[140:143], v[220:223], v[8:11]
	v_mfma_f32_16x16x32_f16 v[12:15], v[132:135], v[220:223], v[12:15]
	s_setprio 0
	s_setprio 1
	v_mfma_f32_16x16x32_f16 v[48:51], v[152:155], v[176:179], v[48:51]
	v_mfma_f32_16x16x32_f16 v[52:55], v[144:147], v[176:179], v[52:55]
	v_mfma_f32_16x16x32_f16 v[32:35], v[152:155], v[184:187], v[32:35]
	v_mfma_f32_16x16x32_f16 v[36:39], v[144:147], v[184:187], v[36:39]
	v_mfma_f32_16x16x32_f16 v[16:19], v[152:155], v[208:211], v[16:19]
	v_mfma_f32_16x16x32_f16 v[20:23], v[144:147], v[208:211], v[20:23]
	v_mfma_f32_16x16x32_f16 v[0:3], v[152:155], v[216:219], v[0:3]
	v_mfma_f32_16x16x32_f16 v[4:7], v[144:147], v[216:219], v[4:7]
	v_mfma_f32_16x16x32_f16 v[48:51], v[156:159], v[180:183], v[48:51]
	v_mfma_f32_16x16x32_f16 v[52:55], v[148:151], v[180:183], v[52:55]
	v_mfma_f32_16x16x32_f16 v[32:35], v[156:159], v[188:191], v[32:35]
	v_mfma_f32_16x16x32_f16 v[36:39], v[148:151], v[188:191], v[36:39]
	v_mfma_f32_16x16x32_f16 v[16:19], v[156:159], v[212:215], v[16:19]
	v_mfma_f32_16x16x32_f16 v[20:23], v[148:151], v[212:215], v[20:23]
	v_mfma_f32_16x16x32_f16 v[0:3], v[156:159], v[220:223], v[0:3]
	v_mfma_f32_16x16x32_f16 v[4:7], v[148:151], v[220:223], v[4:7]
	s_setprio 0
	s_barrier
	s_add_i32 s81, s81, 2
	s_add_u32 s74, s74, 0x100
	s_addc_u32 s75, s75, 0
	s_add_u32 s42, s42, 0x100
	s_addc_u32 s43, s43, 0
	s_cmp_gt_u32 s81, 29
	s_cbranch_scc0 .LBB0_1167
	s_and_b64 vcc, exec, s[18:19]
	s_cbranch_vccz .LBB0_1170
	s_barrier

; #define PG8_STAGE(bufoff, gbase, voff) do { _Pragma("unroll") for (int _i = 0; _i < 2; ++_i) \
;         __builtin_amdgcn_global_load_lds((const unsigned*)((const char*)(gbase) + (voff)[_i]), (PG8_LAS unsigned*)(lds + (bufoff) + ldsw + _i * 8192), 16, 0, 0); } while (0)
; #define PG8_LDA(dst, b, h) do { _Pragma("unroll") for (int m = 0; m < 4; ++m) _Pragma("unroll") for (int k = 0; k < 2; ++k) dst[m][k] = *(const PG8_LAS bf16x8*)(lds + PG8_SA(b, h) + aoff + m * 2048 + k * 1024); } while (0)
; #define PG8_LDB(dst, b, h) do { _Pragma("unroll") for (int n = 0; n < 2; ++n) _Pragma("unroll") for (int k = 0; k < 2; ++k) dst[n][k] = *(const PG8_LAS bf16x8*)(lds + PG8_SB(b, h) + boff + n * 2048 + k * 1024); } while (0)
; #define PG8_MMA(ai, bj, At, Bt) do { __builtin_amdgcn_s_setprio(1); _Pragma("unroll") for (int m = 0; m < 4; ++m) _Pragma("unroll") for (int n = 0; n < 2; ++n) _Pragma("unroll") for (int k = 0; k < 2; ++k) \
;         acc[ai][bj][m][n] = __builtin_amdgcn_mfma_f32_16x16x32_f16(Bt[n][k], At[m][k], acc[ai][bj][m][n], 0, 0, 0); __builtin_amdgcn_s_setprio(0); } while (0)
; #define PG8_WAIT_V(n) asm volatile("s_waitcnt vmcnt(" #n ")" ::: "memory")
; #define PG8_WAIT_L(n) asm volatile("s_waitcnt lgkmcnt(" #n ")" ::: "memory")
; #define PG8_BAR __builtin_amdgcn_s_barrier()
; #define PG8_SCHED __builtin_amdgcn_sched_barrier(0)
; template <class Epi, class Sched, bool ALIGN_EPI = false, bool SP2 = false>
; __device__ __forceinline__ void gemm_phase(PG8_LAS unsigned char* lds, const Gemm g, const Sched& S, const Epi& E) {
;     ...
;             PG8_LDB(B0, 0, 0); PG8_LDB(B1, 0, 1); PG8_SCHED; PG8_LDA(At, 0, 0); PG8_STAGE(PG8_SA(1, 1), a1 + hstep, voffA);
;             PG8_WAIT_V(8); PG8_WAIT_L(0); PG8_BAR; PG8_MMA(0, 0, At, B0); PG8_MMA(0, 1, At, B1); PG8_BAR; PG8_SCHED;
;             PG8_LDA(At, 0, 1); PG8_STAGE(PG8_SB(0, 0), b2, voffB); PG8_STAGE(PG8_SB(0, 1), b2 + hstep, voffB); PG8_STAGE(PG8_SA(0, 0), a2, voffA);
;             PG8_WAIT_V(8); PG8_WAIT_L(0); PG8_BAR; PG8_MMA(1, 0, At, B0); PG8_MMA(1, 1, At, B1); PG8_BAR; PG8_SCHED;
.LBB0_1243:
	ds_read_b128 v[128:131], v189
	ds_read_b128 v[132:135], v189 offset:1024
	ds_read_b128 v[136:139], v189 offset:2048
	ds_read_b128 v[140:143], v189 offset:3072
	ds_read_b128 v[144:147], v190
	ds_read_b128 v[148:151], v190 offset:1024
	ds_read_b128 v[152:155], v190 offset:2048
	ds_read_b128 v[156:159], v190 offset:3072
	s_add_u32 s34, s30, 0xffe00080
	s_addc_u32 s35, s31, -1
	s_cmpk_eq_i32 s61, 0x7c
	s_cselect_b32 s37, s23, s35
	s_cselect_b32 s36, s51, s34
	s_cselect_b32 s35, s21, s60
	s_cselect_b32 s34, s52, s53
	s_add_i32 m0, s29, 0xc000
	ds_read_b128 v[176:179], v191
	ds_read_b128 v[180:183], v191 offset:1024
	ds_read_b128 v[192:195], v191 offset:2048
	ds_read_b128 v[196:199], v191 offset:3072
	ds_read_b128 v[200:203], v191 offset:4096
	ds_read_b128 v[208:211], v191 offset:5120
	ds_read_b128 v[212:215], v191 offset:6144
	ds_read_b128 v[216:219], v191 offset:7168
	global_load_lds_dwordx4 v170, s[30:31]
	s_add_i32 m0, s29, 0xe000
	s_nop 0
	global_load_lds_dwordx4 v168, s[30:31]
	s_waitcnt vmcnt(8)
	s_waitcnt lgkmcnt(0)
	s_barrier
	s_setprio 1
	s_waitcnt lgkmcnt(0)
	v_mfma_f32_16x16x32_f16 v[120:123], v[136:139], v[176:179], v[120:123]
	v_mfma_f32_16x16x32_f16 v[124:127], v[128:131], v[176:179], v[124:127]
	v_mfma_f32_16x16x32_f16 v[104:107], v[136:139], v[192:195], v[104:107]
	v_mfma_f32_16x16x32_f16 v[108:111], v[128:131], v[192:195], v[108:111]
	v_mfma_f32_16x16x32_f16 v[88:91], v[136:139], v[200:203], v[88:91]
	v_mfma_f32_16x16x32_f16 v[92:95], v[128:131], v[200:203], v[92:95]
	v_mfma_f32_16x16x32_f16 v[72:75], v[136:139], v[212:215], v[72:75]
	v_mfma_f32_16x16x32_f16 v[76:79], v[128:131], v[212:215], v[76:79]
	v_mfma_f32_16x16x32_f16 v[120:123], v[140:143], v[180:183], v[120:123]
	v_mfma_f32_16x16x32_f16 v[124:127], v[132:135], v[180:183], v[124:127]
	v_mfma_f32_16x16x32_f16 v[104:107], v[140:143], v[196:199], v[104:107]
	v_mfma_f32_16x16x32_f16 v[108:111], v[132:135], v[196:199], v[108:111]
	v_mfma_f32_16x16x32_f16 v[88:91], v[140:143], v[208:211], v[88:91]
	v_mfma_f32_16x16x32_f16 v[92:95], v[132:135], v[208:211], v[92:95]
	v_mfma_f32_16x16x32_f16 v[72:75], v[140:143], v[216:219], v[72:75]
	v_mfma_f32_16x16x32_f16 v[76:79], v[132:135], v[216:219], v[76:79]
	s_setprio 0
	s_setprio 1
	v_mfma_f32_16x16x32_f16 v[112:115], v[152:155], v[176:179], v[112:115]
	v_mfma_f32_16x16x32_f16 v[116:119], v[144:147], v[176:179], v[116:119]
	v_mfma_f32_16x16x32_f16 v[96:99], v[152:155], v[192:195], v[96:99]
	v_mfma_f32_16x16x32_f16 v[100:103], v[144:147], v[192:195], v[100:103]
	v_mfma_f32_16x16x32_f16 v[80:83], v[152:155], v[200:203], v[80:83]
	v_mfma_f32_16x16x32_f16 v[84:87], v[144:147], v[200:203], v[84:87]
	v_mfma_f32_16x16x32_f16 v[64:67], v[152:155], v[212:215], v[64:67]
	v_mfma_f32_16x16x32_f16 v[68:71], v[144:147], v[212:215], v[68:71]
	v_mfma_f32_16x16x32_f16 v[112:115], v[156:159], v[180:183], v[112:115]
	v_mfma_f32_16x16x32_f16 v[116:119], v[148:151], v[180:183], v[116:119]
	v_mfma_f32_16x16x32_f16 v[96:99], v[156:159], v[196:199], v[96:99]
	v_mfma_f32_16x16x32_f16 v[100:103], v[148:151], v[196:199], v[100:103]
	v_mfma_f32_16x16x32_f16 v[80:83], v[156:159], v[208:211], v[80:83]
	v_mfma_f32_16x16x32_f16 v[84:87], v[148:151], v[208:211], v[84:87]
	v_mfma_f32_16x16x32_f16 v[64:67], v[156:159], v[216:219], v[64:67]
	v_mfma_f32_16x16x32_f16 v[68:71], v[148:151], v[216:219], v[68:71]
	s_setprio 0
	s_barrier
	s_add_i32 s62, s48, s39
	s_add_u32 s98, s34, s12
	s_addc_u32 s99, s35, s13
	s_mov_b32 m0, s62
	ds_read_b128 v[176:179], v191 offset:16384
	ds_read_b128 v[180:183], v191 offset:17408
	ds_read_b128 v[192:195], v191 offset:18432
	ds_read_b128 v[196:199], v191 offset:19456
	ds_read_b128 v[200:203], v191 offset:20480
	ds_read_b128 v[208:211], v191 offset:21504
	ds_read_b128 v[212:215], v191 offset:22528
	ds_read_b128 v[216:219], v191 offset:23552
	global_load_lds_dwordx4 v162, s[34:35]
	s_add_i32 m0, s62, 0x2000
	s_add_u32 s62, s34, 0x200000
	s_addc_u32 s63, s35, 0
	s_add_i32 s64, s49, s39
	global_load_lds_dwordx4 v166, s[34:35]
	s_mov_b32 m0, s64
	s_nop 0
	global_load_lds_dwordx4 v162, s[62:63]
	s_add_i32 m0, s64, 0x2000
	s_nop 0
	global_load_lds_dwordx4 v166, s[62:63]
	s_add_u32 s100, s36, s12
	s_addc_u32 s101, s37, s13
	s_mov_b32 m0, s29
	s_nop 0
	global_load_lds_dwordx4 v160, s[36:37]
	s_mov_b32 m0, s40
	s_nop 0
	global_load_lds_dwordx4 v164, s[36:37]
	s_waitcnt vmcnt(8)
	s_waitcnt lgkmcnt(0)
	s_barrier
	s_setprio 1
	s_waitcnt lgkmcnt(0)
	v_mfma_f32_16x16x32_f16 v[56:59], v[136:139], v[176:179], v[56:59]
	v_mfma_f32_16x16x32_f16 v[60:63], v[128:131], v[176:179], v[60:63]
	v_mfma_f32_16x16x32_f16 v[40:43], v[136:139], v[192:195], v[40:43]
	v_mfma_f32_16x16x32_f16 v[44:47], v[128:131], v[192:195], v[44:47]
	v_mfma_f32_16x16x32_f16 v[24:27], v[136:139], v[200:203], v[24:27]
	v_mfma_f32_16x16x32_f16 v[28:31], v[128:131], v[200:203], v[28:31]
	v_mfma_f32_16x16x32_f16 v[8:11], v[136:139], v[212:215], v[8:11]
	v_mfma_f32_16x16x32_f16 v[12:15], v[128:131], v[212:215], v[12:15]
	v_mfma_f32_16x16x32_f16 v[56:59], v[140:143], v[180:183], v[56:59]
	v_mfma_f32_16x16x32_f16 v[60:63], v[132:135], v[180:183], v[60:63]
	v_mfma_f32_16x16x32_f16 v[40:43], v[140:143], v[196:199], v[40:43]
	v_mfma_f32_16x16x32_f16 v[44:47], v[132:135], v[196:199], v[44:47]
	v_mfma_f32_16x16x32_f16 v[24:27], v[140:143], v[208:211], v[24:27]
	v_mfma_f32_16x16x32_f16 v[28:31], v[132:135], v[208:211], v[28:31]
	v_mfma_f32_16x16x32_f16 v[8:11], v[140:143], v[216:219], v[8:11]
	v_mfma_f32_16x16x32_f16 v[12:15], v[132:135], v[216:219], v[12:15]
	s_setprio 0
	s_setprio 1
	v_mfma_f32_16x16x32_f16 v[48:51], v[152:155], v[176:179], v[48:51]
	v_mfma_f32_16x16x32_f16 v[52:55], v[144:147], v[176:179], v[52:55]
	v_mfma_f32_16x16x32_f16 v[32:35], v[152:155], v[192:195], v[32:35]
	v_mfma_f32_16x16x32_f16 v[36:39], v[144:147], v[192:195], v[36:39]
	v_mfma_f32_16x16x32_f16 v[16:19], v[152:155], v[200:203], v[16:19]
	v_mfma_f32_16x16x32_f16 v[20:23], v[144:147], v[200:203], v[20:23]
	v_mfma_f32_16x16x32_f16 v[0:3], v[152:155], v[212:215], v[0:3]
	v_mfma_f32_16x16x32_f16 v[4:7], v[144:147], v[212:215], v[4:7]
	v_mfma_f32_16x16x32_f16 v[48:51], v[156:159], v[180:183], v[48:51]
	v_mfma_f32_16x16x32_f16 v[52:55], v[148:151], v[180:183], v[52:55]
	v_mfma_f32_16x16x32_f16 v[32:35], v[156:159], v[196:199], v[32:35]
	v_mfma_f32_16x16x32_f16 v[36:39], v[148:151], v[196:199], v[36:39]
	v_mfma_f32_16x16x32_f16 v[16:19], v[156:159], v[208:211], v[16:19]
	v_mfma_f32_16x16x32_f16 v[20:23], v[148:151], v[208:211], v[20:23]
	v_mfma_f32_16x16x32_f16 v[0:3], v[156:159], v[216:219], v[0:3]
	v_mfma_f32_16x16x32_f16 v[4:7], v[148:151], v[216:219], v[4:7]
	s_setprio 0
	s_barrier
; #define PG8_STAGE(bufoff, gbase, voff) do { _Pragma("unroll") for (int _i = 0; _i < 2; ++_i) \
;         __builtin_amdgcn_global_load_lds((const unsigned*)((const char*)(gbase) + (voff)[_i]), (PG8_LAS unsigned*)(lds + (bufoff) + ldsw + _i * 8192), 16, 0, 0); } while (0)
; #define PG8_LDA(dst, b, h) do { _Pragma("unroll") for (int m = 0; m < 4; ++m) _Pragma("unroll") for (int k = 0; k < 2; ++k) dst[m][k] = *(const PG8_LAS bf16x8*)(lds + PG8_SA(b, h) + aoff + m * 2048 + k * 1024); } while (0)
; #define PG8_LDB(dst, b, h) do { _Pragma("unroll") for (int n = 0; n < 2; ++n) _Pragma("unroll") for (int k = 0; k < 2; ++k) dst[n][k] = *(const PG8_LAS bf16x8*)(lds + PG8_SB(b, h) + boff + n * 2048 + k * 1024); } while (0)
; #define PG8_MMA(ai, bj, At, Bt) do { __builtin_amdgcn_s_setprio(1); _Pragma("unroll") for (int m = 0; m < 4; ++m) _Pragma("unroll") for (int n = 0; n < 2; ++n) _Pragma("unroll") for (int k = 0; k < 2; ++k) \
;         acc[ai][bj][m][n] = __builtin_amdgcn_mfma_f32_16x16x32_f16(Bt[n][k], At[m][k], acc[ai][bj][m][n], 0, 0, 0); __builtin_amdgcn_s_setprio(0); } while (0)
; #define PG8_WAIT_V(n) asm volatile("s_waitcnt vmcnt(" #n ")" ::: "memory")
; #define PG8_WAIT_L(n) asm volatile("s_waitcnt lgkmcnt(" #n ")" ::: "memory")
; #define PG8_BAR __builtin_amdgcn_s_barrier()
; #define PG8_SCHED __builtin_amdgcn_sched_barrier(0)
; template <class Epi, class Sched, bool ALIGN_EPI = false, bool SP2 = false>
; __device__ __forceinline__ void gemm_phase(PG8_LAS unsigned char* lds, const Gemm g, const Sched& S, const Epi& E) {
;     ...
;         for (int t = 0; t < nt; t += 2) {
;     ...
;             PG8_LDB(B0, 1, 0); PG8_LDB(B1, 1, 1); PG8_SCHED; PG8_LDA(At, 1, 0); PG8_STAGE(PG8_SA(0, 1), a2 + hstep, voffA);
;             PG8_WAIT_V(8); PG8_WAIT_L(0); PG8_BAR; PG8_MMA(0, 0, At, B0); PG8_MMA(0, 1, At, B1); PG8_BAR; PG8_SCHED;
;             PG8_LDA(At, 1, 1); PG8_STAGE(PG8_SB(1, 0), b3, voffB); PG8_STAGE(PG8_SB(1, 1), b3 + hstep, voffB); PG8_STAGE(PG8_SA(1, 0), a3, voffA);
;             PG8_WAIT_V(8); PG8_WAIT_L(0); PG8_BAR; PG8_MMA(1, 0, At, B0); PG8_MMA(1, 1, At, B1); PG8_BAR; PG8_SCHED;
	s_add_i32 s62, 0, 0x18000
	s_add_i32 s63, 0, 0x1c000
	v_add_u32_e32 v140, s62, v187
	v_add_u32_e32 v156, s63, v187
	ds_read_b128 v[128:131], v140
	ds_read_b128 v[132:135], v140 offset:1024
	ds_read_b128 v[136:139], v140 offset:2048
	ds_read_b128 v[140:143], v140 offset:3072
	ds_read_b128 v[144:147], v156
	ds_read_b128 v[148:151], v156 offset:1024
	ds_read_b128 v[152:155], v156 offset:2048
	ds_read_b128 v[156:159], v156 offset:3072
	s_add_u32 s36, s36, 0x200000
	s_addc_u32 s37, s37, 0
	s_mov_b32 m0, s41
	ds_read_b128 v[176:179], v191 offset:32768
	ds_read_b128 v[180:183], v191 offset:33792
	ds_read_b128 v[192:195], v191 offset:34816
	ds_read_b128 v[196:199], v191 offset:35840
	ds_read_b128 v[200:203], v191 offset:36864
	ds_read_b128 v[208:211], v191 offset:37888
	ds_read_b128 v[212:215], v191 offset:38912
	ds_read_b128 v[216:219], v191 offset:39936
	global_load_lds_dwordx4 v160, s[36:37]
	s_mov_b32 m0, s42
	s_nop 0
	global_load_lds_dwordx4 v164, s[36:37]
	s_waitcnt vmcnt(8)
	s_waitcnt lgkmcnt(0)
	s_barrier
	s_setprio 1
	s_waitcnt lgkmcnt(0)
	v_mfma_f32_16x16x32_f16 v[120:123], v[136:139], v[176:179], v[120:123]
	v_mfma_f32_16x16x32_f16 v[124:127], v[128:131], v[176:179], v[124:127]
	v_mfma_f32_16x16x32_f16 v[104:107], v[136:139], v[192:195], v[104:107]
	v_mfma_f32_16x16x32_f16 v[108:111], v[128:131], v[192:195], v[108:111]
	v_mfma_f32_16x16x32_f16 v[88:91], v[136:139], v[200:203], v[88:91]
	v_mfma_f32_16x16x32_f16 v[92:95], v[128:131], v[200:203], v[92:95]
	v_mfma_f32_16x16x32_f16 v[72:75], v[136:139], v[212:215], v[72:75]
	v_mfma_f32_16x16x32_f16 v[76:79], v[128:131], v[212:215], v[76:79]
	v_mfma_f32_16x16x32_f16 v[120:123], v[140:143], v[180:183], v[120:123]
	v_mfma_f32_16x16x32_f16 v[124:127], v[132:135], v[180:183], v[124:127]
	v_mfma_f32_16x16x32_f16 v[104:107], v[140:143], v[196:199], v[104:107]
	v_mfma_f32_16x16x32_f16 v[108:111], v[132:135], v[196:199], v[108:111]
	v_mfma_f32_16x16x32_f16 v[88:91], v[140:143], v[208:211], v[88:91]
	v_mfma_f32_16x16x32_f16 v[92:95], v[132:135], v[208:211], v[92:95]
	v_mfma_f32_16x16x32_f16 v[72:75], v[140:143], v[216:219], v[72:75]
	v_mfma_f32_16x16x32_f16 v[76:79], v[132:135], v[216:219], v[76:79]
	s_setprio 0
	s_setprio 1
	v_mfma_f32_16x16x32_f16 v[112:115], v[152:155], v[176:179], v[112:115]
	v_mfma_f32_16x16x32_f16 v[116:119], v[144:147], v[176:179], v[116:119]
	v_mfma_f32_16x16x32_f16 v[96:99], v[152:155], v[192:195], v[96:99]
	v_mfma_f32_16x16x32_f16 v[100:103], v[144:147], v[192:195], v[100:103]
	v_mfma_f32_16x16x32_f16 v[80:83], v[152:155], v[200:203], v[80:83]
	v_mfma_f32_16x16x32_f16 v[84:87], v[144:147], v[200:203], v[84:87]
	v_mfma_f32_16x16x32_f16 v[64:67], v[152:155], v[212:215], v[64:67]
	v_mfma_f32_16x16x32_f16 v[68:71], v[144:147], v[212:215], v[68:71]
	v_mfma_f32_16x16x32_f16 v[112:115], v[156:159], v[180:183], v[112:115]
	v_mfma_f32_16x16x32_f16 v[116:119], v[148:151], v[180:183], v[116:119]
	v_mfma_f32_16x16x32_f16 v[96:99], v[156:159], v[196:199], v[96:99]
	v_mfma_f32_16x16x32_f16 v[100:103], v[148:151], v[196:199], v[100:103]
	v_mfma_f32_16x16x32_f16 v[80:83], v[156:159], v[208:211], v[80:83]
	v_mfma_f32_16x16x32_f16 v[84:87], v[148:151], v[208:211], v[84:87]
	v_mfma_f32_16x16x32_f16 v[64:67], v[156:159], v[216:219], v[64:67]
	v_mfma_f32_16x16x32_f16 v[68:71], v[148:151], v[216:219], v[68:71]
	s_setprio 0
	s_barrier
	s_add_i32 s36, s62, s39
	s_mov_b32 m0, s36
	ds_read_b128 v[176:179], v191 offset:49152
	ds_read_b128 v[180:183], v191 offset:50176
	ds_read_b128 v[192:195], v191 offset:51200
	ds_read_b128 v[196:199], v191 offset:52224
	ds_read_b128 v[200:203], v191 offset:53248
	ds_read_b128 v[208:211], v191 offset:54272
	ds_read_b128 v[212:215], v191 offset:55296
	ds_read_b128 v[216:219], v191 offset:56320
	global_load_lds_dwordx4 v162, s[98:99]
	s_add_i32 m0, s36, 0x2000
	s_add_u32 s34, s34, 0x200080
	s_addc_u32 s35, s35, 0
	s_add_i32 s36, s63, s39
	global_load_lds_dwordx4 v166, s[98:99]
	s_mov_b32 m0, s36
	s_nop 0
	global_load_lds_dwordx4 v162, s[34:35]
	s_add_i32 m0, s36, 0x2000
	s_nop 0
	global_load_lds_dwordx4 v166, s[34:35]
	s_mov_b32 m0, s44
	s_nop 0
	global_load_lds_dwordx4 v160, s[100:101]
	s_mov_b32 m0, s45
	s_nop 0
	global_load_lds_dwordx4 v164, s[100:101]
	s_waitcnt vmcnt(8)
	s_waitcnt lgkmcnt(0)
	s_barrier
	s_setprio 1
	s_waitcnt lgkmcnt(0)
	v_mfma_f32_16x16x32_f16 v[56:59], v[136:139], v[176:179], v[56:59]
	v_mfma_f32_16x16x32_f16 v[60:63], v[128:131], v[176:179], v[60:63]
	v_mfma_f32_16x16x32_f16 v[40:43], v[136:139], v[192:195], v[40:43]
	v_mfma_f32_16x16x32_f16 v[44:47], v[128:131], v[192:195], v[44:47]
	v_mfma_f32_16x16x32_f16 v[24:27], v[136:139], v[200:203], v[24:27]
	v_mfma_f32_16x16x32_f16 v[28:31], v[128:131], v[200:203], v[28:31]
	v_mfma_f32_16x16x32_f16 v[8:11], v[136:139], v[212:215], v[8:11]
	v_mfma_f32_16x16x32_f16 v[12:15], v[128:131], v[212:215], v[12:15]
	v_mfma_f32_16x16x32_f16 v[56:59], v[140:143], v[180:183], v[56:59]
	v_mfma_f32_16x16x32_f16 v[60:63], v[132:135], v[180:183], v[60:63]
	v_mfma_f32_16x16x32_f16 v[40:43], v[140:143], v[196:199], v[40:43]
	v_mfma_f32_16x16x32_f16 v[44:47], v[132:135], v[196:199], v[44:47]
	v_mfma_f32_16x16x32_f16 v[24:27], v[140:143], v[208:211], v[24:27]
	v_mfma_f32_16x16x32_f16 v[28:31], v[132:135], v[208:211], v[28:31]
	v_mfma_f32_16x16x32_f16 v[8:11], v[140:143], v[216:219], v[8:11]
	v_mfma_f32_16x16x32_f16 v[12:15], v[132:135], v[216:219], v[12:15]
	s_setprio 0
	s_setprio 1
	v_mfma_f32_16x16x32_f16 v[48:51], v[152:155], v[176:179], v[48:51]
	v_mfma_f32_16x16x32_f16 v[52:55], v[144:147], v[176:179], v[52:55]
	v_mfma_f32_16x16x32_f16 v[32:35], v[152:155], v[192:195], v[32:35]
	v_mfma_f32_16x16x32_f16 v[36:39], v[144:147], v[192:195], v[36:39]
	v_mfma_f32_16x16x32_f16 v[16:19], v[152:155], v[200:203], v[16:19]
	v_mfma_f32_16x16x32_f16 v[20:23], v[144:147], v[200:203], v[20:23]
	v_mfma_f32_16x16x32_f16 v[0:3], v[152:155], v[212:215], v[0:3]
	v_mfma_f32_16x16x32_f16 v[4:7], v[144:147], v[212:215], v[4:7]
	v_mfma_f32_16x16x32_f16 v[48:51], v[156:159], v[180:183], v[48:51]
	v_mfma_f32_16x16x32_f16 v[52:55], v[148:151], v[180:183], v[52:55]
	v_mfma_f32_16x16x32_f16 v[32:35], v[156:159], v[196:199], v[32:35]
	v_mfma_f32_16x16x32_f16 v[36:39], v[148:151], v[196:199], v[36:39]
	v_mfma_f32_16x16x32_f16 v[16:19], v[156:159], v[208:211], v[16:19]
	v_mfma_f32_16x16x32_f16 v[20:23], v[148:151], v[208:211], v[20:23]
	v_mfma_f32_16x16x32_f16 v[0:3], v[156:159], v[216:219], v[0:3]
	v_mfma_f32_16x16x32_f16 v[4:7], v[148:151], v[216:219], v[4:7]
	s_setprio 0
	s_barrier
	s_add_i32 s61, s61, 2
	s_add_u32 s53, s53, 0x100
	s_addc_u32 s60, s60, 0
	s_add_u32 s30, s30, 0x100
	s_addc_u32 s31, s31, 0
	s_cmpk_gt_u32 s61, 0x7d
	s_cbranch_scc0 .LBB0_1243
	s_and_b64 vcc, exec, s[14:15]
	s_cbranch_vccz .LBB0_1246
	s_barrier

; __global__ void __launch_bounds__(NWAVES * 64, 2) mega_fwd(Params P) {
	.amdhsa_kernel _Z8mega_fwd6Params
		.amdhsa_group_segment_fixed_size 0
		.amdhsa_private_segment_fixed_size 0
		.amdhsa_kernarg_size 400
		.amdhsa_user_sgpr_count 2
		.amdhsa_user_sgpr_dispatch_ptr 0
		.amdhsa_user_sgpr_queue_ptr 0
		.amdhsa_user_sgpr_kernarg_segment_ptr 1
		.amdhsa_user_sgpr_dispatch_id 0
		.amdhsa_user_sgpr_kernarg_preload_length 0
		.amdhsa_user_sgpr_kernarg_preload_offset 0
		.amdhsa_user_sgpr_private_segment_size 0
		.amdhsa_uses_dynamic_stack 0
		.amdhsa_enable_private_segment 0
		.amdhsa_system_sgpr_workgroup_id_x 1
		.amdhsa_system_sgpr_workgroup_id_y 0
		.amdhsa_system_sgpr_workgroup_id_z 0
		.amdhsa_system_sgpr_workgroup_info 0
		.amdhsa_system_vgpr_workitem_id 2
		.amdhsa_next_free_vgpr 235
		.amdhsa_next_free_sgpr 102
		.amdhsa_accum_offset 236
		.amdhsa_reserve_vcc 1
		.amdhsa_float_round_mode_32 0
		.amdhsa_float_round_mode_16_64 0
		.amdhsa_float_denorm_mode_32 3
		.amdhsa_float_denorm_mode_16_64 3
		.amdhsa_dx10_clamp 1
		.amdhsa_ieee_mode 1
		.amdhsa_fp16_overflow 0
		.amdhsa_tg_split 0
		.amdhsa_exception_fp_ieee_invalid_op 0
		.amdhsa_exception_fp_denorm_src 0
		.amdhsa_exception_fp_ieee_div_zero 0
		.amdhsa_exception_fp_ieee_overflow 0
		.amdhsa_exception_fp_ieee_underflow 0
		.amdhsa_exception_fp_ieee_inexact 0
		.amdhsa_exception_int_div_zero 0
	.end_amdhsa_kernel

; __global__ void __launch_bounds__(NWAVES * 64, 2) mega_fwd(Params P) {
amdhsa.kernels:
  - .agpr_count:     0
    .args:
      - .offset:         0
        .size:           144
        .value_kind:     by_value
      - .offset:         144
        .size:           4
        .value_kind:     hidden_block_count_x
      - .offset:         148
        .size:           4
        .value_kind:     hidden_block_count_y
      - .offset:         152
        .size:           4
        .value_kind:     hidden_block_count_z
      - .offset:         156
        .size:           2
        .value_kind:     hidden_group_size_x
      - .offset:         158
        .size:           2
        .value_kind:     hidden_group_size_y
      - .offset:         160
        .size:           2
        .value_kind:     hidden_group_size_z
      - .offset:         162
        .size:           2
        .value_kind:     hidden_remainder_x
      - .offset:         164
        .size:           2
        .value_kind:     hidden_remainder_y
      - .offset:         166
        .size:           2
        .value_kind:     hidden_remainder_z
      - .offset:         184
        .size:           8
        .value_kind:     hidden_global_offset_x
      - .offset:         192
        .size:           8
        .value_kind:     hidden_global_offset_y
      - .offset:         200
        .size:           8
        .value_kind:     hidden_global_offset_z
      - .offset:         208
        .size:           2
        .value_kind:     hidden_grid_dims
      - .offset:         232
        .size:           8
        .value_kind:     hidden_multigrid_sync_arg
      - .offset:         264
        .size:           4
        .value_kind:     hidden_dynamic_lds_size
    .group_segment_fixed_size: 0
    .kernarg_segment_align: 8
    .kernarg_segment_size: 400
    .language:       OpenCL C
    .language_version:
      - 2
      - 0
    .max_flat_workgroup_size: 512
    .name:           _Z8mega_fwd6Params
    .private_segment_fixed_size: 0
    .sgpr_count:     108
    .sgpr_spill_count: 33
    .symbol:         _Z8mega_fwd6Params.kd
    .uniform_work_group_size: 1
    .uses_dynamic_stack: false
    .vgpr_count:     235
    .vgpr_spill_count: 0
    .wavefront_size: 64
